# adds P1 rope epilogue load-before-store reorder, P5 epilogue loads 6 steps ahead, K-loop LDS-DMA scalar-base addressing to the lean sweep / LN2 preload / P6 epilogue / attention wait version
# speedup vs baseline: 1.0072x; 1.0072x over previous
.LBB0_130:
	ds_read_b128 v[18:21], v201
	ds_read_b128 v[26:29], v201 offset:2048
	ds_read_b128 v[22:25], v202
	ds_read_b128 v[30:33], v202 offset:2048
	ds_read_b128 v[2:5], v203
	ds_read_b128 v[10:13], v203 offset:2048
	ds_read_b128 v[6:9], v204
	ds_read_b128 v[14:17], v204 offset:2048
	s_add_u32 s48, s46, 0xfffc0080
	s_addc_u32 s49, s47, -1
	s_cmp_eq_u32 s77, 12
	s_cselect_b32 s51, s37, s49
	s_cselect_b32 s50, s45, s48
	s_cselect_b32 s49, s35, s76
	s_cselect_b32 s48, s52, s53
	s_add_i32 m0, s33, 0xc000
	ds_read_b128 v[188:191], v205
	ds_read_b128 v[208:211], v205 offset:2048
	ds_read_b128 v[192:195], v206
	ds_read_b128 v[212:215], v206 offset:2048
	ds_read_b128 v[216:219], v205 offset:4096
	ds_read_b128 v[224:227], v205 offset:6144
	ds_read_b128 v[220:223], v206 offset:4096
	ds_read_b128 v[228:231], v206 offset:6144
	global_load_lds_dwordx4 v176, s[46:47]
	s_add_i32 m0, s33, 0xe000
	s_nop 0
	global_load_lds_dwordx4 v178, s[46:47]
	s_waitcnt vmcnt(8)
	s_waitcnt lgkmcnt(0)
	s_barrier
	s_setprio 1
	s_waitcnt lgkmcnt(0)
	v_mfma_scale_f32_16x16x128_f8f6f4 v[158:161], v[18:25], v[188:195], v[158:161], v1, v1 op_sel_hi:[0,0,0]
	v_mfma_scale_f32_16x16x128_f8f6f4 v[154:157], v[26:33], v[188:195], v[154:157], v1, v1 op_sel_hi:[0,0,0]
	v_mfma_scale_f32_16x16x128_f8f6f4 v[142:145], v[18:25], v[208:215], v[142:145], v1, v1 op_sel_hi:[0,0,0]
	v_mfma_scale_f32_16x16x128_f8f6f4 v[138:141], v[26:33], v[208:215], v[138:141], v1, v1 op_sel_hi:[0,0,0]
	v_mfma_scale_f32_16x16x128_f8f6f4 v[126:129], v[18:25], v[216:223], v[126:129], v1, v1 op_sel_hi:[0,0,0]
	v_mfma_scale_f32_16x16x128_f8f6f4 v[122:125], v[26:33], v[216:223], v[122:125], v1, v1 op_sel_hi:[0,0,0]
	v_mfma_scale_f32_16x16x128_f8f6f4 v[110:113], v[18:25], v[224:231], v[110:113], v1, v1 op_sel_hi:[0,0,0]
	v_mfma_scale_f32_16x16x128_f8f6f4 v[106:109], v[26:33], v[224:231], v[106:109], v1, v1 op_sel_hi:[0,0,0]
	s_setprio 0
	s_setprio 1
	v_mfma_scale_f32_16x16x128_f8f6f4 v[150:153], v[2:9], v[188:195], v[150:153], v1, v1 op_sel_hi:[0,0,0]
	v_mfma_scale_f32_16x16x128_f8f6f4 v[146:149], v[10:17], v[188:195], v[146:149], v1, v1 op_sel_hi:[0,0,0]
	v_mfma_scale_f32_16x16x128_f8f6f4 v[134:137], v[2:9], v[208:215], v[134:137], v1, v1 op_sel_hi:[0,0,0]
	v_mfma_scale_f32_16x16x128_f8f6f4 v[130:133], v[10:17], v[208:215], v[130:133], v1, v1 op_sel_hi:[0,0,0]
	v_mfma_scale_f32_16x16x128_f8f6f4 v[118:121], v[2:9], v[216:223], v[118:121], v1, v1 op_sel_hi:[0,0,0]
	v_mfma_scale_f32_16x16x128_f8f6f4 v[114:117], v[10:17], v[216:223], v[114:117], v1, v1 op_sel_hi:[0,0,0]
	v_mfma_scale_f32_16x16x128_f8f6f4 v[102:105], v[2:9], v[224:231], v[102:105], v1, v1 op_sel_hi:[0,0,0]
	v_mfma_scale_f32_16x16x128_f8f6f4 v[98:101], v[10:17], v[224:231], v[98:101], v1, v1 op_sel_hi:[0,0,0]
	s_setprio 0
	s_barrier
	s_add_i32 s78, s63, s3
	v_lshl_add_u64 v[188:189], s[48:49], 0, v[164:165]
	s_mov_b32 m0, s78
	ds_read_b128 v[208:211], v205 offset:16384
	ds_read_b128 v[216:219], v205 offset:18432
	ds_read_b128 v[212:215], v206 offset:16384
	ds_read_b128 v[220:223], v206 offset:18432
	ds_read_b128 v[224:227], v205 offset:20480
	ds_read_b128 v[232:235], v205 offset:22528
	ds_read_b128 v[228:231], v206 offset:20480
	ds_read_b128 v[236:239], v206 offset:22528
	global_load_lds_dwordx4 v[188:189], off
	s_add_i32 m0, s78, 0x2000
	s_add_u32 s78, s48, 0x40000
	v_lshl_add_u64 v[190:191], s[48:49], 0, v[168:169]
	s_addc_u32 s79, s49, 0
	s_add_i32 s80, s64, s3
	global_load_lds_dwordx4 v[190:191], off
	s_mov_b32 m0, s80
	v_lshl_add_u64 v[194:195], s[50:51], 0, v[166:167]
	global_load_lds_dwordx4 v164, s[78:79]
	s_add_i32 m0, s80, 0x2000
	s_nop 0
	global_load_lds_dwordx4 v168, s[78:79]
	v_lshl_add_u64 v[192:193], s[50:51], 0, v[162:163]
	s_mov_b32 m0, s33
	s_nop 0
	global_load_lds_dwordx4 v[192:193], off
	s_mov_b32 m0, s43
	s_nop 0
	global_load_lds_dwordx4 v[194:195], off
	s_waitcnt vmcnt(8)
	s_waitcnt lgkmcnt(0)
	s_barrier
	s_setprio 1
	s_waitcnt lgkmcnt(0)
	v_mfma_scale_f32_16x16x128_f8f6f4 v[94:97], v[18:25], v[208:215], v[94:97], v1, v1 op_sel_hi:[0,0,0]
	v_mfma_scale_f32_16x16x128_f8f6f4 v[90:93], v[26:33], v[208:215], v[90:93], v1, v1 op_sel_hi:[0,0,0]
	v_mfma_scale_f32_16x16x128_f8f6f4 v[78:81], v[18:25], v[216:223], v[78:81], v1, v1 op_sel_hi:[0,0,0]
	v_mfma_scale_f32_16x16x128_f8f6f4 v[74:77], v[26:33], v[216:223], v[74:77], v1, v1 op_sel_hi:[0,0,0]
	v_mfma_scale_f32_16x16x128_f8f6f4 v[62:65], v[18:25], v[224:231], v[62:65], v1, v1 op_sel_hi:[0,0,0]
	v_mfma_scale_f32_16x16x128_f8f6f4 v[58:61], v[26:33], v[224:231], v[58:61], v1, v1 op_sel_hi:[0,0,0]
	v_mfma_scale_f32_16x16x128_f8f6f4 v[46:49], v[18:25], v[232:239], v[46:49], v1, v1 op_sel_hi:[0,0,0]
	v_mfma_scale_f32_16x16x128_f8f6f4 v[42:45], v[26:33], v[232:239], v[42:45], v1, v1 op_sel_hi:[0,0,0]
	s_setprio 0
	s_setprio 1
	v_mfma_scale_f32_16x16x128_f8f6f4 v[86:89], v[2:9], v[208:215], v[86:89], v1, v1 op_sel_hi:[0,0,0]
	v_mfma_scale_f32_16x16x128_f8f6f4 v[82:85], v[10:17], v[208:215], v[82:85], v1, v1 op_sel_hi:[0,0,0]
	v_mfma_scale_f32_16x16x128_f8f6f4 v[70:73], v[2:9], v[216:223], v[70:73], v1, v1 op_sel_hi:[0,0,0]
	v_mfma_scale_f32_16x16x128_f8f6f4 v[66:69], v[10:17], v[216:223], v[66:69], v1, v1 op_sel_hi:[0,0,0]
	v_mfma_scale_f32_16x16x128_f8f6f4 v[54:57], v[2:9], v[224:231], v[54:57], v1, v1 op_sel_hi:[0,0,0]
	v_mfma_scale_f32_16x16x128_f8f6f4 v[50:53], v[10:17], v[224:231], v[50:53], v1, v1 op_sel_hi:[0,0,0]
	v_mfma_scale_f32_16x16x128_f8f6f4 v[38:41], v[2:9], v[232:239], v[38:41], v1, v1 op_sel_hi:[0,0,0]
	v_mfma_scale_f32_16x16x128_f8f6f4 v[34:37], v[10:17], v[232:239], v[34:37], v1, v1 op_sel_hi:[0,0,0]
	s_setprio 0
	s_barrier
	s_add_i32 s78, 0, 0x18000
	s_add_i32 s79, 0, 0x1c000
	v_add_u32_e32 v6, s78, v198
	v_add_u32_e32 v14, s78, v199
	v_add_u32_e32 v22, s79, v198
	v_add_u32_e32 v30, s79, v199
	ds_read_b128 v[2:5], v6
	ds_read_b128 v[10:13], v6 offset:2048
	ds_read_b128 v[6:9], v14
	ds_read_b128 v[14:17], v14 offset:2048
	ds_read_b128 v[18:21], v22
	ds_read_b128 v[26:29], v22 offset:2048
	ds_read_b128 v[22:25], v30
	ds_read_b128 v[30:33], v30 offset:2048
	s_add_u32 s50, s50, 0x40000
	s_addc_u32 s51, s51, 0
	s_mov_b32 m0, s54
	ds_read_b128 v[208:211], v205 offset:32768
	ds_read_b128 v[216:219], v205 offset:34816
	ds_read_b128 v[212:215], v206 offset:32768
	ds_read_b128 v[220:223], v206 offset:34816
	ds_read_b128 v[224:227], v205 offset:36864
	ds_read_b128 v[232:235], v205 offset:38912
	ds_read_b128 v[228:231], v206 offset:36864
	ds_read_b128 v[236:239], v206 offset:38912
	global_load_lds_dwordx4 v162, s[50:51]
	s_mov_b32 m0, s55
	s_nop 0
	global_load_lds_dwordx4 v166, s[50:51]
	s_waitcnt vmcnt(8)
	s_waitcnt lgkmcnt(0)
	s_barrier
	s_setprio 1
	s_waitcnt lgkmcnt(0)
	v_mfma_scale_f32_16x16x128_f8f6f4 v[158:161], v[2:9], v[208:215], v[158:161], v1, v1 op_sel_hi:[0,0,0]
	v_mfma_scale_f32_16x16x128_f8f6f4 v[154:157], v[10:17], v[208:215], v[154:157], v1, v1 op_sel_hi:[0,0,0]
	v_mfma_scale_f32_16x16x128_f8f6f4 v[142:145], v[2:9], v[216:223], v[142:145], v1, v1 op_sel_hi:[0,0,0]
	v_mfma_scale_f32_16x16x128_f8f6f4 v[138:141], v[10:17], v[216:223], v[138:141], v1, v1 op_sel_hi:[0,0,0]
	v_mfma_scale_f32_16x16x128_f8f6f4 v[126:129], v[2:9], v[224:231], v[126:129], v1, v1 op_sel_hi:[0,0,0]
	v_mfma_scale_f32_16x16x128_f8f6f4 v[122:125], v[10:17], v[224:231], v[122:125], v1, v1 op_sel_hi:[0,0,0]
	v_mfma_scale_f32_16x16x128_f8f6f4 v[110:113], v[2:9], v[232:239], v[110:113], v1, v1 op_sel_hi:[0,0,0]
	v_mfma_scale_f32_16x16x128_f8f6f4 v[106:109], v[10:17], v[232:239], v[106:109], v1, v1 op_sel_hi:[0,0,0]
	s_setprio 0
	s_setprio 1
	v_mfma_scale_f32_16x16x128_f8f6f4 v[150:153], v[18:25], v[208:215], v[150:153], v1, v1 op_sel_hi:[0,0,0]
	v_mfma_scale_f32_16x16x128_f8f6f4 v[146:149], v[26:33], v[208:215], v[146:149], v1, v1 op_sel_hi:[0,0,0]
	v_mfma_scale_f32_16x16x128_f8f6f4 v[134:137], v[18:25], v[216:223], v[134:137], v1, v1 op_sel_hi:[0,0,0]
	v_mfma_scale_f32_16x16x128_f8f6f4 v[130:133], v[26:33], v[216:223], v[130:133], v1, v1 op_sel_hi:[0,0,0]
	v_mfma_scale_f32_16x16x128_f8f6f4 v[118:121], v[18:25], v[224:231], v[118:121], v1, v1 op_sel_hi:[0,0,0]
	v_mfma_scale_f32_16x16x128_f8f6f4 v[114:117], v[26:33], v[224:231], v[114:117], v1, v1 op_sel_hi:[0,0,0]
	v_mfma_scale_f32_16x16x128_f8f6f4 v[102:105], v[18:25], v[232:239], v[102:105], v1, v1 op_sel_hi:[0,0,0]
	v_mfma_scale_f32_16x16x128_f8f6f4 v[98:101], v[26:33], v[232:239], v[98:101], v1, v1 op_sel_hi:[0,0,0]
	s_setprio 0
	s_barrier
	s_add_i32 s50, s78, s3
	v_lshl_add_u64 v[188:189], v[188:189], 0, s[14:15]
	s_mov_b32 m0, s50
	ds_read_b128 v[208:211], v205 offset:49152
	ds_read_b128 v[216:219], v205 offset:51200
	ds_read_b128 v[212:215], v206 offset:49152
	ds_read_b128 v[220:223], v206 offset:51200
	ds_read_b128 v[224:227], v205 offset:53248
	ds_read_b128 v[232:235], v205 offset:55296
	ds_read_b128 v[228:231], v206 offset:53248
	ds_read_b128 v[236:239], v206 offset:55296
	global_load_lds_dwordx4 v[188:189], off
	s_add_i32 m0, s50, 0x2000
	s_add_u32 s48, s48, 0x40080
	v_lshl_add_u64 v[188:189], v[190:191], 0, s[14:15]
	s_addc_u32 s49, s49, 0
	s_add_i32 s50, s79, s3
	global_load_lds_dwordx4 v[188:189], off
	s_mov_b32 m0, s50
	s_nop 0
	global_load_lds_dwordx4 v164, s[48:49]
	s_add_i32 m0, s50, 0x2000
	s_nop 0
	global_load_lds_dwordx4 v168, s[48:49]
	v_lshl_add_u64 v[188:189], v[192:193], 0, s[14:15]
	s_mov_b32 m0, s57
	s_nop 0
	global_load_lds_dwordx4 v[188:189], off
	v_lshl_add_u64 v[188:189], v[194:195], 0, s[14:15]
	s_mov_b32 m0, s58
	s_nop 0
	global_load_lds_dwordx4 v[188:189], off
	s_waitcnt vmcnt(8)
	s_waitcnt lgkmcnt(0)
	s_barrier
	s_setprio 1
	s_waitcnt lgkmcnt(0)
	v_mfma_scale_f32_16x16x128_f8f6f4 v[94:97], v[2:9], v[208:215], v[94:97], v1, v1 op_sel_hi:[0,0,0]
	v_mfma_scale_f32_16x16x128_f8f6f4 v[90:93], v[10:17], v[208:215], v[90:93], v1, v1 op_sel_hi:[0,0,0]
	v_mfma_scale_f32_16x16x128_f8f6f4 v[78:81], v[2:9], v[216:223], v[78:81], v1, v1 op_sel_hi:[0,0,0]
	v_mfma_scale_f32_16x16x128_f8f6f4 v[74:77], v[10:17], v[216:223], v[74:77], v1, v1 op_sel_hi:[0,0,0]
	v_mfma_scale_f32_16x16x128_f8f6f4 v[62:65], v[2:9], v[224:231], v[62:65], v1, v1 op_sel_hi:[0,0,0]
	v_mfma_scale_f32_16x16x128_f8f6f4 v[58:61], v[10:17], v[224:231], v[58:61], v1, v1 op_sel_hi:[0,0,0]
	v_mfma_scale_f32_16x16x128_f8f6f4 v[46:49], v[2:9], v[232:239], v[46:49], v1, v1 op_sel_hi:[0,0,0]
	v_mfma_scale_f32_16x16x128_f8f6f4 v[42:45], v[10:17], v[232:239], v[42:45], v1, v1 op_sel_hi:[0,0,0]
	s_setprio 0
	s_setprio 1
	v_mfma_scale_f32_16x16x128_f8f6f4 v[86:89], v[18:25], v[208:215], v[86:89], v1, v1 op_sel_hi:[0,0,0]
	v_mfma_scale_f32_16x16x128_f8f6f4 v[82:85], v[26:33], v[208:215], v[82:85], v1, v1 op_sel_hi:[0,0,0]
	v_mfma_scale_f32_16x16x128_f8f6f4 v[70:73], v[18:25], v[216:223], v[70:73], v1, v1 op_sel_hi:[0,0,0]
	v_mfma_scale_f32_16x16x128_f8f6f4 v[66:69], v[26:33], v[216:223], v[66:69], v1, v1 op_sel_hi:[0,0,0]
	v_mfma_scale_f32_16x16x128_f8f6f4 v[54:57], v[18:25], v[224:231], v[54:57], v1, v1 op_sel_hi:[0,0,0]
	v_mfma_scale_f32_16x16x128_f8f6f4 v[50:53], v[26:33], v[224:231], v[50:53], v1, v1 op_sel_hi:[0,0,0]
	v_mfma_scale_f32_16x16x128_f8f6f4 v[38:41], v[18:25], v[232:239], v[38:41], v1, v1 op_sel_hi:[0,0,0]
	v_mfma_scale_f32_16x16x128_f8f6f4 v[34:37], v[26:33], v[232:239], v[34:37], v1, v1 op_sel_hi:[0,0,0]
	s_setprio 0
	s_barrier
	s_add_i32 s77, s77, 2
	s_add_u32 s46, s46, 0x100
	s_addc_u32 s47, s47, 0
	s_add_u32 s53, s53, 0x100
	s_addc_u32 s76, s76, 0
	s_cmp_gt_u32 s77, 13
	s_cbranch_scc0 .LBB0_130
	s_nop 15
	s_nop 15
	s_and_b64 vcc, exec, s[16:17]
	s_cbranch_vccz .LBB0_133
	s_barrier

.LBB0_152:
	s_andn2_b64 vcc, exec, s[52:53]
	s_cbranch_vccnz .LBB0_154
	v_lshlrev_b32_e32 v170, 8, v18
	v_lshl_add_u64 v[4:5], v[174:175], 0, v[170:171]
	global_load_dwordx4 v[18:21], v[4:5], off
	v_lshl_add_u64 v[4:5], v[172:173], 0, v[170:171]
	global_load_dwordx4 v[22:25], v[4:5], off
	v_mov_b32_e32 v187, v171
	v_pk_mul_f32 v[30:31], v[156:157], s[24:25] op_sel_hi:[1,0]
	v_pk_mul_f32 v[32:33], v[154:155], s[24:25] op_sel_hi:[1,0]
	v_mov_b32_e32 v7, v171
	v_pk_mul_f32 v[26:27], v[160:161], s[24:25] op_sel_hi:[1,0]
	v_pk_mul_f32 v[28:29], v[158:159], s[24:25] op_sel_hi:[1,0]
	s_lshl_b64 s[48:49], s[48:49], 20
	v_pk_mul_f32 v[188:189], v[152:153], s[24:25] op_sel_hi:[1,0]
	v_pk_mul_f32 v[190:191], v[150:151], s[24:25] op_sel_hi:[1,0]
	v_pk_mul_f32 v[192:193], v[148:149], s[24:25] op_sel_hi:[1,0]
	v_pk_mul_f32 v[194:195], v[146:147], s[24:25] op_sel_hi:[1,0]
	v_lshl_add_u64 v[4:5], s[46:47], 0, v[186:187]
	s_add_u32 s46, s48, 0x100000
	v_lshl_add_u64 v[6:7], v[4:5], 0, v[6:7]
	v_lshlrev_b32_e32 v170, 8, v17
	s_addc_u32 s47, s49, 0
	v_lshl_add_u64 v[210:211], v[6:7], 0, s[44:45]
	v_lshl_add_u64 v[208:209], v[174:175], 0, v[170:171]
	v_lshl_add_u64 v[6:7], v[6:7], 0, s[46:47]
	v_and_b32_e32 v13, 0xfff, v13
	v_or_b32_e32 v185, 16, v3
	s_waitcnt vmcnt(0)
	v_pk_mul_f32 v[212:213], v[30:31], v[20:21]
	v_pk_mul_f32 v[214:215], v[32:33], v[18:19]
	v_pk_mul_f32 v[216:217], v[26:27], v[20:21]
	v_pk_mul_f32 v[218:219], v[28:29], v[18:19]
	v_pk_mul_f32 v[220:221], v[192:193], v[20:21]
	v_pk_mul_f32 v[222:223], v[194:195], v[18:19]
	v_pk_mul_f32 v[20:21], v[188:189], v[20:21]
	v_pk_mul_f32 v[18:19], v[190:191], v[18:19]
	v_pk_fma_f32 v[26:27], v[26:27], v[24:25], v[212:213] neg_lo:[0,0,1] neg_hi:[0,0,1]
	v_pk_fma_f32 v[28:29], v[28:29], v[22:23], v[214:215] neg_lo:[0,0,1] neg_hi:[0,0,1]
	v_pk_fma_f32 v[30:31], v[30:31], v[24:25], v[216:217]
	v_pk_fma_f32 v[32:33], v[32:33], v[22:23], v[218:219]
	v_pk_fma_f32 v[188:189], v[188:189], v[24:25], v[220:221] neg_lo:[0,0,1] neg_hi:[0,0,1]
	v_pk_fma_f32 v[190:191], v[190:191], v[22:23], v[222:223] neg_lo:[0,0,1] neg_hi:[0,0,1]
	v_pk_fma_f32 v[20:21], v[192:193], v[24:25], v[20:21]
	v_pk_fma_f32 v[18:19], v[194:195], v[22:23], v[18:19]
	v_cvt_pk_bf16_f32 v224, v28, v29
	v_cvt_pk_bf16_f32 v225, v26, v27
	v_cvt_pk_bf16_f32 v226, v32, v33
	v_cvt_pk_bf16_f32 v227, v30, v31
	v_cvt_pk_bf16_f32 v228, v190, v191
	v_cvt_pk_bf16_f32 v229, v188, v189
	v_cvt_pk_bf16_f32 v230, v18, v19
	v_cvt_pk_bf16_f32 v231, v20, v21
	v_mov_b32_e32 v234, v210
	v_mov_b32_e32 v235, v211
	v_mov_b32_e32 v236, v6
	v_mov_b32_e32 v237, v7
	v_lshl_add_u64 v[232:233], v[172:173], 0, v[170:171]
	global_load_dwordx4 v[18:21], v[208:209], off
	global_load_dwordx4 v[22:25], v[232:233], off
	global_store_dwordx2 v[234:235], v[224:225], off
	global_store_dwordx2 v[234:235], v[226:227], off offset:128
	global_store_dwordx2 v[236:237], v[228:229], off
	global_store_dwordx2 v[236:237], v[230:231], off offset:128
	v_and_b32_e32 v170, 0xfff, v16
	v_pk_mul_f32 v[26:27], v[140:141], s[24:25] op_sel_hi:[1,0]
	v_pk_mul_f32 v[28:29], v[138:139], s[24:25] op_sel_hi:[1,0]
	v_pk_mul_f32 v[6:7], v[144:145], s[24:25] op_sel_hi:[1,0]
	v_pk_mul_f32 v[16:17], v[142:143], s[24:25] op_sel_hi:[1,0]
	v_pk_mul_f32 v[30:31], v[136:137], s[24:25] op_sel_hi:[1,0]
	v_pk_mul_f32 v[32:33], v[134:135], s[24:25] op_sel_hi:[1,0]
	v_pk_mul_f32 v[188:189], v[132:133], s[24:25] op_sel_hi:[1,0]
	v_pk_mul_f32 v[190:191], v[130:131], s[24:25] op_sel_hi:[1,0]
	v_add_lshl_u32 v170, v170, v15, 8
	v_lshl_add_u64 v[192:193], v[4:5], 0, v[170:171]
	v_lshlrev_b32_e32 v170, 8, v14
	v_lshl_add_u64 v[14:15], v[192:193], 0, s[44:45]
	v_lshl_add_u64 v[192:193], v[192:193], 0, s[46:47]
	v_lshl_add_u64 v[194:195], v[174:175], 0, v[170:171]
	s_waitcnt vmcnt(5)
	v_pk_mul_f32 v[208:209], v[26:27], v[20:21]
	v_pk_mul_f32 v[210:211], v[28:29], v[18:19]
	v_pk_mul_f32 v[212:213], v[6:7], v[20:21]
	v_pk_mul_f32 v[214:215], v[16:17], v[18:19]
	v_pk_mul_f32 v[216:217], v[188:189], v[20:21]
	v_pk_mul_f32 v[218:219], v[190:191], v[18:19]
	v_pk_mul_f32 v[20:21], v[30:31], v[20:21]
	v_pk_mul_f32 v[18:19], v[32:33], v[18:19]
	s_waitcnt vmcnt(4)
	v_pk_fma_f32 v[6:7], v[6:7], v[24:25], v[208:209] neg_lo:[0,0,1] neg_hi:[0,0,1]
	v_pk_fma_f32 v[16:17], v[16:17], v[22:23], v[210:211] neg_lo:[0,0,1] neg_hi:[0,0,1]
	v_pk_fma_f32 v[26:27], v[26:27], v[24:25], v[212:213]
	v_pk_fma_f32 v[28:29], v[28:29], v[22:23], v[214:215]
	v_pk_fma_f32 v[30:31], v[30:31], v[24:25], v[216:217] neg_lo:[0,0,1] neg_hi:[0,0,1]
	v_pk_fma_f32 v[32:33], v[32:33], v[22:23], v[218:219] neg_lo:[0,0,1] neg_hi:[0,0,1]
	v_pk_fma_f32 v[20:21], v[188:189], v[24:25], v[20:21]
	v_pk_fma_f32 v[18:19], v[190:191], v[22:23], v[18:19]
	v_cvt_pk_bf16_f32 v224, v16, v17
	v_cvt_pk_bf16_f32 v225, v6, v7
	v_cvt_pk_bf16_f32 v226, v28, v29
	v_cvt_pk_bf16_f32 v227, v26, v27
	v_cvt_pk_bf16_f32 v228, v32, v33
	v_cvt_pk_bf16_f32 v229, v30, v31
	v_cvt_pk_bf16_f32 v230, v18, v19
	v_cvt_pk_bf16_f32 v231, v20, v21
	v_mov_b32_e32 v234, v14
	v_mov_b32_e32 v235, v15
	v_mov_b32_e32 v236, v192
	v_mov_b32_e32 v237, v193
	v_lshl_add_u64 v[232:233], v[172:173], 0, v[170:171]
	global_load_dwordx4 v[14:17], v[194:195], off
	global_load_dwordx4 v[18:21], v[232:233], off
	global_store_dwordx2 v[234:235], v[224:225], off
	global_store_dwordx2 v[234:235], v[226:227], off offset:128
	global_store_dwordx2 v[236:237], v[228:229], off
	global_store_dwordx2 v[236:237], v[230:231], off offset:128
	v_pk_mul_f32 v[24:25], v[124:125], s[24:25] op_sel_hi:[1,0]
	v_pk_mul_f32 v[26:27], v[122:123], s[24:25] op_sel_hi:[1,0]
	v_pk_mul_f32 v[6:7], v[128:129], s[24:25] op_sel_hi:[1,0]
	v_pk_mul_f32 v[22:23], v[126:127], s[24:25] op_sel_hi:[1,0]
	v_pk_mul_f32 v[28:29], v[120:121], s[24:25] op_sel_hi:[1,0]
	v_pk_mul_f32 v[30:31], v[118:119], s[24:25] op_sel_hi:[1,0]
	v_pk_mul_f32 v[32:33], v[116:117], s[24:25] op_sel_hi:[1,0]
	v_pk_mul_f32 v[188:189], v[114:115], s[24:25] op_sel_hi:[1,0]
	v_add_lshl_u32 v170, v13, v12, 8
	v_lshl_add_u64 v[12:13], v[4:5], 0, v[170:171]
	v_lshlrev_b32_e32 v170, 8, v11
	v_lshl_add_u64 v[190:191], v[12:13], 0, s[44:45]
	v_lshl_add_u64 v[12:13], v[12:13], 0, s[46:47]
	v_lshl_add_u64 v[192:193], v[174:175], 0, v[170:171]
	s_waitcnt vmcnt(5)
	v_pk_mul_f32 v[194:195], v[24:25], v[16:17]
	v_pk_mul_f32 v[208:209], v[26:27], v[14:15]
	v_pk_mul_f32 v[210:211], v[6:7], v[16:17]
	v_pk_mul_f32 v[212:213], v[22:23], v[14:15]
	v_pk_mul_f32 v[214:215], v[32:33], v[16:17]
	v_pk_mul_f32 v[216:217], v[188:189], v[14:15]
	v_pk_mul_f32 v[16:17], v[28:29], v[16:17]
	v_pk_mul_f32 v[14:15], v[30:31], v[14:15]
	s_waitcnt vmcnt(4)
	v_pk_fma_f32 v[6:7], v[6:7], v[20:21], v[194:195] neg_lo:[0,0,1] neg_hi:[0,0,1]
	v_pk_fma_f32 v[22:23], v[22:23], v[18:19], v[208:209] neg_lo:[0,0,1] neg_hi:[0,0,1]
	v_pk_fma_f32 v[24:25], v[24:25], v[20:21], v[210:211]
	v_pk_fma_f32 v[26:27], v[26:27], v[18:19], v[212:213]
	v_pk_fma_f32 v[28:29], v[28:29], v[20:21], v[214:215] neg_lo:[0,0,1] neg_hi:[0,0,1]
	v_pk_fma_f32 v[30:31], v[30:31], v[18:19], v[216:217] neg_lo:[0,0,1] neg_hi:[0,0,1]
	v_pk_fma_f32 v[16:17], v[32:33], v[20:21], v[16:17]
	v_pk_fma_f32 v[14:15], v[188:189], v[18:19], v[14:15]
	v_cvt_pk_bf16_f32 v224, v22, v23
	v_cvt_pk_bf16_f32 v225, v6, v7
	v_cvt_pk_bf16_f32 v226, v26, v27
	v_cvt_pk_bf16_f32 v227, v24, v25
	v_cvt_pk_bf16_f32 v228, v30, v31
	v_cvt_pk_bf16_f32 v229, v28, v29
	v_cvt_pk_bf16_f32 v230, v14, v15
	v_cvt_pk_bf16_f32 v231, v16, v17
	v_mov_b32_e32 v234, v190
	v_mov_b32_e32 v235, v191
	v_mov_b32_e32 v236, v12
	v_mov_b32_e32 v237, v13
	v_lshl_add_u64 v[232:233], v[172:173], 0, v[170:171]
	global_load_dwordx4 v[12:15], v[192:193], off
	global_load_dwordx4 v[16:19], v[232:233], off
	global_store_dwordx2 v[234:235], v[224:225], off
	global_store_dwordx2 v[234:235], v[226:227], off offset:128
	global_store_dwordx2 v[236:237], v[228:229], off
	global_store_dwordx2 v[236:237], v[230:231], off offset:128
	v_and_b32_e32 v32, 0xfff, v10
	v_pk_mul_f32 v[20:21], v[108:109], s[24:25] op_sel_hi:[1,0]
	v_pk_mul_f32 v[22:23], v[106:107], s[24:25] op_sel_hi:[1,0]
	v_pk_mul_f32 v[6:7], v[112:113], s[24:25] op_sel_hi:[1,0]
	v_pk_mul_f32 v[10:11], v[110:111], s[24:25] op_sel_hi:[1,0]
	v_pk_mul_f32 v[24:25], v[104:105], s[24:25] op_sel_hi:[1,0]
	v_pk_mul_f32 v[26:27], v[102:103], s[24:25] op_sel_hi:[1,0]
	v_pk_mul_f32 v[28:29], v[100:101], s[24:25] op_sel_hi:[1,0]
	v_pk_mul_f32 v[30:31], v[98:99], s[24:25] op_sel_hi:[1,0]
	v_add_lshl_u32 v170, v32, v9, 8
	v_lshl_add_u64 v[32:33], v[4:5], 0, v[170:171]
	v_lshlrev_b32_e32 v170, 8, v3
	v_lshl_add_u64 v[188:189], v[32:33], 0, s[44:45]
	v_lshl_add_u64 v[32:33], v[32:33], 0, s[46:47]
	v_lshl_add_u64 v[190:191], v[174:175], 0, v[170:171]
	s_waitcnt vmcnt(5)
	v_pk_mul_f32 v[192:193], v[20:21], v[14:15]
	v_pk_mul_f32 v[194:195], v[22:23], v[12:13]
	v_pk_mul_f32 v[208:209], v[6:7], v[14:15]
	v_pk_mul_f32 v[210:211], v[10:11], v[12:13]
	v_pk_mul_f32 v[212:213], v[28:29], v[14:15]
	v_pk_mul_f32 v[214:215], v[30:31], v[12:13]
	v_pk_mul_f32 v[14:15], v[24:25], v[14:15]
	v_pk_mul_f32 v[12:13], v[26:27], v[12:13]
	s_waitcnt vmcnt(4)
	v_pk_fma_f32 v[6:7], v[6:7], v[18:19], v[192:193] neg_lo:[0,0,1] neg_hi:[0,0,1]
	v_pk_fma_f32 v[10:11], v[10:11], v[16:17], v[194:195] neg_lo:[0,0,1] neg_hi:[0,0,1]
	v_pk_fma_f32 v[20:21], v[20:21], v[18:19], v[208:209]
	v_pk_fma_f32 v[22:23], v[22:23], v[16:17], v[210:211]
	v_pk_fma_f32 v[24:25], v[24:25], v[18:19], v[212:213] neg_lo:[0,0,1] neg_hi:[0,0,1]
	v_pk_fma_f32 v[26:27], v[26:27], v[16:17], v[214:215] neg_lo:[0,0,1] neg_hi:[0,0,1]
	v_pk_fma_f32 v[14:15], v[28:29], v[18:19], v[14:15]
	v_pk_fma_f32 v[12:13], v[30:31], v[16:17], v[12:13]
	v_cvt_pk_bf16_f32 v224, v10, v11
	v_cvt_pk_bf16_f32 v225, v6, v7
	v_cvt_pk_bf16_f32 v226, v22, v23
	v_cvt_pk_bf16_f32 v227, v20, v21
	v_cvt_pk_bf16_f32 v228, v26, v27
	v_cvt_pk_bf16_f32 v229, v24, v25
	v_cvt_pk_bf16_f32 v230, v12, v13
	v_cvt_pk_bf16_f32 v231, v14, v15
	v_mov_b32_e32 v234, v188
	v_mov_b32_e32 v235, v189
	v_mov_b32_e32 v236, v32
	v_mov_b32_e32 v237, v33
	v_lshl_add_u64 v[232:233], v[172:173], 0, v[170:171]
	global_load_dwordx4 v[10:13], v[190:191], off
	global_load_dwordx4 v[14:17], v[232:233], off
	global_store_dwordx2 v[234:235], v[224:225], off
	global_store_dwordx2 v[234:235], v[226:227], off offset:128
	global_store_dwordx2 v[236:237], v[228:229], off
	global_store_dwordx2 v[236:237], v[230:231], off offset:128
	v_mov_b32_e32 v6, s77
	v_lshlrev_b32_e32 v7, s37, v3
	v_lshrrev_b32_e32 v170, s35, v3
	v_pk_mul_f32 v[22:23], v[92:93], s[24:25] op_sel_hi:[1,0]
	v_pk_mul_f32 v[24:25], v[90:91], s[24:25] op_sel_hi:[1,0]
	v_mad_i32_i24 v6, s76, v8, v6
	v_and_b32_e32 v187, 0xfff, v7
	v_pk_mul_f32 v[18:19], v[96:97], s[24:25] op_sel_hi:[1,0]
	v_pk_mul_f32 v[20:21], v[94:95], s[24:25] op_sel_hi:[1,0]
	v_pk_mul_f32 v[26:27], v[88:89], s[24:25] op_sel_hi:[1,0]
	v_pk_mul_f32 v[28:29], v[86:87], s[24:25] op_sel_hi:[1,0]
	v_pk_mul_f32 v[30:31], v[84:85], s[24:25] op_sel_hi:[1,0]
	v_pk_mul_f32 v[32:33], v[82:83], s[24:25] op_sel_hi:[1,0]
	v_ashrrev_i32_e32 v7, 31, v6
	v_add_lshl_u32 v170, v187, v170, 8
	v_lshlrev_b64 v[6:7], 20, v[6:7]
	v_lshl_add_u64 v[188:189], v[4:5], 0, v[170:171]
	v_lshl_add_u64 v[8:9], v[6:7], 0, s[22:23]
	v_lshlrev_b32_e32 v170, 8, v185
	v_lshl_add_u64 v[190:191], v[188:189], 0, v[6:7]
	v_lshl_add_u64 v[188:189], v[188:189], 0, v[8:9]
	v_lshl_add_u64 v[192:193], v[174:175], 0, v[170:171]
	v_or_b32_e32 v187, 32, v3
	v_or_b32_e32 v3, 48, v3
	s_waitcnt vmcnt(5)
	v_pk_mul_f32 v[194:195], v[22:23], v[12:13]
	v_pk_mul_f32 v[208:209], v[24:25], v[10:11]
	v_pk_mul_f32 v[210:211], v[18:19], v[12:13]
	v_pk_mul_f32 v[212:213], v[20:21], v[10:11]
	v_pk_mul_f32 v[214:215], v[30:31], v[12:13]
	v_pk_mul_f32 v[216:217], v[32:33], v[10:11]
	v_pk_mul_f32 v[12:13], v[26:27], v[12:13]
	v_pk_mul_f32 v[10:11], v[28:29], v[10:11]
	s_waitcnt vmcnt(4)
	v_pk_fma_f32 v[18:19], v[18:19], v[16:17], v[194:195] neg_lo:[0,0,1] neg_hi:[0,0,1]
	v_pk_fma_f32 v[20:21], v[20:21], v[14:15], v[208:209] neg_lo:[0,0,1] neg_hi:[0,0,1]
	v_pk_fma_f32 v[22:23], v[22:23], v[16:17], v[210:211]
	v_pk_fma_f32 v[24:25], v[24:25], v[14:15], v[212:213]
	v_pk_fma_f32 v[26:27], v[26:27], v[16:17], v[214:215] neg_lo:[0,0,1] neg_hi:[0,0,1]
	v_pk_fma_f32 v[28:29], v[28:29], v[14:15], v[216:217] neg_lo:[0,0,1] neg_hi:[0,0,1]
	v_pk_fma_f32 v[12:13], v[30:31], v[16:17], v[12:13]
	v_pk_fma_f32 v[10:11], v[32:33], v[14:15], v[10:11]
	v_cvt_pk_bf16_f32 v224, v20, v21
	v_cvt_pk_bf16_f32 v225, v18, v19
	v_cvt_pk_bf16_f32 v226, v24, v25
	v_cvt_pk_bf16_f32 v227, v22, v23
	v_cvt_pk_bf16_f32 v228, v28, v29
	v_cvt_pk_bf16_f32 v229, v26, v27
	v_cvt_pk_bf16_f32 v230, v10, v11
	v_cvt_pk_bf16_f32 v231, v12, v13
	v_mov_b32_e32 v234, v190
	v_mov_b32_e32 v235, v191
	v_mov_b32_e32 v236, v188
	v_mov_b32_e32 v237, v189
	v_lshl_add_u64 v[232:233], v[172:173], 0, v[170:171]
	global_load_dwordx4 v[10:13], v[192:193], off
	global_load_dwordx4 v[14:17], v[232:233], off
	global_store_dwordx2 v[234:235], v[224:225], off
	global_store_dwordx2 v[234:235], v[226:227], off offset:128
	global_store_dwordx2 v[236:237], v[228:229], off
	global_store_dwordx2 v[236:237], v[230:231], off offset:128
	v_lshlrev_b32_e32 v170, s37, v185
	v_pk_mul_f32 v[22:23], v[76:77], s[24:25] op_sel_hi:[1,0]
	v_pk_mul_f32 v[24:25], v[74:75], s[24:25] op_sel_hi:[1,0]
	v_lshrrev_b32_e32 v185, s35, v185
	v_and_b32_e32 v170, 0xfff, v170
	v_pk_mul_f32 v[18:19], v[80:81], s[24:25] op_sel_hi:[1,0]
	v_pk_mul_f32 v[20:21], v[78:79], s[24:25] op_sel_hi:[1,0]
	v_pk_mul_f32 v[26:27], v[72:73], s[24:25] op_sel_hi:[1,0]
	v_pk_mul_f32 v[28:29], v[70:71], s[24:25] op_sel_hi:[1,0]
	v_pk_mul_f32 v[30:31], v[68:69], s[24:25] op_sel_hi:[1,0]
	v_pk_mul_f32 v[32:33], v[66:67], s[24:25] op_sel_hi:[1,0]
	v_add_lshl_u32 v170, v170, v185, 8
	v_lshl_add_u64 v[188:189], v[4:5], 0, v[170:171]
	v_lshlrev_b32_e32 v170, 8, v187
	v_lshl_add_u64 v[190:191], v[188:189], 0, v[6:7]
	v_lshl_add_u64 v[188:189], v[188:189], 0, v[8:9]
	v_lshl_add_u64 v[192:193], v[174:175], 0, v[170:171]
	v_lshrrev_b32_e32 v185, s35, v187
	s_waitcnt vmcnt(5)
	v_pk_mul_f32 v[194:195], v[22:23], v[12:13]
	v_pk_mul_f32 v[208:209], v[24:25], v[10:11]
	v_pk_mul_f32 v[210:211], v[18:19], v[12:13]
	v_pk_mul_f32 v[212:213], v[20:21], v[10:11]
	v_pk_mul_f32 v[214:215], v[30:31], v[12:13]
	v_pk_mul_f32 v[216:217], v[32:33], v[10:11]
	v_pk_mul_f32 v[12:13], v[26:27], v[12:13]
	v_pk_mul_f32 v[10:11], v[28:29], v[10:11]
	s_waitcnt vmcnt(4)
	v_pk_fma_f32 v[18:19], v[18:19], v[16:17], v[194:195] neg_lo:[0,0,1] neg_hi:[0,0,1]
	v_pk_fma_f32 v[20:21], v[20:21], v[14:15], v[208:209] neg_lo:[0,0,1] neg_hi:[0,0,1]
	v_pk_fma_f32 v[22:23], v[22:23], v[16:17], v[210:211]
	v_pk_fma_f32 v[24:25], v[24:25], v[14:15], v[212:213]
	v_pk_fma_f32 v[26:27], v[26:27], v[16:17], v[214:215] neg_lo:[0,0,1] neg_hi:[0,0,1]
	v_pk_fma_f32 v[28:29], v[28:29], v[14:15], v[216:217] neg_lo:[0,0,1] neg_hi:[0,0,1]
	v_pk_fma_f32 v[12:13], v[30:31], v[16:17], v[12:13]
	v_pk_fma_f32 v[10:11], v[32:33], v[14:15], v[10:11]
	v_cvt_pk_bf16_f32 v224, v20, v21
	v_cvt_pk_bf16_f32 v225, v18, v19
	v_cvt_pk_bf16_f32 v226, v24, v25
	v_cvt_pk_bf16_f32 v227, v22, v23
	v_cvt_pk_bf16_f32 v228, v28, v29
	v_cvt_pk_bf16_f32 v229, v26, v27
	v_cvt_pk_bf16_f32 v230, v10, v11
	v_cvt_pk_bf16_f32 v231, v12, v13
	v_mov_b32_e32 v234, v190
	v_mov_b32_e32 v235, v191
	v_mov_b32_e32 v236, v188
	v_mov_b32_e32 v237, v189
	v_lshl_add_u64 v[232:233], v[172:173], 0, v[170:171]
	global_load_dwordx4 v[10:13], v[192:193], off
	global_load_dwordx4 v[14:17], v[232:233], off
	global_store_dwordx2 v[234:235], v[224:225], off
	global_store_dwordx2 v[234:235], v[226:227], off offset:128
	global_store_dwordx2 v[236:237], v[228:229], off
	global_store_dwordx2 v[236:237], v[230:231], off offset:128
	v_lshlrev_b32_e32 v170, s37, v187
	v_pk_mul_f32 v[22:23], v[60:61], s[24:25] op_sel_hi:[1,0]
	v_pk_mul_f32 v[24:25], v[58:59], s[24:25] op_sel_hi:[1,0]
	v_and_b32_e32 v170, 0xfff, v170
	v_pk_mul_f32 v[18:19], v[64:65], s[24:25] op_sel_hi:[1,0]
	v_pk_mul_f32 v[20:21], v[62:63], s[24:25] op_sel_hi:[1,0]
	v_pk_mul_f32 v[26:27], v[56:57], s[24:25] op_sel_hi:[1,0]
	v_pk_mul_f32 v[28:29], v[54:55], s[24:25] op_sel_hi:[1,0]
	v_pk_mul_f32 v[30:31], v[52:53], s[24:25] op_sel_hi:[1,0]
	v_pk_mul_f32 v[32:33], v[50:51], s[24:25] op_sel_hi:[1,0]
	v_add_lshl_u32 v170, v170, v185, 8
	v_lshl_add_u64 v[188:189], v[4:5], 0, v[170:171]
	v_lshlrev_b32_e32 v170, 8, v3
	v_lshl_add_u64 v[190:191], v[188:189], 0, v[6:7]
	v_lshl_add_u64 v[188:189], v[188:189], 0, v[8:9]
	v_lshl_add_u64 v[192:193], v[174:175], 0, v[170:171]
	s_waitcnt vmcnt(5)
	v_pk_mul_f32 v[194:195], v[22:23], v[12:13]
	v_pk_mul_f32 v[208:209], v[24:25], v[10:11]
	v_pk_mul_f32 v[210:211], v[18:19], v[12:13]
	v_pk_mul_f32 v[212:213], v[20:21], v[10:11]
	v_pk_mul_f32 v[214:215], v[30:31], v[12:13]
	v_pk_mul_f32 v[216:217], v[32:33], v[10:11]
	v_pk_mul_f32 v[12:13], v[26:27], v[12:13]
	v_pk_mul_f32 v[10:11], v[28:29], v[10:11]
	s_waitcnt vmcnt(4)
	v_pk_fma_f32 v[18:19], v[18:19], v[16:17], v[194:195] neg_lo:[0,0,1] neg_hi:[0,0,1]
	v_pk_fma_f32 v[20:21], v[20:21], v[14:15], v[208:209] neg_lo:[0,0,1] neg_hi:[0,0,1]
	v_pk_fma_f32 v[22:23], v[22:23], v[16:17], v[210:211]
	v_pk_fma_f32 v[24:25], v[24:25], v[14:15], v[212:213]
	v_pk_fma_f32 v[26:27], v[26:27], v[16:17], v[214:215] neg_lo:[0,0,1] neg_hi:[0,0,1]
	v_pk_fma_f32 v[28:29], v[28:29], v[14:15], v[216:217] neg_lo:[0,0,1] neg_hi:[0,0,1]
	v_pk_fma_f32 v[12:13], v[30:31], v[16:17], v[12:13]
	v_pk_fma_f32 v[10:11], v[32:33], v[14:15], v[10:11]
	v_cvt_pk_bf16_f32 v224, v20, v21
	v_cvt_pk_bf16_f32 v225, v18, v19
	v_cvt_pk_bf16_f32 v226, v24, v25
	v_cvt_pk_bf16_f32 v227, v22, v23
	v_cvt_pk_bf16_f32 v228, v28, v29
	v_cvt_pk_bf16_f32 v229, v26, v27
	v_cvt_pk_bf16_f32 v230, v10, v11
	v_cvt_pk_bf16_f32 v231, v12, v13
	v_mov_b32_e32 v234, v190
	v_mov_b32_e32 v235, v191
	v_mov_b32_e32 v236, v188
	v_mov_b32_e32 v237, v189
	v_lshl_add_u64 v[232:233], v[172:173], 0, v[170:171]
	global_load_dwordx4 v[10:13], v[192:193], off
	global_load_dwordx4 v[14:17], v[232:233], off
	global_store_dwordx2 v[234:235], v[224:225], off
	global_store_dwordx2 v[234:235], v[226:227], off offset:128
	global_store_dwordx2 v[236:237], v[228:229], off
	global_store_dwordx2 v[236:237], v[230:231], off offset:128
	v_lshlrev_b32_e32 v170, s37, v3
	v_lshrrev_b32_e32 v3, s35, v3
	v_and_b32_e32 v170, 0xfff, v170
	v_add_lshl_u32 v170, v170, v3, 8
	v_pk_mul_f32 v[22:23], v[44:45], s[24:25] op_sel_hi:[1,0]
	v_pk_mul_f32 v[24:25], v[42:43], s[24:25] op_sel_hi:[1,0]
	v_lshl_add_u64 v[4:5], v[4:5], 0, v[170:171]
	v_pk_mul_f32 v[18:19], v[48:49], s[24:25] op_sel_hi:[1,0]
	v_pk_mul_f32 v[20:21], v[46:47], s[24:25] op_sel_hi:[1,0]
	v_pk_mul_f32 v[26:27], v[40:41], s[24:25] op_sel_hi:[1,0]
	v_pk_mul_f32 v[28:29], v[38:39], s[24:25] op_sel_hi:[1,0]
	v_pk_mul_f32 v[30:31], v[36:37], s[24:25] op_sel_hi:[1,0]
	v_pk_mul_f32 v[32:33], v[34:35], s[24:25] op_sel_hi:[1,0]
	v_lshl_add_u64 v[6:7], v[4:5], 0, v[6:7]
	v_lshl_add_u64 v[4:5], v[4:5], 0, v[8:9]
	s_waitcnt vmcnt(5)
	v_pk_mul_f32 v[8:9], v[22:23], v[12:13]
	v_pk_mul_f32 v[188:189], v[24:25], v[10:11]
	v_pk_mul_f32 v[190:191], v[18:19], v[12:13]
	v_pk_mul_f32 v[192:193], v[20:21], v[10:11]
	v_pk_mul_f32 v[194:195], v[30:31], v[12:13]
	v_pk_mul_f32 v[208:209], v[32:33], v[10:11]
	v_pk_mul_f32 v[12:13], v[26:27], v[12:13]
	v_pk_mul_f32 v[10:11], v[28:29], v[10:11]
	s_waitcnt vmcnt(4)
	v_pk_fma_f32 v[8:9], v[18:19], v[16:17], v[8:9] neg_lo:[0,0,1] neg_hi:[0,0,1]
	v_pk_fma_f32 v[18:19], v[20:21], v[14:15], v[188:189] neg_lo:[0,0,1] neg_hi:[0,0,1]
	v_pk_fma_f32 v[20:21], v[22:23], v[16:17], v[190:191]
	v_pk_fma_f32 v[22:23], v[24:25], v[14:15], v[192:193]
	v_pk_fma_f32 v[24:25], v[26:27], v[16:17], v[194:195] neg_lo:[0,0,1] neg_hi:[0,0,1]
	v_pk_fma_f32 v[26:27], v[28:29], v[14:15], v[208:209] neg_lo:[0,0,1] neg_hi:[0,0,1]
	v_pk_fma_f32 v[12:13], v[30:31], v[16:17], v[12:13]
	v_pk_fma_f32 v[10:11], v[32:33], v[14:15], v[10:11]
	v_cvt_pk_bf16_f32 v14, v18, v19
	v_cvt_pk_bf16_f32 v15, v8, v9
	v_cvt_pk_bf16_f32 v8, v22, v23
	v_cvt_pk_bf16_f32 v9, v20, v21
	v_cvt_pk_bf16_f32 v16, v26, v27
	v_cvt_pk_bf16_f32 v17, v24, v25
	v_cvt_pk_bf16_f32 v10, v10, v11
	v_cvt_pk_bf16_f32 v11, v12, v13
	global_store_dwordx2 v[6:7], v[14:15], off
	global_store_dwordx2 v[6:7], v[8:9], off offset:128
	global_store_dwordx2 v[4:5], v[16:17], off
	global_store_dwordx2 v[4:5], v[10:11], off offset:128

.LBB0_435:
	ds_read_b128 v[18:21], v194
	ds_read_b128 v[26:29], v194 offset:2048
	ds_read_b128 v[22:25], v195
	ds_read_b128 v[30:33], v195 offset:2048
	ds_read_b128 v[2:5], v197
	ds_read_b128 v[10:13], v197 offset:2048
	ds_read_b128 v[6:9], v198
	ds_read_b128 v[14:17], v198 offset:2048
	s_add_i32 s66, s38, 2
	s_add_u32 s40, s36, 0x80
	s_addc_u32 s39, s37, 0
	s_cmp_eq_u32 s52, s38
	s_cselect_b32 s38, s4, s40
	s_cselect_b32 s39, s5, s39
	s_cselect_b32 s41, s35, s65
	s_cselect_b32 s40, s34, s64
	v_lshl_add_u64 v[186:187], s[36:37], 0, v[170:171]
	s_add_i32 m0, s44, 0xc000
	ds_read_b128 v[178:181], v199
	ds_read_b128 v[202:205], v199 offset:2048
	ds_read_b128 v[182:185], v200
	ds_read_b128 v[206:209], v200 offset:2048
	ds_read_b128 v[210:213], v199 offset:4096
	ds_read_b128 v[218:221], v199 offset:6144
	ds_read_b128 v[214:217], v200 offset:4096
	ds_read_b128 v[222:225], v200 offset:6144
	global_load_lds_dwordx4 v[186:187], off
	v_lshl_add_u64 v[186:187], s[36:37], 0, v[172:173]
	s_add_i32 m0, s44, 0xe000
	s_nop 0
	global_load_lds_dwordx4 v[186:187], off
	s_waitcnt vmcnt(8)
	s_waitcnt lgkmcnt(0)
	s_barrier
	s_setprio 1
	s_waitcnt lgkmcnt(0)
	v_mfma_scale_f32_16x16x128_f8f6f4 v[158:161], v[18:25], v[178:185], v[158:161], v1, v1 op_sel_hi:[0,0,0]
	v_mfma_scale_f32_16x16x128_f8f6f4 v[154:157], v[26:33], v[178:185], v[154:157], v1, v1 op_sel_hi:[0,0,0]
	v_mfma_scale_f32_16x16x128_f8f6f4 v[150:153], v[18:25], v[202:209], v[150:153], v1, v1 op_sel_hi:[0,0,0]
	v_mfma_scale_f32_16x16x128_f8f6f4 v[146:149], v[26:33], v[202:209], v[146:149], v1, v1 op_sel_hi:[0,0,0]
	v_mfma_scale_f32_16x16x128_f8f6f4 v[138:141], v[18:25], v[210:217], v[138:141], v1, v1 op_sel_hi:[0,0,0]
	v_mfma_scale_f32_16x16x128_f8f6f4 v[130:133], v[26:33], v[210:217], v[130:133], v1, v1 op_sel_hi:[0,0,0]
	v_mfma_scale_f32_16x16x128_f8f6f4 v[122:125], v[18:25], v[218:225], v[122:125], v1, v1 op_sel_hi:[0,0,0]
	v_mfma_scale_f32_16x16x128_f8f6f4 v[114:117], v[26:33], v[218:225], v[114:117], v1, v1 op_sel_hi:[0,0,0]
	s_setprio 0
	s_setprio 1
	v_mfma_scale_f32_16x16x128_f8f6f4 v[142:145], v[2:9], v[178:185], v[142:145], v1, v1 op_sel_hi:[0,0,0]
	v_mfma_scale_f32_16x16x128_f8f6f4 v[134:137], v[10:17], v[178:185], v[134:137], v1, v1 op_sel_hi:[0,0,0]
	v_mfma_scale_f32_16x16x128_f8f6f4 v[126:129], v[2:9], v[202:209], v[126:129], v1, v1 op_sel_hi:[0,0,0]
	v_mfma_scale_f32_16x16x128_f8f6f4 v[118:121], v[10:17], v[202:209], v[118:121], v1, v1 op_sel_hi:[0,0,0]
	v_mfma_scale_f32_16x16x128_f8f6f4 v[110:113], v[2:9], v[210:217], v[110:113], v1, v1 op_sel_hi:[0,0,0]
	v_mfma_scale_f32_16x16x128_f8f6f4 v[106:109], v[10:17], v[210:217], v[106:109], v1, v1 op_sel_hi:[0,0,0]
	v_mfma_scale_f32_16x16x128_f8f6f4 v[102:105], v[2:9], v[218:225], v[102:105], v1, v1 op_sel_hi:[0,0,0]
	v_mfma_scale_f32_16x16x128_f8f6f4 v[98:101], v[10:17], v[218:225], v[98:101], v1, v1 op_sel_hi:[0,0,0]
	s_setprio 0
	s_barrier
	s_add_i32 s67, s54, s43
	v_lshl_add_u64 v[178:179], s[40:41], 0, v[164:165]
	s_mov_b32 m0, s67
	ds_read_b128 v[202:205], v199 offset:16384
	ds_read_b128 v[210:213], v199 offset:18432
	ds_read_b128 v[206:209], v200 offset:16384
	ds_read_b128 v[214:217], v200 offset:18432
	ds_read_b128 v[218:221], v199 offset:20480
	ds_read_b128 v[226:229], v199 offset:22528
	ds_read_b128 v[222:225], v200 offset:20480
	ds_read_b128 v[230:233], v200 offset:22528
	global_load_lds_dwordx4 v[178:179], off
	s_add_i32 m0, s67, 0x2000
	v_lshl_add_u64 v[180:181], s[40:41], 0, v[168:169]
	s_add_u32 s40, s40, s6
	s_addc_u32 s41, s41, s7
	s_add_i32 s67, s55, s43
	global_load_lds_dwordx4 v[180:181], off
	v_lshl_add_u64 v[182:183], s[40:41], 0, v[164:165]
	s_mov_b32 m0, s67
	v_lshl_add_u64 v[184:185], s[40:41], 0, v[168:169]
	global_load_lds_dwordx4 v[182:183], off
	s_add_i32 m0, s67, 0x2000
	v_lshl_add_u64 v[186:187], s[38:39], 0, v[162:163]
	global_load_lds_dwordx4 v[184:185], off
	s_mov_b32 m0, s44
	v_lshl_add_u64 v[188:189], s[38:39], 0, v[166:167]
	global_load_lds_dwordx4 v[186:187], off
	s_mov_b32 m0, s45
	s_nop 0
	global_load_lds_dwordx4 v[188:189], off
	s_waitcnt vmcnt(8)
	s_waitcnt lgkmcnt(0)
	s_barrier
	s_setprio 1
	s_waitcnt lgkmcnt(0)
	v_mfma_scale_f32_16x16x128_f8f6f4 v[94:97], v[18:25], v[202:209], v[94:97], v1, v1 op_sel_hi:[0,0,0]
	v_mfma_scale_f32_16x16x128_f8f6f4 v[90:93], v[26:33], v[202:209], v[90:93], v1, v1 op_sel_hi:[0,0,0]
	v_mfma_scale_f32_16x16x128_f8f6f4 v[86:89], v[18:25], v[210:217], v[86:89], v1, v1 op_sel_hi:[0,0,0]
	v_mfma_scale_f32_16x16x128_f8f6f4 v[82:85], v[26:33], v[210:217], v[82:85], v1, v1 op_sel_hi:[0,0,0]
	v_mfma_scale_f32_16x16x128_f8f6f4 v[74:77], v[18:25], v[218:225], v[74:77], v1, v1 op_sel_hi:[0,0,0]
	v_mfma_scale_f32_16x16x128_f8f6f4 v[66:69], v[26:33], v[218:225], v[66:69], v1, v1 op_sel_hi:[0,0,0]
	v_mfma_scale_f32_16x16x128_f8f6f4 v[58:61], v[18:25], v[226:233], v[58:61], v1, v1 op_sel_hi:[0,0,0]
	v_mfma_scale_f32_16x16x128_f8f6f4 v[50:53], v[26:33], v[226:233], v[50:53], v1, v1 op_sel_hi:[0,0,0]
	s_setprio 0
	s_setprio 1
	v_mfma_scale_f32_16x16x128_f8f6f4 v[78:81], v[2:9], v[202:209], v[78:81], v1, v1 op_sel_hi:[0,0,0]
	v_mfma_scale_f32_16x16x128_f8f6f4 v[70:73], v[10:17], v[202:209], v[70:73], v1, v1 op_sel_hi:[0,0,0]
	v_mfma_scale_f32_16x16x128_f8f6f4 v[62:65], v[2:9], v[210:217], v[62:65], v1, v1 op_sel_hi:[0,0,0]
	v_mfma_scale_f32_16x16x128_f8f6f4 v[54:57], v[10:17], v[210:217], v[54:57], v1, v1 op_sel_hi:[0,0,0]
	v_mfma_scale_f32_16x16x128_f8f6f4 v[46:49], v[2:9], v[218:225], v[46:49], v1, v1 op_sel_hi:[0,0,0]
	v_mfma_scale_f32_16x16x128_f8f6f4 v[42:45], v[10:17], v[218:225], v[42:45], v1, v1 op_sel_hi:[0,0,0]
	v_mfma_scale_f32_16x16x128_f8f6f4 v[38:41], v[2:9], v[226:233], v[38:41], v1, v1 op_sel_hi:[0,0,0]
	v_mfma_scale_f32_16x16x128_f8f6f4 v[34:37], v[10:17], v[226:233], v[34:37], v1, v1 op_sel_hi:[0,0,0]
	s_setprio 0
	s_barrier
	s_add_i32 s40, 0, 0x18000
	s_add_i32 s41, 0, 0x1c000
	v_add_u32_e32 v6, s40, v190
	v_add_u32_e32 v14, s40, v191
	v_add_u32_e32 v22, s41, v190
	v_add_u32_e32 v30, s41, v191
	ds_read_b128 v[2:5], v6
	ds_read_b128 v[10:13], v6 offset:2048
	ds_read_b128 v[6:9], v14
	ds_read_b128 v[14:17], v14 offset:2048
	ds_read_b128 v[18:21], v22
	ds_read_b128 v[26:29], v22 offset:2048
	ds_read_b128 v[22:25], v30
	ds_read_b128 v[30:33], v30 offset:2048
	s_add_u32 s38, s38, s6
	s_addc_u32 s39, s39, s7
	s_mov_b32 m0, s46
	ds_read_b128 v[202:205], v199 offset:32768
	ds_read_b128 v[210:213], v199 offset:34816
	ds_read_b128 v[206:209], v200 offset:32768
	ds_read_b128 v[214:217], v200 offset:34816
	ds_read_b128 v[218:221], v199 offset:36864
	ds_read_b128 v[226:229], v199 offset:38912
	ds_read_b128 v[222:225], v200 offset:36864
	ds_read_b128 v[230:233], v200 offset:38912
	global_load_lds_dwordx4 v162, s[38:39]
	s_mov_b32 m0, s47
	s_nop 0
	global_load_lds_dwordx4 v166, s[38:39]
	s_waitcnt vmcnt(8)
	s_waitcnt lgkmcnt(0)
	s_barrier
	s_setprio 1
	s_waitcnt lgkmcnt(0)
	v_mfma_scale_f32_16x16x128_f8f6f4 v[158:161], v[2:9], v[202:209], v[158:161], v1, v1 op_sel_hi:[0,0,0]
	v_mfma_scale_f32_16x16x128_f8f6f4 v[154:157], v[10:17], v[202:209], v[154:157], v1, v1 op_sel_hi:[0,0,0]
	v_mfma_scale_f32_16x16x128_f8f6f4 v[150:153], v[2:9], v[210:217], v[150:153], v1, v1 op_sel_hi:[0,0,0]
	v_mfma_scale_f32_16x16x128_f8f6f4 v[146:149], v[10:17], v[210:217], v[146:149], v1, v1 op_sel_hi:[0,0,0]
	v_mfma_scale_f32_16x16x128_f8f6f4 v[138:141], v[2:9], v[218:225], v[138:141], v1, v1 op_sel_hi:[0,0,0]
	v_mfma_scale_f32_16x16x128_f8f6f4 v[130:133], v[10:17], v[218:225], v[130:133], v1, v1 op_sel_hi:[0,0,0]
	v_mfma_scale_f32_16x16x128_f8f6f4 v[122:125], v[2:9], v[226:233], v[122:125], v1, v1 op_sel_hi:[0,0,0]
	v_mfma_scale_f32_16x16x128_f8f6f4 v[114:117], v[10:17], v[226:233], v[114:117], v1, v1 op_sel_hi:[0,0,0]
	s_setprio 0
	s_setprio 1
	v_mfma_scale_f32_16x16x128_f8f6f4 v[142:145], v[18:25], v[202:209], v[142:145], v1, v1 op_sel_hi:[0,0,0]
	v_mfma_scale_f32_16x16x128_f8f6f4 v[134:137], v[26:33], v[202:209], v[134:137], v1, v1 op_sel_hi:[0,0,0]
	v_mfma_scale_f32_16x16x128_f8f6f4 v[126:129], v[18:25], v[210:217], v[126:129], v1, v1 op_sel_hi:[0,0,0]
	v_mfma_scale_f32_16x16x128_f8f6f4 v[118:121], v[26:33], v[210:217], v[118:121], v1, v1 op_sel_hi:[0,0,0]
	v_mfma_scale_f32_16x16x128_f8f6f4 v[110:113], v[18:25], v[218:225], v[110:113], v1, v1 op_sel_hi:[0,0,0]
	v_mfma_scale_f32_16x16x128_f8f6f4 v[106:109], v[26:33], v[218:225], v[106:109], v1, v1 op_sel_hi:[0,0,0]
	v_mfma_scale_f32_16x16x128_f8f6f4 v[102:105], v[18:25], v[226:233], v[102:105], v1, v1 op_sel_hi:[0,0,0]
	v_mfma_scale_f32_16x16x128_f8f6f4 v[98:101], v[26:33], v[226:233], v[98:101], v1, v1 op_sel_hi:[0,0,0]
	s_setprio 0
	s_barrier
	s_add_i32 s38, s40, s43
	v_lshl_add_u64 v[178:179], v[178:179], 0, s[12:13]
	s_mov_b32 m0, s38
	ds_read_b128 v[202:205], v199 offset:49152
	ds_read_b128 v[210:213], v199 offset:51200
	ds_read_b128 v[206:209], v200 offset:49152
	ds_read_b128 v[214:217], v200 offset:51200
	ds_read_b128 v[218:221], v199 offset:53248
	ds_read_b128 v[226:229], v199 offset:55296
	ds_read_b128 v[222:225], v200 offset:53248
	ds_read_b128 v[230:233], v200 offset:55296
	global_load_lds_dwordx4 v[178:179], off
	v_lshl_add_u64 v[178:179], v[180:181], 0, s[12:13]
	s_add_i32 m0, s38, 0x2000
	s_add_i32 s38, s41, s43
	global_load_lds_dwordx4 v[178:179], off
	v_lshl_add_u64 v[178:179], v[182:183], 0, s[12:13]
	s_mov_b32 m0, s38
	s_nop 0
	global_load_lds_dwordx4 v[178:179], off
	v_lshl_add_u64 v[178:179], v[184:185], 0, s[12:13]
	s_add_i32 m0, s38, 0x2000
	s_nop 0
	global_load_lds_dwordx4 v[178:179], off
	v_lshl_add_u64 v[178:179], v[186:187], 0, s[12:13]
	s_mov_b32 m0, s49
	s_nop 0
	global_load_lds_dwordx4 v[178:179], off
	v_lshl_add_u64 v[178:179], v[188:189], 0, s[12:13]
	s_mov_b32 m0, s50
	s_nop 0
	global_load_lds_dwordx4 v[178:179], off
	s_waitcnt vmcnt(8)
	s_waitcnt lgkmcnt(0)
	s_barrier
	s_setprio 1
	s_waitcnt lgkmcnt(0)
	v_mfma_scale_f32_16x16x128_f8f6f4 v[94:97], v[2:9], v[202:209], v[94:97], v1, v1 op_sel_hi:[0,0,0]
	v_mfma_scale_f32_16x16x128_f8f6f4 v[90:93], v[10:17], v[202:209], v[90:93], v1, v1 op_sel_hi:[0,0,0]
	v_mfma_scale_f32_16x16x128_f8f6f4 v[86:89], v[2:9], v[210:217], v[86:89], v1, v1 op_sel_hi:[0,0,0]
	v_mfma_scale_f32_16x16x128_f8f6f4 v[82:85], v[10:17], v[210:217], v[82:85], v1, v1 op_sel_hi:[0,0,0]
	v_mfma_scale_f32_16x16x128_f8f6f4 v[74:77], v[2:9], v[218:225], v[74:77], v1, v1 op_sel_hi:[0,0,0]
	v_mfma_scale_f32_16x16x128_f8f6f4 v[66:69], v[10:17], v[218:225], v[66:69], v1, v1 op_sel_hi:[0,0,0]
	v_mfma_scale_f32_16x16x128_f8f6f4 v[58:61], v[2:9], v[226:233], v[58:61], v1, v1 op_sel_hi:[0,0,0]
	v_mfma_scale_f32_16x16x128_f8f6f4 v[50:53], v[10:17], v[226:233], v[50:53], v1, v1 op_sel_hi:[0,0,0]
	s_setprio 0
	s_setprio 1
	v_mfma_scale_f32_16x16x128_f8f6f4 v[78:81], v[18:25], v[202:209], v[78:81], v1, v1 op_sel_hi:[0,0,0]
	v_mfma_scale_f32_16x16x128_f8f6f4 v[70:73], v[26:33], v[202:209], v[70:73], v1, v1 op_sel_hi:[0,0,0]
	v_mfma_scale_f32_16x16x128_f8f6f4 v[62:65], v[18:25], v[210:217], v[62:65], v1, v1 op_sel_hi:[0,0,0]
	v_mfma_scale_f32_16x16x128_f8f6f4 v[54:57], v[26:33], v[210:217], v[54:57], v1, v1 op_sel_hi:[0,0,0]
	v_mfma_scale_f32_16x16x128_f8f6f4 v[46:49], v[18:25], v[218:225], v[46:49], v1, v1 op_sel_hi:[0,0,0]
	v_mfma_scale_f32_16x16x128_f8f6f4 v[42:45], v[26:33], v[218:225], v[42:45], v1, v1 op_sel_hi:[0,0,0]
	v_mfma_scale_f32_16x16x128_f8f6f4 v[38:41], v[18:25], v[226:233], v[38:41], v1, v1 op_sel_hi:[0,0,0]
	v_mfma_scale_f32_16x16x128_f8f6f4 v[34:37], v[26:33], v[226:233], v[34:37], v1, v1 op_sel_hi:[0,0,0]
	s_setprio 0
	s_barrier
	s_add_u32 s36, s36, 0x100
	s_addc_u32 s37, s37, 0
	s_add_u32 s64, s64, 0x100
	s_addc_u32 s65, s65, 0
	s_cmp_ge_i32 s66, s51
	s_mov_b32 s38, s66
	s_cbranch_scc0 .LBB0_435
	v_pk_mul_f32 v[160:161], v[160:161], s[22:23] op_sel_hi:[1,0]
	v_pk_mul_f32 v[158:159], v[158:159], s[22:23] op_sel_hi:[1,0]
	v_pk_mul_f32 v[156:157], v[156:157], s[22:23] op_sel_hi:[1,0]
	v_pk_mul_f32 v[154:155], v[154:155], s[22:23] op_sel_hi:[1,0]
	v_pk_mul_f32 v[182:183], v[144:145], s[22:23] op_sel_hi:[1,0]
	v_pk_mul_f32 v[184:185], v[142:143], s[22:23] op_sel_hi:[1,0]
	v_pk_mul_f32 v[186:187], v[136:137], s[22:23] op_sel_hi:[1,0]
	v_pk_mul_f32 v[188:189], v[134:135], s[22:23] op_sel_hi:[1,0]
	v_pk_mul_f32 v[142:143], v[152:153], s[22:23] op_sel_hi:[1,0]
	v_pk_mul_f32 v[144:145], v[150:151], s[22:23] op_sel_hi:[1,0]
	v_pk_mul_f32 v[148:149], v[148:149], s[22:23] op_sel_hi:[1,0]
	v_pk_mul_f32 v[146:147], v[146:147], s[22:23] op_sel_hi:[1,0]
	v_pk_mul_f32 v[150:151], v[128:129], s[22:23] op_sel_hi:[1,0]
	v_pk_mul_f32 v[152:153], v[126:127], s[22:23] op_sel_hi:[1,0]
	v_pk_mul_f32 v[178:179], v[120:121], s[22:23] op_sel_hi:[1,0]
	v_pk_mul_f32 v[180:181], v[118:119], s[22:23] op_sel_hi:[1,0]
	v_pk_mul_f32 v[134:135], v[140:141], s[22:23] op_sel_hi:[1,0]
	v_pk_mul_f32 v[136:137], v[138:139], s[22:23] op_sel_hi:[1,0]
	v_pk_mul_f32 v[138:139], v[132:133], s[22:23] op_sel_hi:[1,0]
	v_pk_mul_f32 v[140:141], v[130:131], s[22:23] op_sel_hi:[1,0]
	v_pk_mul_f32 v[126:127], v[112:113], s[22:23] op_sel_hi:[1,0]
	v_pk_mul_f32 v[128:129], v[110:111], s[22:23] op_sel_hi:[1,0]
	v_pk_mul_f32 v[130:131], v[108:109], s[22:23] op_sel_hi:[1,0]
	v_pk_mul_f32 v[132:133], v[106:107], s[22:23] op_sel_hi:[1,0]
	v_pk_mul_f32 v[118:119], v[124:125], s[22:23] op_sel_hi:[1,0]
	v_pk_mul_f32 v[120:121], v[122:123], s[22:23] op_sel_hi:[1,0]
	v_pk_mul_f32 v[116:117], v[116:117], s[22:23] op_sel_hi:[1,0]
	v_pk_mul_f32 v[114:115], v[114:115], s[22:23] op_sel_hi:[1,0]
	v_pk_mul_f32 v[106:107], v[104:105], s[22:23] op_sel_hi:[1,0]
	v_pk_mul_f32 v[108:109], v[102:103], s[22:23] op_sel_hi:[1,0]
	v_pk_mul_f32 v[110:111], v[100:101], s[22:23] op_sel_hi:[1,0]
	v_pk_mul_f32 v[112:113], v[98:99], s[22:23] op_sel_hi:[1,0]
	v_pk_mul_f32 v[98:99], v[96:97], s[22:23] op_sel_hi:[1,0]
	v_pk_mul_f32 v[100:101], v[94:95], s[22:23] op_sel_hi:[1,0]
	v_pk_mul_f32 v[102:103], v[92:93], s[22:23] op_sel_hi:[1,0]
	v_pk_mul_f32 v[104:105], v[90:91], s[22:23] op_sel_hi:[1,0]
	v_pk_mul_f32 v[90:91], v[80:81], s[22:23] op_sel_hi:[1,0]
	v_pk_mul_f32 v[92:93], v[78:79], s[22:23] op_sel_hi:[1,0]
	v_pk_mul_f32 v[94:95], v[72:73], s[22:23] op_sel_hi:[1,0]
	v_pk_mul_f32 v[96:97], v[70:71], s[22:23] op_sel_hi:[1,0]
	v_pk_mul_f32 v[70:71], v[88:89], s[22:23] op_sel_hi:[1,0]
	v_pk_mul_f32 v[72:73], v[86:87], s[22:23] op_sel_hi:[1,0]
	v_pk_mul_f32 v[78:79], v[84:85], s[22:23] op_sel_hi:[1,0]
	v_pk_mul_f32 v[80:81], v[82:83], s[22:23] op_sel_hi:[1,0]
	v_pk_mul_f32 v[64:65], v[64:65], s[22:23] op_sel_hi:[1,0]
	v_pk_mul_f32 v[62:63], v[62:63], s[22:23] op_sel_hi:[1,0]
	v_pk_mul_f32 v[56:57], v[56:57], s[22:23] op_sel_hi:[1,0]
	v_pk_mul_f32 v[82:83], v[54:55], s[22:23] op_sel_hi:[1,0]
	v_pk_mul_f32 v[26:27], v[76:77], s[22:23] op_sel_hi:[1,0]
	v_pk_mul_f32 v[28:29], v[74:75], s[22:23] op_sel_hi:[1,0]
	v_pk_mul_f32 v[32:33], v[68:69], s[22:23] op_sel_hi:[1,0]
	v_pk_mul_f32 v[54:55], v[66:67], s[22:23] op_sel_hi:[1,0]
	v_pk_mul_f32 v[48:49], v[48:49], s[22:23] op_sel_hi:[1,0]
	v_pk_mul_f32 v[46:47], v[46:47], s[22:23] op_sel_hi:[1,0]
	v_pk_mul_f32 v[44:45], v[44:45], s[22:23] op_sel_hi:[1,0]
	v_pk_mul_f32 v[42:43], v[42:43], s[22:23] op_sel_hi:[1,0]
	v_pk_mul_f32 v[18:19], v[60:61], s[22:23] op_sel_hi:[1,0]
	v_pk_mul_f32 v[20:21], v[58:59], s[22:23] op_sel_hi:[1,0]
	v_pk_mul_f32 v[22:23], v[52:53], s[22:23] op_sel_hi:[1,0]
	v_pk_mul_f32 v[24:25], v[50:51], s[22:23] op_sel_hi:[1,0]
	v_pk_mul_f32 v[40:41], v[40:41], s[22:23] op_sel_hi:[1,0]
	v_pk_mul_f32 v[38:39], v[38:39], s[22:23] op_sel_hi:[1,0]
	v_pk_mul_f32 v[36:37], v[36:37], s[22:23] op_sel_hi:[1,0]
	v_pk_mul_f32 v[30:31], v[34:35], s[22:23] op_sel_hi:[1,0]

.LBB0_457:
	ds_read_b128 v[18:21], v190
	ds_read_b128 v[26:29], v190 offset:2048
	ds_read_b128 v[22:25], v191
	ds_read_b128 v[30:33], v191 offset:2048
	ds_read_b128 v[2:5], v192
	ds_read_b128 v[10:13], v192 offset:2048
	ds_read_b128 v[6:9], v193
	ds_read_b128 v[14:17], v193 offset:2048
	s_add_u32 s34, s30, 0xfffe0080
	s_addc_u32 s35, s31, -1
	s_cmp_eq_u32 s55, 4
	s_cselect_b32 s37, s23, s35
	s_cselect_b32 s36, s51, s34
	s_cselect_b32 s35, s17, s54
	s_cselect_b32 s34, s52, s53
	s_add_i32 m0, s29, 0xc000
	ds_read_b128 v[178:181], v194
	ds_read_b128 v[198:201], v194 offset:2048
	ds_read_b128 v[182:185], v195
	ds_read_b128 v[202:205], v195 offset:2048
	ds_read_b128 v[206:209], v194 offset:4096
	ds_read_b128 v[214:217], v194 offset:6144
	ds_read_b128 v[210:213], v195 offset:4096
	ds_read_b128 v[218:221], v195 offset:6144
	global_load_lds_dwordx4 v170, s[30:31]
	s_add_i32 m0, s29, 0xe000
	s_nop 0
	global_load_lds_dwordx4 v172, s[30:31]
	s_waitcnt vmcnt(8)
	s_waitcnt lgkmcnt(0)
	s_barrier
	s_setprio 1
	s_waitcnt lgkmcnt(0)
	v_mfma_scale_f32_16x16x128_f8f6f4 v[158:161], v[18:25], v[178:185], v[158:161], v1, v1 op_sel_hi:[0,0,0]
	v_mfma_scale_f32_16x16x128_f8f6f4 v[154:157], v[26:33], v[178:185], v[154:157], v1, v1 op_sel_hi:[0,0,0]
	v_mfma_scale_f32_16x16x128_f8f6f4 v[142:145], v[18:25], v[198:205], v[142:145], v1, v1 op_sel_hi:[0,0,0]
	v_mfma_scale_f32_16x16x128_f8f6f4 v[138:141], v[26:33], v[198:205], v[138:141], v1, v1 op_sel_hi:[0,0,0]
	v_mfma_scale_f32_16x16x128_f8f6f4 v[126:129], v[18:25], v[206:213], v[126:129], v1, v1 op_sel_hi:[0,0,0]
	v_mfma_scale_f32_16x16x128_f8f6f4 v[122:125], v[26:33], v[206:213], v[122:125], v1, v1 op_sel_hi:[0,0,0]
	v_mfma_scale_f32_16x16x128_f8f6f4 v[110:113], v[18:25], v[214:221], v[110:113], v1, v1 op_sel_hi:[0,0,0]
	v_mfma_scale_f32_16x16x128_f8f6f4 v[106:109], v[26:33], v[214:221], v[106:109], v1, v1 op_sel_hi:[0,0,0]
	s_setprio 0
	s_setprio 1
	v_mfma_scale_f32_16x16x128_f8f6f4 v[150:153], v[2:9], v[178:185], v[150:153], v1, v1 op_sel_hi:[0,0,0]
	v_mfma_scale_f32_16x16x128_f8f6f4 v[146:149], v[10:17], v[178:185], v[146:149], v1, v1 op_sel_hi:[0,0,0]
	v_mfma_scale_f32_16x16x128_f8f6f4 v[134:137], v[2:9], v[198:205], v[134:137], v1, v1 op_sel_hi:[0,0,0]
	v_mfma_scale_f32_16x16x128_f8f6f4 v[130:133], v[10:17], v[198:205], v[130:133], v1, v1 op_sel_hi:[0,0,0]
	v_mfma_scale_f32_16x16x128_f8f6f4 v[118:121], v[2:9], v[206:213], v[118:121], v1, v1 op_sel_hi:[0,0,0]
	v_mfma_scale_f32_16x16x128_f8f6f4 v[114:117], v[10:17], v[206:213], v[114:117], v1, v1 op_sel_hi:[0,0,0]
	v_mfma_scale_f32_16x16x128_f8f6f4 v[102:105], v[2:9], v[214:221], v[102:105], v1, v1 op_sel_hi:[0,0,0]
	v_mfma_scale_f32_16x16x128_f8f6f4 v[98:101], v[10:17], v[214:221], v[98:101], v1, v1 op_sel_hi:[0,0,0]
	s_setprio 0
	s_barrier
	s_add_i32 s56, s46, s33
	v_lshl_add_u64 v[178:179], s[34:35], 0, v[164:165]
	s_mov_b32 m0, s56
	ds_read_b128 v[198:201], v194 offset:16384
	ds_read_b128 v[206:209], v194 offset:18432
	ds_read_b128 v[202:205], v195 offset:16384
	ds_read_b128 v[210:213], v195 offset:18432
	ds_read_b128 v[214:217], v194 offset:20480
	ds_read_b128 v[222:225], v194 offset:22528
	ds_read_b128 v[218:221], v195 offset:20480
	ds_read_b128 v[226:229], v195 offset:22528
	global_load_lds_dwordx4 v[178:179], off
	s_add_i32 m0, s56, 0x2000
	s_add_u32 s56, s34, 0x20000
	v_lshl_add_u64 v[180:181], s[34:35], 0, v[168:169]
	s_addc_u32 s57, s35, 0
	s_add_i32 s58, s47, s33
	global_load_lds_dwordx4 v[180:181], off
	s_mov_b32 m0, s58
	v_lshl_add_u64 v[184:185], s[36:37], 0, v[166:167]
	global_load_lds_dwordx4 v164, s[56:57]
	s_add_i32 m0, s58, 0x2000
	s_nop 0
	global_load_lds_dwordx4 v168, s[56:57]
	v_lshl_add_u64 v[182:183], s[36:37], 0, v[162:163]
	s_mov_b32 m0, s29
	s_nop 0
	global_load_lds_dwordx4 v[182:183], off
	s_mov_b32 m0, s39
	s_nop 0
	global_load_lds_dwordx4 v[184:185], off
	s_waitcnt vmcnt(8)
	s_waitcnt lgkmcnt(0)
	s_barrier
	s_setprio 1
	s_waitcnt lgkmcnt(0)
	v_mfma_scale_f32_16x16x128_f8f6f4 v[94:97], v[18:25], v[198:205], v[94:97], v1, v1 op_sel_hi:[0,0,0]
	v_mfma_scale_f32_16x16x128_f8f6f4 v[90:93], v[26:33], v[198:205], v[90:93], v1, v1 op_sel_hi:[0,0,0]
	v_mfma_scale_f32_16x16x128_f8f6f4 v[78:81], v[18:25], v[206:213], v[78:81], v1, v1 op_sel_hi:[0,0,0]
	v_mfma_scale_f32_16x16x128_f8f6f4 v[74:77], v[26:33], v[206:213], v[74:77], v1, v1 op_sel_hi:[0,0,0]
	v_mfma_scale_f32_16x16x128_f8f6f4 v[62:65], v[18:25], v[214:221], v[62:65], v1, v1 op_sel_hi:[0,0,0]
	v_mfma_scale_f32_16x16x128_f8f6f4 v[58:61], v[26:33], v[214:221], v[58:61], v1, v1 op_sel_hi:[0,0,0]
	v_mfma_scale_f32_16x16x128_f8f6f4 v[46:49], v[18:25], v[222:229], v[46:49], v1, v1 op_sel_hi:[0,0,0]
	v_mfma_scale_f32_16x16x128_f8f6f4 v[42:45], v[26:33], v[222:229], v[42:45], v1, v1 op_sel_hi:[0,0,0]
	s_setprio 0
	s_setprio 1
	v_mfma_scale_f32_16x16x128_f8f6f4 v[86:89], v[2:9], v[198:205], v[86:89], v1, v1 op_sel_hi:[0,0,0]
	v_mfma_scale_f32_16x16x128_f8f6f4 v[82:85], v[10:17], v[198:205], v[82:85], v1, v1 op_sel_hi:[0,0,0]
	v_mfma_scale_f32_16x16x128_f8f6f4 v[70:73], v[2:9], v[206:213], v[70:73], v1, v1 op_sel_hi:[0,0,0]
	v_mfma_scale_f32_16x16x128_f8f6f4 v[66:69], v[10:17], v[206:213], v[66:69], v1, v1 op_sel_hi:[0,0,0]
	v_mfma_scale_f32_16x16x128_f8f6f4 v[54:57], v[2:9], v[214:221], v[54:57], v1, v1 op_sel_hi:[0,0,0]
	v_mfma_scale_f32_16x16x128_f8f6f4 v[50:53], v[10:17], v[214:221], v[50:53], v1, v1 op_sel_hi:[0,0,0]
	v_mfma_scale_f32_16x16x128_f8f6f4 v[38:41], v[2:9], v[222:229], v[38:41], v1, v1 op_sel_hi:[0,0,0]
	v_mfma_scale_f32_16x16x128_f8f6f4 v[34:37], v[10:17], v[222:229], v[34:37], v1, v1 op_sel_hi:[0,0,0]
	s_setprio 0
	s_barrier
	s_add_i32 s56, 0, 0x18000
	s_add_i32 s57, 0, 0x1c000
	v_add_u32_e32 v6, s56, v186
	v_add_u32_e32 v14, s56, v187
	v_add_u32_e32 v22, s57, v186
	v_add_u32_e32 v30, s57, v187
	ds_read_b128 v[2:5], v6
	ds_read_b128 v[10:13], v6 offset:2048
	ds_read_b128 v[6:9], v14
	ds_read_b128 v[14:17], v14 offset:2048
	ds_read_b128 v[18:21], v22
	ds_read_b128 v[26:29], v22 offset:2048
	ds_read_b128 v[22:25], v30
	ds_read_b128 v[30:33], v30 offset:2048
	s_add_u32 s36, s36, 0x20000
	s_addc_u32 s37, s37, 0
	s_mov_b32 m0, s40
	ds_read_b128 v[198:201], v194 offset:32768
	ds_read_b128 v[206:209], v194 offset:34816
	ds_read_b128 v[202:205], v195 offset:32768
	ds_read_b128 v[210:213], v195 offset:34816
	ds_read_b128 v[214:217], v194 offset:36864
	ds_read_b128 v[222:225], v194 offset:38912
	ds_read_b128 v[218:221], v195 offset:36864
	ds_read_b128 v[226:229], v195 offset:38912
	global_load_lds_dwordx4 v162, s[36:37]
	s_mov_b32 m0, s41
	s_nop 0
	global_load_lds_dwordx4 v166, s[36:37]
	s_waitcnt vmcnt(8)
	s_waitcnt lgkmcnt(0)
	s_barrier
	s_setprio 1
	s_waitcnt lgkmcnt(0)
	v_mfma_scale_f32_16x16x128_f8f6f4 v[158:161], v[2:9], v[198:205], v[158:161], v1, v1 op_sel_hi:[0,0,0]
	v_mfma_scale_f32_16x16x128_f8f6f4 v[154:157], v[10:17], v[198:205], v[154:157], v1, v1 op_sel_hi:[0,0,0]
	v_mfma_scale_f32_16x16x128_f8f6f4 v[142:145], v[2:9], v[206:213], v[142:145], v1, v1 op_sel_hi:[0,0,0]
	v_mfma_scale_f32_16x16x128_f8f6f4 v[138:141], v[10:17], v[206:213], v[138:141], v1, v1 op_sel_hi:[0,0,0]
	v_mfma_scale_f32_16x16x128_f8f6f4 v[126:129], v[2:9], v[214:221], v[126:129], v1, v1 op_sel_hi:[0,0,0]
	v_mfma_scale_f32_16x16x128_f8f6f4 v[122:125], v[10:17], v[214:221], v[122:125], v1, v1 op_sel_hi:[0,0,0]
	v_mfma_scale_f32_16x16x128_f8f6f4 v[110:113], v[2:9], v[222:229], v[110:113], v1, v1 op_sel_hi:[0,0,0]
	v_mfma_scale_f32_16x16x128_f8f6f4 v[106:109], v[10:17], v[222:229], v[106:109], v1, v1 op_sel_hi:[0,0,0]
	s_setprio 0
	s_setprio 1
	v_mfma_scale_f32_16x16x128_f8f6f4 v[150:153], v[18:25], v[198:205], v[150:153], v1, v1 op_sel_hi:[0,0,0]
	v_mfma_scale_f32_16x16x128_f8f6f4 v[146:149], v[26:33], v[198:205], v[146:149], v1, v1 op_sel_hi:[0,0,0]
	v_mfma_scale_f32_16x16x128_f8f6f4 v[134:137], v[18:25], v[206:213], v[134:137], v1, v1 op_sel_hi:[0,0,0]
	v_mfma_scale_f32_16x16x128_f8f6f4 v[130:133], v[26:33], v[206:213], v[130:133], v1, v1 op_sel_hi:[0,0,0]
	v_mfma_scale_f32_16x16x128_f8f6f4 v[118:121], v[18:25], v[214:221], v[118:121], v1, v1 op_sel_hi:[0,0,0]
	v_mfma_scale_f32_16x16x128_f8f6f4 v[114:117], v[26:33], v[214:221], v[114:117], v1, v1 op_sel_hi:[0,0,0]
	v_mfma_scale_f32_16x16x128_f8f6f4 v[102:105], v[18:25], v[222:229], v[102:105], v1, v1 op_sel_hi:[0,0,0]
	v_mfma_scale_f32_16x16x128_f8f6f4 v[98:101], v[26:33], v[222:229], v[98:101], v1, v1 op_sel_hi:[0,0,0]
	s_setprio 0
	s_barrier
	s_add_i32 s36, s56, s33
	v_lshl_add_u64 v[178:179], v[178:179], 0, s[8:9]
	s_mov_b32 m0, s36
	ds_read_b128 v[198:201], v194 offset:49152
	ds_read_b128 v[206:209], v194 offset:51200
	ds_read_b128 v[202:205], v195 offset:49152
	ds_read_b128 v[210:213], v195 offset:51200
	ds_read_b128 v[214:217], v194 offset:53248
	ds_read_b128 v[222:225], v194 offset:55296
	ds_read_b128 v[218:221], v195 offset:53248
	ds_read_b128 v[226:229], v195 offset:55296
	global_load_lds_dwordx4 v[178:179], off
	s_add_i32 m0, s36, 0x2000
	s_add_u32 s34, s34, 0x20080
	v_lshl_add_u64 v[178:179], v[180:181], 0, s[8:9]
	s_addc_u32 s35, s35, 0
	s_add_i32 s36, s57, s33
	global_load_lds_dwordx4 v[178:179], off
	s_mov_b32 m0, s36
	s_nop 0
	global_load_lds_dwordx4 v164, s[34:35]
	s_add_i32 m0, s36, 0x2000
	s_nop 0
	global_load_lds_dwordx4 v168, s[34:35]
	v_lshl_add_u64 v[178:179], v[182:183], 0, s[8:9]
	s_mov_b32 m0, s44
	s_nop 0
	global_load_lds_dwordx4 v[178:179], off
	v_lshl_add_u64 v[178:179], v[184:185], 0, s[8:9]
	s_mov_b32 m0, s45
	s_nop 0
	global_load_lds_dwordx4 v[178:179], off
	s_waitcnt vmcnt(8)
	s_waitcnt lgkmcnt(0)
	s_barrier
	s_setprio 1
	s_waitcnt lgkmcnt(0)
	v_mfma_scale_f32_16x16x128_f8f6f4 v[94:97], v[2:9], v[198:205], v[94:97], v1, v1 op_sel_hi:[0,0,0]
	v_mfma_scale_f32_16x16x128_f8f6f4 v[90:93], v[10:17], v[198:205], v[90:93], v1, v1 op_sel_hi:[0,0,0]
	v_mfma_scale_f32_16x16x128_f8f6f4 v[78:81], v[2:9], v[206:213], v[78:81], v1, v1 op_sel_hi:[0,0,0]
	v_mfma_scale_f32_16x16x128_f8f6f4 v[74:77], v[10:17], v[206:213], v[74:77], v1, v1 op_sel_hi:[0,0,0]
	v_mfma_scale_f32_16x16x128_f8f6f4 v[62:65], v[2:9], v[214:221], v[62:65], v1, v1 op_sel_hi:[0,0,0]
	v_mfma_scale_f32_16x16x128_f8f6f4 v[58:61], v[10:17], v[214:221], v[58:61], v1, v1 op_sel_hi:[0,0,0]
	v_mfma_scale_f32_16x16x128_f8f6f4 v[46:49], v[2:9], v[222:229], v[46:49], v1, v1 op_sel_hi:[0,0,0]
	v_mfma_scale_f32_16x16x128_f8f6f4 v[42:45], v[10:17], v[222:229], v[42:45], v1, v1 op_sel_hi:[0,0,0]
	s_setprio 0
	s_setprio 1
	v_mfma_scale_f32_16x16x128_f8f6f4 v[86:89], v[18:25], v[198:205], v[86:89], v1, v1 op_sel_hi:[0,0,0]
	v_mfma_scale_f32_16x16x128_f8f6f4 v[82:85], v[26:33], v[198:205], v[82:85], v1, v1 op_sel_hi:[0,0,0]
	v_mfma_scale_f32_16x16x128_f8f6f4 v[70:73], v[18:25], v[206:213], v[70:73], v1, v1 op_sel_hi:[0,0,0]
	v_mfma_scale_f32_16x16x128_f8f6f4 v[66:69], v[26:33], v[206:213], v[66:69], v1, v1 op_sel_hi:[0,0,0]
	v_mfma_scale_f32_16x16x128_f8f6f4 v[54:57], v[18:25], v[214:221], v[54:57], v1, v1 op_sel_hi:[0,0,0]
	v_mfma_scale_f32_16x16x128_f8f6f4 v[50:53], v[26:33], v[214:221], v[50:53], v1, v1 op_sel_hi:[0,0,0]
	v_mfma_scale_f32_16x16x128_f8f6f4 v[38:41], v[18:25], v[222:229], v[38:41], v1, v1 op_sel_hi:[0,0,0]
	v_mfma_scale_f32_16x16x128_f8f6f4 v[34:37], v[26:33], v[222:229], v[34:37], v1, v1 op_sel_hi:[0,0,0]
	s_setprio 0
	s_barrier
	s_add_i32 s55, s55, 2
	s_add_u32 s30, s30, 0x100
	s_addc_u32 s31, s31, 0
	s_add_u32 s53, s53, 0x100
	s_addc_u32 s54, s54, 0
	s_cmp_gt_u32 s55, 5
	s_cbranch_scc0 .LBB0_457
	s_nop 15
	s_nop 15
	s_and_b64 vcc, exec, s[10:11]
	s_cbranch_vccz .LBB0_460
	s_barrier
.LBB0_460:
	v_lshl_add_u32 v252, s28, 8, v188
	v_lshl_or_b32 v253, s50, 8, v189
	v_lshlrev_b32_e32 v254, 13, v252
	v_lshl_add_u32 v254, v253, 1, v254
	v_lshl_add_u32 v255, v252, 11, v253
	s_add_u32 s100, s20, 0x1000
	s_addc_u32 s101, s21, 0
	v_mov_b32_e32 v32, v254
	global_load_dwordx4 v[198:201], v32, s[20:21] offset:0
	global_load_dwordx4 v[202:205], v32, s[100:101] offset:0
	global_load_dwordx4 v[206:209], v32, s[20:21] offset:256
	global_load_dwordx4 v[210:213], v32, s[100:101] offset:256
	v_add_u32_e32 v32, 0x20000, v254
	global_load_dwordx4 v[214:217], v32, s[20:21] offset:0
	global_load_dwordx4 v[218:221], v32, s[100:101] offset:0
	global_load_dwordx4 v[222:225], v32, s[20:21] offset:256
	global_load_dwordx4 v[226:229], v32, s[100:101] offset:256
	v_add_u32_e32 v32, 0x40000, v254
	global_load_dwordx4 v[178:181], v32, s[20:21] offset:0
	global_load_dwordx4 v[182:185], v32, s[100:101] offset:0
	global_load_dwordx4 v[244:247], v32, s[20:21] offset:256
	global_load_dwordx4 v[248:251], v32, s[100:101] offset:256
	v_pk_mul_f32 v[4:5], v[160:161], s[12:13] op_sel_hi:[1,0]
	v_pk_mul_f32 v[2:3], v[158:159], s[12:13] op_sel_hi:[1,0]
	v_pk_mul_f32 v[8:9], v[156:157], s[12:13] op_sel_hi:[1,0]
	v_pk_mul_f32 v[6:7], v[154:155], s[12:13] op_sel_hi:[1,0]
	v_mov_b32_e32 v30, 0
	v_mov_b32_e32 v31, 0
	s_waitcnt vmcnt(10)
	v_lshlrev_b32_e32 v10, 16, v198
	v_and_b32_e32 v11, 0xffff0000, v198
	v_lshlrev_b32_e32 v12, 16, v199
	v_and_b32_e32 v13, 0xffff0000, v199
	v_lshlrev_b32_e32 v14, 16, v200
	v_and_b32_e32 v15, 0xffff0000, v200
	v_lshlrev_b32_e32 v16, 16, v201
	v_and_b32_e32 v17, 0xffff0000, v201
	v_lshlrev_b32_e32 v18, 16, v202
	v_and_b32_e32 v19, 0xffff0000, v202
	v_lshlrev_b32_e32 v20, 16, v203
	v_and_b32_e32 v21, 0xffff0000, v203
	v_lshlrev_b32_e32 v22, 16, v204
	v_and_b32_e32 v23, 0xffff0000, v204
	v_lshlrev_b32_e32 v24, 16, v205
	v_and_b32_e32 v25, 0xffff0000, v205
	v_pk_fma_f32 v[10:11], v[2:3], v[18:19], v[10:11]
	v_pk_fma_f32 v[12:13], v[4:5], v[20:21], v[12:13]
	v_pk_fma_f32 v[14:15], v[6:7], v[22:23], v[14:15]
	v_pk_fma_f32 v[16:17], v[8:9], v[24:25], v[16:17]
	v_pk_mul_f32 v[10:11], v[10:11], s[14:15] op_sel_hi:[1,0]
	v_pk_mul_f32 v[12:13], v[12:13], s[14:15] op_sel_hi:[1,0]
	v_pk_mul_f32 v[14:15], v[14:15], s[14:15] op_sel_hi:[1,0]
	v_pk_mul_f32 v[16:17], v[16:17], s[14:15] op_sel_hi:[1,0]
	v_med3_f32 v10, v10, s49, v197
	v_med3_f32 v11, v11, s49, v197
	v_med3_f32 v12, v12, s49, v197
	v_med3_f32 v13, v13, s49, v197
	v_med3_f32 v14, v14, s49, v197
	v_med3_f32 v15, v15, s49, v197
	v_med3_f32 v16, v16, s49, v197
	v_med3_f32 v17, v17, s49, v197
	v_cvt_pk_fp8_f32 v30, v10, v11
	v_cvt_pk_fp8_f32 v31, v14, v15
	v_cvt_pk_fp8_f32 v30, v12, v13 op_sel:[0,0,1]
	v_cvt_pk_fp8_f32 v31, v16, v17 op_sel:[0,0,1]
	v_mov_b32_e32 v33, v255
	s_nop 0
	global_store_dwordx2 v33, v[30:31], s[6:7] offset:0
	v_add_u32_e32 v32, 0x60000, v254
	global_load_dwordx4 v[198:201], v32, s[20:21] offset:0
	global_load_dwordx4 v[202:205], v32, s[100:101] offset:0
	v_pk_mul_f32 v[4:5], v[152:153], s[12:13] op_sel_hi:[1,0]
	v_pk_mul_f32 v[2:3], v[150:151], s[12:13] op_sel_hi:[1,0]
	v_pk_mul_f32 v[8:9], v[148:149], s[12:13] op_sel_hi:[1,0]
	v_pk_mul_f32 v[6:7], v[146:147], s[12:13] op_sel_hi:[1,0]
	v_mov_b32_e32 v30, 0
	v_mov_b32_e32 v31, 0
	s_waitcnt vmcnt(11)
	v_lshlrev_b32_e32 v10, 16, v206
	v_and_b32_e32 v11, 0xffff0000, v206
	v_lshlrev_b32_e32 v12, 16, v207
	v_and_b32_e32 v13, 0xffff0000, v207
	v_lshlrev_b32_e32 v14, 16, v208
	v_and_b32_e32 v15, 0xffff0000, v208
	v_lshlrev_b32_e32 v16, 16, v209
	v_and_b32_e32 v17, 0xffff0000, v209
	v_lshlrev_b32_e32 v18, 16, v210
	v_and_b32_e32 v19, 0xffff0000, v210
	v_lshlrev_b32_e32 v20, 16, v211
	v_and_b32_e32 v21, 0xffff0000, v211
	v_lshlrev_b32_e32 v22, 16, v212
	v_and_b32_e32 v23, 0xffff0000, v212
	v_lshlrev_b32_e32 v24, 16, v213
	v_and_b32_e32 v25, 0xffff0000, v213
	v_pk_fma_f32 v[10:11], v[2:3], v[18:19], v[10:11]
	v_pk_fma_f32 v[12:13], v[4:5], v[20:21], v[12:13]
	v_pk_fma_f32 v[14:15], v[6:7], v[22:23], v[14:15]
	v_pk_fma_f32 v[16:17], v[8:9], v[24:25], v[16:17]
	v_pk_mul_f32 v[10:11], v[10:11], s[14:15] op_sel_hi:[1,0]
	v_pk_mul_f32 v[12:13], v[12:13], s[14:15] op_sel_hi:[1,0]
	v_pk_mul_f32 v[14:15], v[14:15], s[14:15] op_sel_hi:[1,0]
	v_pk_mul_f32 v[16:17], v[16:17], s[14:15] op_sel_hi:[1,0]
	v_med3_f32 v10, v10, s49, v197
	v_med3_f32 v11, v11, s49, v197
	v_med3_f32 v12, v12, s49, v197
	v_med3_f32 v13, v13, s49, v197
	v_med3_f32 v14, v14, s49, v197
	v_med3_f32 v15, v15, s49, v197
	v_med3_f32 v16, v16, s49, v197
	v_med3_f32 v17, v17, s49, v197
	v_cvt_pk_fp8_f32 v30, v10, v11
	v_cvt_pk_fp8_f32 v31, v14, v15
	v_cvt_pk_fp8_f32 v30, v12, v13 op_sel:[0,0,1]
	v_cvt_pk_fp8_f32 v31, v16, v17 op_sel:[0,0,1]
	s_nop 0
	global_store_dwordx2 v33, v[30:31], s[6:7] offset:128
	global_load_dwordx4 v[206:209], v32, s[20:21] offset:256
	global_load_dwordx4 v[210:213], v32, s[100:101] offset:256
	v_pk_mul_f32 v[4:5], v[144:145], s[12:13] op_sel_hi:[1,0]
	v_pk_mul_f32 v[2:3], v[142:143], s[12:13] op_sel_hi:[1,0]
	v_pk_mul_f32 v[8:9], v[140:141], s[12:13] op_sel_hi:[1,0]
	v_pk_mul_f32 v[6:7], v[138:139], s[12:13] op_sel_hi:[1,0]
	v_mov_b32_e32 v30, 0
	v_mov_b32_e32 v31, 0
	s_waitcnt vmcnt(12)
	v_lshlrev_b32_e32 v10, 16, v214
	v_and_b32_e32 v11, 0xffff0000, v214
	v_lshlrev_b32_e32 v12, 16, v215
	v_and_b32_e32 v13, 0xffff0000, v215
	v_lshlrev_b32_e32 v14, 16, v216
	v_and_b32_e32 v15, 0xffff0000, v216
	v_lshlrev_b32_e32 v16, 16, v217
	v_and_b32_e32 v17, 0xffff0000, v217
	v_lshlrev_b32_e32 v18, 16, v218
	v_and_b32_e32 v19, 0xffff0000, v218
	v_lshlrev_b32_e32 v20, 16, v219
	v_and_b32_e32 v21, 0xffff0000, v219
	v_lshlrev_b32_e32 v22, 16, v220
	v_and_b32_e32 v23, 0xffff0000, v220
	v_lshlrev_b32_e32 v24, 16, v221
	v_and_b32_e32 v25, 0xffff0000, v221
	v_pk_fma_f32 v[10:11], v[2:3], v[18:19], v[10:11]
	v_pk_fma_f32 v[12:13], v[4:5], v[20:21], v[12:13]
	v_pk_fma_f32 v[14:15], v[6:7], v[22:23], v[14:15]
	v_pk_fma_f32 v[16:17], v[8:9], v[24:25], v[16:17]
	v_pk_mul_f32 v[10:11], v[10:11], s[14:15] op_sel_hi:[1,0]
	v_pk_mul_f32 v[12:13], v[12:13], s[14:15] op_sel_hi:[1,0]
	v_pk_mul_f32 v[14:15], v[14:15], s[14:15] op_sel_hi:[1,0]
	v_pk_mul_f32 v[16:17], v[16:17], s[14:15] op_sel_hi:[1,0]
	v_med3_f32 v10, v10, s49, v197
	v_med3_f32 v11, v11, s49, v197
	v_med3_f32 v12, v12, s49, v197
	v_med3_f32 v13, v13, s49, v197
	v_med3_f32 v14, v14, s49, v197
	v_med3_f32 v15, v15, s49, v197
	v_med3_f32 v16, v16, s49, v197
	v_med3_f32 v17, v17, s49, v197
	v_cvt_pk_fp8_f32 v30, v10, v11
	v_cvt_pk_fp8_f32 v31, v14, v15
	v_cvt_pk_fp8_f32 v30, v12, v13 op_sel:[0,0,1]
	v_cvt_pk_fp8_f32 v31, v16, v17 op_sel:[0,0,1]
	v_add_u32_e32 v33, 0x8000, v255
	s_nop 0
	global_store_dwordx2 v33, v[30:31], s[6:7] offset:0
	v_add_u32_e32 v32, 0x100000, v254
	global_load_dwordx4 v[214:217], v32, s[20:21] offset:0
	global_load_dwordx4 v[218:221], v32, s[100:101] offset:0
	v_pk_mul_f32 v[4:5], v[136:137], s[12:13] op_sel_hi:[1,0]
	v_pk_mul_f32 v[2:3], v[134:135], s[12:13] op_sel_hi:[1,0]
	v_pk_mul_f32 v[8:9], v[132:133], s[12:13] op_sel_hi:[1,0]
	v_pk_mul_f32 v[6:7], v[130:131], s[12:13] op_sel_hi:[1,0]
	v_mov_b32_e32 v30, 0
	v_mov_b32_e32 v31, 0
	s_waitcnt vmcnt(13)
	v_lshlrev_b32_e32 v10, 16, v222
	v_and_b32_e32 v11, 0xffff0000, v222
	v_lshlrev_b32_e32 v12, 16, v223
	v_and_b32_e32 v13, 0xffff0000, v223
	v_lshlrev_b32_e32 v14, 16, v224
	v_and_b32_e32 v15, 0xffff0000, v224
	v_lshlrev_b32_e32 v16, 16, v225
	v_and_b32_e32 v17, 0xffff0000, v225
	v_lshlrev_b32_e32 v18, 16, v226
	v_and_b32_e32 v19, 0xffff0000, v226
	v_lshlrev_b32_e32 v20, 16, v227
	v_and_b32_e32 v21, 0xffff0000, v227
	v_lshlrev_b32_e32 v22, 16, v228
	v_and_b32_e32 v23, 0xffff0000, v228
	v_lshlrev_b32_e32 v24, 16, v229
	v_and_b32_e32 v25, 0xffff0000, v229
	v_pk_fma_f32 v[10:11], v[2:3], v[18:19], v[10:11]
	v_pk_fma_f32 v[12:13], v[4:5], v[20:21], v[12:13]
	v_pk_fma_f32 v[14:15], v[6:7], v[22:23], v[14:15]
	v_pk_fma_f32 v[16:17], v[8:9], v[24:25], v[16:17]
	v_pk_mul_f32 v[10:11], v[10:11], s[14:15] op_sel_hi:[1,0]
	v_pk_mul_f32 v[12:13], v[12:13], s[14:15] op_sel_hi:[1,0]
	v_pk_mul_f32 v[14:15], v[14:15], s[14:15] op_sel_hi:[1,0]
	v_pk_mul_f32 v[16:17], v[16:17], s[14:15] op_sel_hi:[1,0]
	v_med3_f32 v10, v10, s49, v197
	v_med3_f32 v11, v11, s49, v197
	v_med3_f32 v12, v12, s49, v197
	v_med3_f32 v13, v13, s49, v197
	v_med3_f32 v14, v14, s49, v197
	v_med3_f32 v15, v15, s49, v197
	v_med3_f32 v16, v16, s49, v197
	v_med3_f32 v17, v17, s49, v197
	v_cvt_pk_fp8_f32 v30, v10, v11
	v_cvt_pk_fp8_f32 v31, v14, v15
	v_cvt_pk_fp8_f32 v30, v12, v13 op_sel:[0,0,1]
	v_cvt_pk_fp8_f32 v31, v16, v17 op_sel:[0,0,1]
	s_nop 0
	global_store_dwordx2 v33, v[30:31], s[6:7] offset:128
	global_load_dwordx4 v[222:225], v32, s[20:21] offset:256
	global_load_dwordx4 v[226:229], v32, s[100:101] offset:256
	v_pk_mul_f32 v[4:5], v[128:129], s[12:13] op_sel_hi:[1,0]
	v_pk_mul_f32 v[2:3], v[126:127], s[12:13] op_sel_hi:[1,0]
	v_pk_mul_f32 v[8:9], v[124:125], s[12:13] op_sel_hi:[1,0]
	v_pk_mul_f32 v[6:7], v[122:123], s[12:13] op_sel_hi:[1,0]
	v_mov_b32_e32 v30, 0
	v_mov_b32_e32 v31, 0
	s_waitcnt vmcnt(14)
	v_lshlrev_b32_e32 v10, 16, v178
	v_and_b32_e32 v11, 0xffff0000, v178
	v_lshlrev_b32_e32 v12, 16, v179
	v_and_b32_e32 v13, 0xffff0000, v179
	v_lshlrev_b32_e32 v14, 16, v180
	v_and_b32_e32 v15, 0xffff0000, v180
	v_lshlrev_b32_e32 v16, 16, v181
	v_and_b32_e32 v17, 0xffff0000, v181
	v_lshlrev_b32_e32 v18, 16, v182
	v_and_b32_e32 v19, 0xffff0000, v182
	v_lshlrev_b32_e32 v20, 16, v183
	v_and_b32_e32 v21, 0xffff0000, v183
	v_lshlrev_b32_e32 v22, 16, v184
	v_and_b32_e32 v23, 0xffff0000, v184
	v_lshlrev_b32_e32 v24, 16, v185
	v_and_b32_e32 v25, 0xffff0000, v185
	v_pk_fma_f32 v[10:11], v[2:3], v[18:19], v[10:11]
	v_pk_fma_f32 v[12:13], v[4:5], v[20:21], v[12:13]
	v_pk_fma_f32 v[14:15], v[6:7], v[22:23], v[14:15]
	v_pk_fma_f32 v[16:17], v[8:9], v[24:25], v[16:17]
	v_pk_mul_f32 v[10:11], v[10:11], s[14:15] op_sel_hi:[1,0]
	v_pk_mul_f32 v[12:13], v[12:13], s[14:15] op_sel_hi:[1,0]
	v_pk_mul_f32 v[14:15], v[14:15], s[14:15] op_sel_hi:[1,0]
	v_pk_mul_f32 v[16:17], v[16:17], s[14:15] op_sel_hi:[1,0]
	v_med3_f32 v10, v10, s49, v197
	v_med3_f32 v11, v11, s49, v197
	v_med3_f32 v12, v12, s49, v197
	v_med3_f32 v13, v13, s49, v197
	v_med3_f32 v14, v14, s49, v197
	v_med3_f32 v15, v15, s49, v197
	v_med3_f32 v16, v16, s49, v197
	v_med3_f32 v17, v17, s49, v197
	v_cvt_pk_fp8_f32 v30, v10, v11
	v_cvt_pk_fp8_f32 v31, v14, v15
	v_cvt_pk_fp8_f32 v30, v12, v13 op_sel:[0,0,1]
	v_cvt_pk_fp8_f32 v31, v16, v17 op_sel:[0,0,1]
	v_add_u32_e32 v33, 0x10000, v255
	s_nop 0
	global_store_dwordx2 v33, v[30:31], s[6:7] offset:0
	v_add_u32_e32 v32, 0x120000, v254
	global_load_dwordx4 v[178:181], v32, s[20:21] offset:0
	global_load_dwordx4 v[182:185], v32, s[100:101] offset:0
	v_pk_mul_f32 v[4:5], v[120:121], s[12:13] op_sel_hi:[1,0]
	v_pk_mul_f32 v[2:3], v[118:119], s[12:13] op_sel_hi:[1,0]
	v_pk_mul_f32 v[8:9], v[116:117], s[12:13] op_sel_hi:[1,0]
	v_pk_mul_f32 v[6:7], v[114:115], s[12:13] op_sel_hi:[1,0]
	v_mov_b32_e32 v30, 0
	v_mov_b32_e32 v31, 0
	s_waitcnt vmcnt(15)
	v_lshlrev_b32_e32 v10, 16, v244
	v_and_b32_e32 v11, 0xffff0000, v244
	v_lshlrev_b32_e32 v12, 16, v245
	v_and_b32_e32 v13, 0xffff0000, v245
	v_lshlrev_b32_e32 v14, 16, v246
	v_and_b32_e32 v15, 0xffff0000, v246
	v_lshlrev_b32_e32 v16, 16, v247
	v_and_b32_e32 v17, 0xffff0000, v247
	v_lshlrev_b32_e32 v18, 16, v248
	v_and_b32_e32 v19, 0xffff0000, v248
	v_lshlrev_b32_e32 v20, 16, v249
	v_and_b32_e32 v21, 0xffff0000, v249
	v_lshlrev_b32_e32 v22, 16, v250
	v_and_b32_e32 v23, 0xffff0000, v250
	v_lshlrev_b32_e32 v24, 16, v251
	v_and_b32_e32 v25, 0xffff0000, v251
	v_pk_fma_f32 v[10:11], v[2:3], v[18:19], v[10:11]
	v_pk_fma_f32 v[12:13], v[4:5], v[20:21], v[12:13]
	v_pk_fma_f32 v[14:15], v[6:7], v[22:23], v[14:15]
	v_pk_fma_f32 v[16:17], v[8:9], v[24:25], v[16:17]
	v_pk_mul_f32 v[10:11], v[10:11], s[14:15] op_sel_hi:[1,0]
	v_pk_mul_f32 v[12:13], v[12:13], s[14:15] op_sel_hi:[1,0]
	v_pk_mul_f32 v[14:15], v[14:15], s[14:15] op_sel_hi:[1,0]
	v_pk_mul_f32 v[16:17], v[16:17], s[14:15] op_sel_hi:[1,0]
	v_med3_f32 v10, v10, s49, v197
	v_med3_f32 v11, v11, s49, v197
	v_med3_f32 v12, v12, s49, v197
	v_med3_f32 v13, v13, s49, v197
	v_med3_f32 v14, v14, s49, v197
	v_med3_f32 v15, v15, s49, v197
	v_med3_f32 v16, v16, s49, v197
	v_med3_f32 v17, v17, s49, v197
	v_cvt_pk_fp8_f32 v30, v10, v11
	v_cvt_pk_fp8_f32 v31, v14, v15
	v_cvt_pk_fp8_f32 v30, v12, v13 op_sel:[0,0,1]
	v_cvt_pk_fp8_f32 v31, v16, v17 op_sel:[0,0,1]
	s_nop 0
	global_store_dwordx2 v33, v[30:31], s[6:7] offset:128
	global_load_dwordx4 v[244:247], v32, s[20:21] offset:256
	global_load_dwordx4 v[248:251], v32, s[100:101] offset:256
	v_pk_mul_f32 v[4:5], v[112:113], s[12:13] op_sel_hi:[1,0]
	v_pk_mul_f32 v[2:3], v[110:111], s[12:13] op_sel_hi:[1,0]
	v_pk_mul_f32 v[8:9], v[108:109], s[12:13] op_sel_hi:[1,0]
	v_pk_mul_f32 v[6:7], v[106:107], s[12:13] op_sel_hi:[1,0]
	v_mov_b32_e32 v30, 0
	v_mov_b32_e32 v31, 0
	s_waitcnt vmcnt(15)
	v_lshlrev_b32_e32 v10, 16, v198
	v_and_b32_e32 v11, 0xffff0000, v198
	v_lshlrev_b32_e32 v12, 16, v199
	v_and_b32_e32 v13, 0xffff0000, v199
	v_lshlrev_b32_e32 v14, 16, v200
	v_and_b32_e32 v15, 0xffff0000, v200
	v_lshlrev_b32_e32 v16, 16, v201
	v_and_b32_e32 v17, 0xffff0000, v201
	v_lshlrev_b32_e32 v18, 16, v202
	v_and_b32_e32 v19, 0xffff0000, v202
	v_lshlrev_b32_e32 v20, 16, v203
	v_and_b32_e32 v21, 0xffff0000, v203
	v_lshlrev_b32_e32 v22, 16, v204
	v_and_b32_e32 v23, 0xffff0000, v204
	v_lshlrev_b32_e32 v24, 16, v205
	v_and_b32_e32 v25, 0xffff0000, v205
	v_pk_fma_f32 v[10:11], v[2:3], v[18:19], v[10:11]
	v_pk_fma_f32 v[12:13], v[4:5], v[20:21], v[12:13]
	v_pk_fma_f32 v[14:15], v[6:7], v[22:23], v[14:15]
	v_pk_fma_f32 v[16:17], v[8:9], v[24:25], v[16:17]
	v_pk_mul_f32 v[10:11], v[10:11], s[14:15] op_sel_hi:[1,0]
	v_pk_mul_f32 v[12:13], v[12:13], s[14:15] op_sel_hi:[1,0]
	v_pk_mul_f32 v[14:15], v[14:15], s[14:15] op_sel_hi:[1,0]
	v_pk_mul_f32 v[16:17], v[16:17], s[14:15] op_sel_hi:[1,0]
	v_med3_f32 v10, v10, s49, v197
	v_med3_f32 v11, v11, s49, v197
	v_med3_f32 v12, v12, s49, v197
	v_med3_f32 v13, v13, s49, v197
	v_med3_f32 v14, v14, s49, v197
	v_med3_f32 v15, v15, s49, v197
	v_med3_f32 v16, v16, s49, v197
	v_med3_f32 v17, v17, s49, v197
	v_cvt_pk_fp8_f32 v30, v10, v11
	v_cvt_pk_fp8_f32 v31, v14, v15
	v_cvt_pk_fp8_f32 v30, v12, v13 op_sel:[0,0,1]
	v_cvt_pk_fp8_f32 v31, v16, v17 op_sel:[0,0,1]
	v_add_u32_e32 v33, 0x18000, v255
	s_nop 0
	global_store_dwordx2 v33, v[30:31], s[6:7] offset:0
	v_add_u32_e32 v32, 0x140000, v254
	global_load_dwordx4 v[198:201], v32, s[20:21] offset:0
	global_load_dwordx4 v[202:205], v32, s[100:101] offset:0
	v_pk_mul_f32 v[4:5], v[104:105], s[12:13] op_sel_hi:[1,0]
	v_pk_mul_f32 v[2:3], v[102:103], s[12:13] op_sel_hi:[1,0]
	v_pk_mul_f32 v[8:9], v[100:101], s[12:13] op_sel_hi:[1,0]
	v_pk_mul_f32 v[6:7], v[98:99], s[12:13] op_sel_hi:[1,0]
	v_mov_b32_e32 v30, 0
	v_mov_b32_e32 v31, 0
	s_waitcnt vmcnt(15)
	v_lshlrev_b32_e32 v10, 16, v206
	v_and_b32_e32 v11, 0xffff0000, v206
	v_lshlrev_b32_e32 v12, 16, v207
	v_and_b32_e32 v13, 0xffff0000, v207
	v_lshlrev_b32_e32 v14, 16, v208
	v_and_b32_e32 v15, 0xffff0000, v208
	v_lshlrev_b32_e32 v16, 16, v209
	v_and_b32_e32 v17, 0xffff0000, v209
	v_lshlrev_b32_e32 v18, 16, v210
	v_and_b32_e32 v19, 0xffff0000, v210
	v_lshlrev_b32_e32 v20, 16, v211
	v_and_b32_e32 v21, 0xffff0000, v211
	v_lshlrev_b32_e32 v22, 16, v212
	v_and_b32_e32 v23, 0xffff0000, v212
	v_lshlrev_b32_e32 v24, 16, v213
	v_and_b32_e32 v25, 0xffff0000, v213
	v_pk_fma_f32 v[10:11], v[2:3], v[18:19], v[10:11]
	v_pk_fma_f32 v[12:13], v[4:5], v[20:21], v[12:13]
	v_pk_fma_f32 v[14:15], v[6:7], v[22:23], v[14:15]
	v_pk_fma_f32 v[16:17], v[8:9], v[24:25], v[16:17]
	v_pk_mul_f32 v[10:11], v[10:11], s[14:15] op_sel_hi:[1,0]
	v_pk_mul_f32 v[12:13], v[12:13], s[14:15] op_sel_hi:[1,0]
	v_pk_mul_f32 v[14:15], v[14:15], s[14:15] op_sel_hi:[1,0]
	v_pk_mul_f32 v[16:17], v[16:17], s[14:15] op_sel_hi:[1,0]
	v_med3_f32 v10, v10, s49, v197
	v_med3_f32 v11, v11, s49, v197
	v_med3_f32 v12, v12, s49, v197
	v_med3_f32 v13, v13, s49, v197
	v_med3_f32 v14, v14, s49, v197
	v_med3_f32 v15, v15, s49, v197
	v_med3_f32 v16, v16, s49, v197
	v_med3_f32 v17, v17, s49, v197
	v_cvt_pk_fp8_f32 v30, v10, v11
	v_cvt_pk_fp8_f32 v31, v14, v15
	v_cvt_pk_fp8_f32 v30, v12, v13 op_sel:[0,0,1]
	v_cvt_pk_fp8_f32 v31, v16, v17 op_sel:[0,0,1]
	s_nop 0
	global_store_dwordx2 v33, v[30:31], s[6:7] offset:128
	global_load_dwordx4 v[206:209], v32, s[20:21] offset:256
	global_load_dwordx4 v[210:213], v32, s[100:101] offset:256
	v_pk_mul_f32 v[4:5], v[96:97], s[12:13] op_sel_hi:[1,0]
	v_pk_mul_f32 v[2:3], v[94:95], s[12:13] op_sel_hi:[1,0]
	v_pk_mul_f32 v[8:9], v[92:93], s[12:13] op_sel_hi:[1,0]
	v_pk_mul_f32 v[6:7], v[90:91], s[12:13] op_sel_hi:[1,0]
	v_mov_b32_e32 v30, 0
	v_mov_b32_e32 v31, 0
	s_waitcnt vmcnt(15)
	v_lshlrev_b32_e32 v10, 16, v214
	v_and_b32_e32 v11, 0xffff0000, v214
	v_lshlrev_b32_e32 v12, 16, v215
	v_and_b32_e32 v13, 0xffff0000, v215
	v_lshlrev_b32_e32 v14, 16, v216
	v_and_b32_e32 v15, 0xffff0000, v216
	v_lshlrev_b32_e32 v16, 16, v217
	v_and_b32_e32 v17, 0xffff0000, v217
	v_lshlrev_b32_e32 v18, 16, v218
	v_and_b32_e32 v19, 0xffff0000, v218
	v_lshlrev_b32_e32 v20, 16, v219
	v_and_b32_e32 v21, 0xffff0000, v219
	v_lshlrev_b32_e32 v22, 16, v220
	v_and_b32_e32 v23, 0xffff0000, v220
	v_lshlrev_b32_e32 v24, 16, v221
	v_and_b32_e32 v25, 0xffff0000, v221
	v_pk_fma_f32 v[10:11], v[2:3], v[18:19], v[10:11]
	v_pk_fma_f32 v[12:13], v[4:5], v[20:21], v[12:13]
	v_pk_fma_f32 v[14:15], v[6:7], v[22:23], v[14:15]
	v_pk_fma_f32 v[16:17], v[8:9], v[24:25], v[16:17]
	v_pk_mul_f32 v[10:11], v[10:11], s[14:15] op_sel_hi:[1,0]
	v_pk_mul_f32 v[12:13], v[12:13], s[14:15] op_sel_hi:[1,0]
	v_pk_mul_f32 v[14:15], v[14:15], s[14:15] op_sel_hi:[1,0]
	v_pk_mul_f32 v[16:17], v[16:17], s[14:15] op_sel_hi:[1,0]
	v_med3_f32 v10, v10, s49, v197
	v_med3_f32 v11, v11, s49, v197
	v_med3_f32 v12, v12, s49, v197
	v_med3_f32 v13, v13, s49, v197
	v_med3_f32 v14, v14, s49, v197
	v_med3_f32 v15, v15, s49, v197
	v_med3_f32 v16, v16, s49, v197
	v_med3_f32 v17, v17, s49, v197
	v_cvt_pk_fp8_f32 v30, v10, v11
	v_cvt_pk_fp8_f32 v31, v14, v15
	v_cvt_pk_fp8_f32 v30, v12, v13 op_sel:[0,0,1]
	v_cvt_pk_fp8_f32 v31, v16, v17 op_sel:[0,0,1]
	v_add_u32_e32 v33, 0x40000, v255
	s_nop 0
	global_store_dwordx2 v33, v[30:31], s[6:7] offset:0
	v_add_u32_e32 v32, 0x160000, v254
	global_load_dwordx4 v[214:217], v32, s[20:21] offset:0
	global_load_dwordx4 v[218:221], v32, s[100:101] offset:0
	v_pk_mul_f32 v[4:5], v[88:89], s[12:13] op_sel_hi:[1,0]
	v_pk_mul_f32 v[2:3], v[86:87], s[12:13] op_sel_hi:[1,0]
	v_pk_mul_f32 v[8:9], v[84:85], s[12:13] op_sel_hi:[1,0]
	v_pk_mul_f32 v[6:7], v[82:83], s[12:13] op_sel_hi:[1,0]
	v_mov_b32_e32 v30, 0
	v_mov_b32_e32 v31, 0
	s_waitcnt vmcnt(15)
	v_lshlrev_b32_e32 v10, 16, v222
	v_and_b32_e32 v11, 0xffff0000, v222
	v_lshlrev_b32_e32 v12, 16, v223
	v_and_b32_e32 v13, 0xffff0000, v223
	v_lshlrev_b32_e32 v14, 16, v224
	v_and_b32_e32 v15, 0xffff0000, v224
	v_lshlrev_b32_e32 v16, 16, v225
	v_and_b32_e32 v17, 0xffff0000, v225
	v_lshlrev_b32_e32 v18, 16, v226
	v_and_b32_e32 v19, 0xffff0000, v226
	v_lshlrev_b32_e32 v20, 16, v227
	v_and_b32_e32 v21, 0xffff0000, v227
	v_lshlrev_b32_e32 v22, 16, v228
	v_and_b32_e32 v23, 0xffff0000, v228
	v_lshlrev_b32_e32 v24, 16, v229
	v_and_b32_e32 v25, 0xffff0000, v229
	v_pk_fma_f32 v[10:11], v[2:3], v[18:19], v[10:11]
	v_pk_fma_f32 v[12:13], v[4:5], v[20:21], v[12:13]
	v_pk_fma_f32 v[14:15], v[6:7], v[22:23], v[14:15]
	v_pk_fma_f32 v[16:17], v[8:9], v[24:25], v[16:17]
	v_pk_mul_f32 v[10:11], v[10:11], s[14:15] op_sel_hi:[1,0]
	v_pk_mul_f32 v[12:13], v[12:13], s[14:15] op_sel_hi:[1,0]
	v_pk_mul_f32 v[14:15], v[14:15], s[14:15] op_sel_hi:[1,0]
	v_pk_mul_f32 v[16:17], v[16:17], s[14:15] op_sel_hi:[1,0]
	v_med3_f32 v10, v10, s49, v197
	v_med3_f32 v11, v11, s49, v197
	v_med3_f32 v12, v12, s49, v197
	v_med3_f32 v13, v13, s49, v197
	v_med3_f32 v14, v14, s49, v197
	v_med3_f32 v15, v15, s49, v197
	v_med3_f32 v16, v16, s49, v197
	v_med3_f32 v17, v17, s49, v197
	v_cvt_pk_fp8_f32 v30, v10, v11
	v_cvt_pk_fp8_f32 v31, v14, v15
	v_cvt_pk_fp8_f32 v30, v12, v13 op_sel:[0,0,1]
	v_cvt_pk_fp8_f32 v31, v16, v17 op_sel:[0,0,1]
	s_nop 0
	global_store_dwordx2 v33, v[30:31], s[6:7] offset:128
	global_load_dwordx4 v[222:225], v32, s[20:21] offset:256
	global_load_dwordx4 v[226:229], v32, s[100:101] offset:256
	v_pk_mul_f32 v[4:5], v[80:81], s[12:13] op_sel_hi:[1,0]
	v_pk_mul_f32 v[2:3], v[78:79], s[12:13] op_sel_hi:[1,0]
	v_pk_mul_f32 v[8:9], v[76:77], s[12:13] op_sel_hi:[1,0]
	v_pk_mul_f32 v[6:7], v[74:75], s[12:13] op_sel_hi:[1,0]
	v_mov_b32_e32 v30, 0
	v_mov_b32_e32 v31, 0
	s_waitcnt vmcnt(15)
	v_lshlrev_b32_e32 v10, 16, v178
	v_and_b32_e32 v11, 0xffff0000, v178
	v_lshlrev_b32_e32 v12, 16, v179
	v_and_b32_e32 v13, 0xffff0000, v179
	v_lshlrev_b32_e32 v14, 16, v180
	v_and_b32_e32 v15, 0xffff0000, v180
	v_lshlrev_b32_e32 v16, 16, v181
	v_and_b32_e32 v17, 0xffff0000, v181
	v_lshlrev_b32_e32 v18, 16, v182
	v_and_b32_e32 v19, 0xffff0000, v182
	v_lshlrev_b32_e32 v20, 16, v183
	v_and_b32_e32 v21, 0xffff0000, v183
	v_lshlrev_b32_e32 v22, 16, v184
	v_and_b32_e32 v23, 0xffff0000, v184
	v_lshlrev_b32_e32 v24, 16, v185
	v_and_b32_e32 v25, 0xffff0000, v185
	v_pk_fma_f32 v[10:11], v[2:3], v[18:19], v[10:11]
	v_pk_fma_f32 v[12:13], v[4:5], v[20:21], v[12:13]
	v_pk_fma_f32 v[14:15], v[6:7], v[22:23], v[14:15]
	v_pk_fma_f32 v[16:17], v[8:9], v[24:25], v[16:17]
	v_pk_mul_f32 v[10:11], v[10:11], s[14:15] op_sel_hi:[1,0]
	v_pk_mul_f32 v[12:13], v[12:13], s[14:15] op_sel_hi:[1,0]
	v_pk_mul_f32 v[14:15], v[14:15], s[14:15] op_sel_hi:[1,0]
	v_pk_mul_f32 v[16:17], v[16:17], s[14:15] op_sel_hi:[1,0]
	v_med3_f32 v10, v10, s49, v197
	v_med3_f32 v11, v11, s49, v197
	v_med3_f32 v12, v12, s49, v197
	v_med3_f32 v13, v13, s49, v197
	v_med3_f32 v14, v14, s49, v197
	v_med3_f32 v15, v15, s49, v197
	v_med3_f32 v16, v16, s49, v197
	v_med3_f32 v17, v17, s49, v197
	v_cvt_pk_fp8_f32 v30, v10, v11
	v_cvt_pk_fp8_f32 v31, v14, v15
	v_cvt_pk_fp8_f32 v30, v12, v13 op_sel:[0,0,1]
	v_cvt_pk_fp8_f32 v31, v16, v17 op_sel:[0,0,1]
	v_add_u32_e32 v33, 0x48000, v255
	s_nop 0
	global_store_dwordx2 v33, v[30:31], s[6:7] offset:0
	v_pk_mul_f32 v[4:5], v[72:73], s[12:13] op_sel_hi:[1,0]
	v_pk_mul_f32 v[2:3], v[70:71], s[12:13] op_sel_hi:[1,0]
	v_pk_mul_f32 v[8:9], v[68:69], s[12:13] op_sel_hi:[1,0]
	v_pk_mul_f32 v[6:7], v[66:67], s[12:13] op_sel_hi:[1,0]
	v_mov_b32_e32 v30, 0
	v_mov_b32_e32 v31, 0
	s_waitcnt vmcnt(13)
	v_lshlrev_b32_e32 v10, 16, v244
	v_and_b32_e32 v11, 0xffff0000, v244
	v_lshlrev_b32_e32 v12, 16, v245
	v_and_b32_e32 v13, 0xffff0000, v245
	v_lshlrev_b32_e32 v14, 16, v246
	v_and_b32_e32 v15, 0xffff0000, v246
	v_lshlrev_b32_e32 v16, 16, v247
	v_and_b32_e32 v17, 0xffff0000, v247
	v_lshlrev_b32_e32 v18, 16, v248
	v_and_b32_e32 v19, 0xffff0000, v248
	v_lshlrev_b32_e32 v20, 16, v249
	v_and_b32_e32 v21, 0xffff0000, v249
	v_lshlrev_b32_e32 v22, 16, v250
	v_and_b32_e32 v23, 0xffff0000, v250
	v_lshlrev_b32_e32 v24, 16, v251
	v_and_b32_e32 v25, 0xffff0000, v251
	v_pk_fma_f32 v[10:11], v[2:3], v[18:19], v[10:11]
	v_pk_fma_f32 v[12:13], v[4:5], v[20:21], v[12:13]
	v_pk_fma_f32 v[14:15], v[6:7], v[22:23], v[14:15]
	v_pk_fma_f32 v[16:17], v[8:9], v[24:25], v[16:17]
	v_pk_mul_f32 v[10:11], v[10:11], s[14:15] op_sel_hi:[1,0]
	v_pk_mul_f32 v[12:13], v[12:13], s[14:15] op_sel_hi:[1,0]
	v_pk_mul_f32 v[14:15], v[14:15], s[14:15] op_sel_hi:[1,0]
	v_pk_mul_f32 v[16:17], v[16:17], s[14:15] op_sel_hi:[1,0]
	v_med3_f32 v10, v10, s49, v197
	v_med3_f32 v11, v11, s49, v197
	v_med3_f32 v12, v12, s49, v197
	v_med3_f32 v13, v13, s49, v197
	v_med3_f32 v14, v14, s49, v197
	v_med3_f32 v15, v15, s49, v197
	v_med3_f32 v16, v16, s49, v197
	v_med3_f32 v17, v17, s49, v197
	v_cvt_pk_fp8_f32 v30, v10, v11
	v_cvt_pk_fp8_f32 v31, v14, v15
	v_cvt_pk_fp8_f32 v30, v12, v13 op_sel:[0,0,1]
	v_cvt_pk_fp8_f32 v31, v16, v17 op_sel:[0,0,1]
	s_nop 0
	global_store_dwordx2 v33, v[30:31], s[6:7] offset:128
	v_pk_mul_f32 v[4:5], v[64:65], s[12:13] op_sel_hi:[1,0]
	v_pk_mul_f32 v[2:3], v[62:63], s[12:13] op_sel_hi:[1,0]
	v_pk_mul_f32 v[8:9], v[60:61], s[12:13] op_sel_hi:[1,0]
	v_pk_mul_f32 v[6:7], v[58:59], s[12:13] op_sel_hi:[1,0]
	v_mov_b32_e32 v30, 0
	v_mov_b32_e32 v31, 0
	s_waitcnt vmcnt(11)
	v_lshlrev_b32_e32 v10, 16, v198
	v_and_b32_e32 v11, 0xffff0000, v198
	v_lshlrev_b32_e32 v12, 16, v199
	v_and_b32_e32 v13, 0xffff0000, v199
	v_lshlrev_b32_e32 v14, 16, v200
	v_and_b32_e32 v15, 0xffff0000, v200
	v_lshlrev_b32_e32 v16, 16, v201
	v_and_b32_e32 v17, 0xffff0000, v201
	v_lshlrev_b32_e32 v18, 16, v202
	v_and_b32_e32 v19, 0xffff0000, v202
	v_lshlrev_b32_e32 v20, 16, v203
	v_and_b32_e32 v21, 0xffff0000, v203
	v_lshlrev_b32_e32 v22, 16, v204
	v_and_b32_e32 v23, 0xffff0000, v204
	v_lshlrev_b32_e32 v24, 16, v205
	v_and_b32_e32 v25, 0xffff0000, v205
	v_pk_fma_f32 v[10:11], v[2:3], v[18:19], v[10:11]
	v_pk_fma_f32 v[12:13], v[4:5], v[20:21], v[12:13]
	v_pk_fma_f32 v[14:15], v[6:7], v[22:23], v[14:15]
	v_pk_fma_f32 v[16:17], v[8:9], v[24:25], v[16:17]
	v_pk_mul_f32 v[10:11], v[10:11], s[14:15] op_sel_hi:[1,0]
	v_pk_mul_f32 v[12:13], v[12:13], s[14:15] op_sel_hi:[1,0]
	v_pk_mul_f32 v[14:15], v[14:15], s[14:15] op_sel_hi:[1,0]
	v_pk_mul_f32 v[16:17], v[16:17], s[14:15] op_sel_hi:[1,0]
	v_med3_f32 v10, v10, s49, v197
	v_med3_f32 v11, v11, s49, v197
	v_med3_f32 v12, v12, s49, v197
	v_med3_f32 v13, v13, s49, v197
	v_med3_f32 v14, v14, s49, v197
	v_med3_f32 v15, v15, s49, v197
	v_med3_f32 v16, v16, s49, v197
	v_med3_f32 v17, v17, s49, v197
	v_cvt_pk_fp8_f32 v30, v10, v11
	v_cvt_pk_fp8_f32 v31, v14, v15
	v_cvt_pk_fp8_f32 v30, v12, v13 op_sel:[0,0,1]
	v_cvt_pk_fp8_f32 v31, v16, v17 op_sel:[0,0,1]
	v_add_u32_e32 v33, 0x50000, v255
	s_nop 0
	global_store_dwordx2 v33, v[30:31], s[6:7] offset:0
	v_pk_mul_f32 v[4:5], v[56:57], s[12:13] op_sel_hi:[1,0]
	v_pk_mul_f32 v[2:3], v[54:55], s[12:13] op_sel_hi:[1,0]
	v_pk_mul_f32 v[8:9], v[52:53], s[12:13] op_sel_hi:[1,0]
	v_pk_mul_f32 v[6:7], v[50:51], s[12:13] op_sel_hi:[1,0]
	v_mov_b32_e32 v30, 0
	v_mov_b32_e32 v31, 0
	s_waitcnt vmcnt(9)
	v_lshlrev_b32_e32 v10, 16, v206
	v_and_b32_e32 v11, 0xffff0000, v206
	v_lshlrev_b32_e32 v12, 16, v207
	v_and_b32_e32 v13, 0xffff0000, v207
	v_lshlrev_b32_e32 v14, 16, v208
	v_and_b32_e32 v15, 0xffff0000, v208
	v_lshlrev_b32_e32 v16, 16, v209
	v_and_b32_e32 v17, 0xffff0000, v209
	v_lshlrev_b32_e32 v18, 16, v210
	v_and_b32_e32 v19, 0xffff0000, v210
	v_lshlrev_b32_e32 v20, 16, v211
	v_and_b32_e32 v21, 0xffff0000, v211
	v_lshlrev_b32_e32 v22, 16, v212
	v_and_b32_e32 v23, 0xffff0000, v212
	v_lshlrev_b32_e32 v24, 16, v213
	v_and_b32_e32 v25, 0xffff0000, v213
	v_pk_fma_f32 v[10:11], v[2:3], v[18:19], v[10:11]
	v_pk_fma_f32 v[12:13], v[4:5], v[20:21], v[12:13]
	v_pk_fma_f32 v[14:15], v[6:7], v[22:23], v[14:15]
	v_pk_fma_f32 v[16:17], v[8:9], v[24:25], v[16:17]
	v_pk_mul_f32 v[10:11], v[10:11], s[14:15] op_sel_hi:[1,0]
	v_pk_mul_f32 v[12:13], v[12:13], s[14:15] op_sel_hi:[1,0]
	v_pk_mul_f32 v[14:15], v[14:15], s[14:15] op_sel_hi:[1,0]
	v_pk_mul_f32 v[16:17], v[16:17], s[14:15] op_sel_hi:[1,0]
	v_med3_f32 v10, v10, s49, v197
	v_med3_f32 v11, v11, s49, v197
	v_med3_f32 v12, v12, s49, v197
	v_med3_f32 v13, v13, s49, v197
	v_med3_f32 v14, v14, s49, v197
	v_med3_f32 v15, v15, s49, v197
	v_med3_f32 v16, v16, s49, v197
	v_med3_f32 v17, v17, s49, v197
	v_cvt_pk_fp8_f32 v30, v10, v11
	v_cvt_pk_fp8_f32 v31, v14, v15
	v_cvt_pk_fp8_f32 v30, v12, v13 op_sel:[0,0,1]
	v_cvt_pk_fp8_f32 v31, v16, v17 op_sel:[0,0,1]
	s_nop 0
	global_store_dwordx2 v33, v[30:31], s[6:7] offset:128
	v_pk_mul_f32 v[4:5], v[48:49], s[12:13] op_sel_hi:[1,0]
	v_pk_mul_f32 v[2:3], v[46:47], s[12:13] op_sel_hi:[1,0]
	v_pk_mul_f32 v[8:9], v[44:45], s[12:13] op_sel_hi:[1,0]
	v_pk_mul_f32 v[6:7], v[42:43], s[12:13] op_sel_hi:[1,0]
	v_mov_b32_e32 v30, 0
	v_mov_b32_e32 v31, 0
	s_waitcnt vmcnt(7)
	v_lshlrev_b32_e32 v10, 16, v214
	v_and_b32_e32 v11, 0xffff0000, v214
	v_lshlrev_b32_e32 v12, 16, v215
	v_and_b32_e32 v13, 0xffff0000, v215
	v_lshlrev_b32_e32 v14, 16, v216
	v_and_b32_e32 v15, 0xffff0000, v216
	v_lshlrev_b32_e32 v16, 16, v217
	v_and_b32_e32 v17, 0xffff0000, v217
	v_lshlrev_b32_e32 v18, 16, v218
	v_and_b32_e32 v19, 0xffff0000, v218
	v_lshlrev_b32_e32 v20, 16, v219
	v_and_b32_e32 v21, 0xffff0000, v219
	v_lshlrev_b32_e32 v22, 16, v220
	v_and_b32_e32 v23, 0xffff0000, v220
	v_lshlrev_b32_e32 v24, 16, v221
	v_and_b32_e32 v25, 0xffff0000, v221
	v_pk_fma_f32 v[10:11], v[2:3], v[18:19], v[10:11]
	v_pk_fma_f32 v[12:13], v[4:5], v[20:21], v[12:13]
	v_pk_fma_f32 v[14:15], v[6:7], v[22:23], v[14:15]
	v_pk_fma_f32 v[16:17], v[8:9], v[24:25], v[16:17]
	v_pk_mul_f32 v[10:11], v[10:11], s[14:15] op_sel_hi:[1,0]
	v_pk_mul_f32 v[12:13], v[12:13], s[14:15] op_sel_hi:[1,0]
	v_pk_mul_f32 v[14:15], v[14:15], s[14:15] op_sel_hi:[1,0]
	v_pk_mul_f32 v[16:17], v[16:17], s[14:15] op_sel_hi:[1,0]
	v_med3_f32 v10, v10, s49, v197
	v_med3_f32 v11, v11, s49, v197
	v_med3_f32 v12, v12, s49, v197
	v_med3_f32 v13, v13, s49, v197
	v_med3_f32 v14, v14, s49, v197
	v_med3_f32 v15, v15, s49, v197
	v_med3_f32 v16, v16, s49, v197
	v_med3_f32 v17, v17, s49, v197
	v_cvt_pk_fp8_f32 v30, v10, v11
	v_cvt_pk_fp8_f32 v31, v14, v15
	v_cvt_pk_fp8_f32 v30, v12, v13 op_sel:[0,0,1]
	v_cvt_pk_fp8_f32 v31, v16, v17 op_sel:[0,0,1]
	v_add_u32_e32 v33, 0x58000, v255
	s_nop 0
	global_store_dwordx2 v33, v[30:31], s[6:7] offset:0
	v_pk_mul_f32 v[4:5], v[40:41], s[12:13] op_sel_hi:[1,0]
	v_pk_mul_f32 v[2:3], v[38:39], s[12:13] op_sel_hi:[1,0]
	v_pk_mul_f32 v[8:9], v[36:37], s[12:13] op_sel_hi:[1,0]
	v_pk_mul_f32 v[6:7], v[34:35], s[12:13] op_sel_hi:[1,0]
	v_mov_b32_e32 v30, 0
	v_mov_b32_e32 v31, 0
	s_waitcnt vmcnt(5)
	v_lshlrev_b32_e32 v10, 16, v222
	v_and_b32_e32 v11, 0xffff0000, v222
	v_lshlrev_b32_e32 v12, 16, v223
	v_and_b32_e32 v13, 0xffff0000, v223
	v_lshlrev_b32_e32 v14, 16, v224
	v_and_b32_e32 v15, 0xffff0000, v224
	v_lshlrev_b32_e32 v16, 16, v225
	v_and_b32_e32 v17, 0xffff0000, v225
	v_lshlrev_b32_e32 v18, 16, v226
	v_and_b32_e32 v19, 0xffff0000, v226
	v_lshlrev_b32_e32 v20, 16, v227
	v_and_b32_e32 v21, 0xffff0000, v227
	v_lshlrev_b32_e32 v22, 16, v228
	v_and_b32_e32 v23, 0xffff0000, v228
	v_lshlrev_b32_e32 v24, 16, v229
	v_and_b32_e32 v25, 0xffff0000, v229
	v_pk_fma_f32 v[10:11], v[2:3], v[18:19], v[10:11]
	v_pk_fma_f32 v[12:13], v[4:5], v[20:21], v[12:13]
	v_pk_fma_f32 v[14:15], v[6:7], v[22:23], v[14:15]
	v_pk_fma_f32 v[16:17], v[8:9], v[24:25], v[16:17]
	v_pk_mul_f32 v[10:11], v[10:11], s[14:15] op_sel_hi:[1,0]
	v_pk_mul_f32 v[12:13], v[12:13], s[14:15] op_sel_hi:[1,0]
	v_pk_mul_f32 v[14:15], v[14:15], s[14:15] op_sel_hi:[1,0]
	v_pk_mul_f32 v[16:17], v[16:17], s[14:15] op_sel_hi:[1,0]
	v_med3_f32 v10, v10, s49, v197
	v_med3_f32 v11, v11, s49, v197
	v_med3_f32 v12, v12, s49, v197
	v_med3_f32 v13, v13, s49, v197
	v_med3_f32 v14, v14, s49, v197
	v_med3_f32 v15, v15, s49, v197
	v_med3_f32 v16, v16, s49, v197
	v_med3_f32 v17, v17, s49, v197
	v_cvt_pk_fp8_f32 v30, v10, v11
	v_cvt_pk_fp8_f32 v31, v14, v15
	v_cvt_pk_fp8_f32 v30, v12, v13 op_sel:[0,0,1]
	v_cvt_pk_fp8_f32 v31, v16, v17 op_sel:[0,0,1]
	s_nop 0
	global_store_dwordx2 v33, v[30:31], s[6:7] offset:128
	s_andn2_b64 vcc, exec, s[0:1]
	s_mov_b64 s[0:1], -1
	s_cbranch_vccnz .LBB0_449
	s_andn2_b64 vcc, exec, s[4:5]
	s_cbranch_vccnz .LBB0_448
	s_barrier
	s_branch .LBB0_448

.LBB0_532:
	ds_read_b128 v[18:21], v190
	ds_read_b128 v[26:29], v190 offset:2048
	ds_read_b128 v[22:25], v191
	ds_read_b128 v[30:33], v191 offset:2048
	ds_read_b128 v[2:5], v192
	ds_read_b128 v[10:13], v192 offset:2048
	ds_read_b128 v[6:9], v193
	ds_read_b128 v[14:17], v193 offset:2048
	s_add_u32 s42, s40, 0xfffc0080
	s_addc_u32 s43, s41, -1
	s_cmp_eq_u32 s61, 12
	s_cselect_b32 s45, s31, s43
	s_cselect_b32 s44, s57, s42
	s_cselect_b32 s43, s29, s60
	s_cselect_b32 s42, s58, s59
	s_add_i32 m0, s39, 0xc000
	ds_read_b128 v[178:181], v194
	ds_read_b128 v[198:201], v194 offset:2048
	ds_read_b128 v[182:185], v195
	ds_read_b128 v[202:205], v195 offset:2048
	ds_read_b128 v[206:209], v194 offset:4096
	ds_read_b128 v[214:217], v194 offset:6144
	ds_read_b128 v[210:213], v195 offset:4096
	ds_read_b128 v[218:221], v195 offset:6144
	global_load_lds_dwordx4 v170, s[40:41]
	s_add_i32 m0, s39, 0xe000
	s_nop 0
	global_load_lds_dwordx4 v172, s[40:41]
	s_waitcnt vmcnt(8)
	s_waitcnt lgkmcnt(0)
	s_barrier
	s_setprio 1
	s_waitcnt lgkmcnt(0)
	v_mfma_scale_f32_16x16x128_f8f6f4 v[158:161], v[18:25], v[178:185], v[158:161], v1, v1 op_sel_hi:[0,0,0]
	v_mfma_scale_f32_16x16x128_f8f6f4 v[154:157], v[26:33], v[178:185], v[154:157], v1, v1 op_sel_hi:[0,0,0]
	v_mfma_scale_f32_16x16x128_f8f6f4 v[142:145], v[18:25], v[198:205], v[142:145], v1, v1 op_sel_hi:[0,0,0]
	v_mfma_scale_f32_16x16x128_f8f6f4 v[138:141], v[26:33], v[198:205], v[138:141], v1, v1 op_sel_hi:[0,0,0]
	v_mfma_scale_f32_16x16x128_f8f6f4 v[126:129], v[18:25], v[206:213], v[126:129], v1, v1 op_sel_hi:[0,0,0]
	v_mfma_scale_f32_16x16x128_f8f6f4 v[122:125], v[26:33], v[206:213], v[122:125], v1, v1 op_sel_hi:[0,0,0]
	v_mfma_scale_f32_16x16x128_f8f6f4 v[110:113], v[18:25], v[214:221], v[110:113], v1, v1 op_sel_hi:[0,0,0]
	v_mfma_scale_f32_16x16x128_f8f6f4 v[106:109], v[26:33], v[214:221], v[106:109], v1, v1 op_sel_hi:[0,0,0]
	s_setprio 0
	s_setprio 1
	v_mfma_scale_f32_16x16x128_f8f6f4 v[150:153], v[2:9], v[178:185], v[150:153], v1, v1 op_sel_hi:[0,0,0]
	v_mfma_scale_f32_16x16x128_f8f6f4 v[146:149], v[10:17], v[178:185], v[146:149], v1, v1 op_sel_hi:[0,0,0]
	v_mfma_scale_f32_16x16x128_f8f6f4 v[134:137], v[2:9], v[198:205], v[134:137], v1, v1 op_sel_hi:[0,0,0]
	v_mfma_scale_f32_16x16x128_f8f6f4 v[130:133], v[10:17], v[198:205], v[130:133], v1, v1 op_sel_hi:[0,0,0]
	v_mfma_scale_f32_16x16x128_f8f6f4 v[118:121], v[2:9], v[206:213], v[118:121], v1, v1 op_sel_hi:[0,0,0]
	v_mfma_scale_f32_16x16x128_f8f6f4 v[114:117], v[10:17], v[206:213], v[114:117], v1, v1 op_sel_hi:[0,0,0]
	v_mfma_scale_f32_16x16x128_f8f6f4 v[102:105], v[2:9], v[214:221], v[102:105], v1, v1 op_sel_hi:[0,0,0]
	v_mfma_scale_f32_16x16x128_f8f6f4 v[98:101], v[10:17], v[214:221], v[98:101], v1, v1 op_sel_hi:[0,0,0]
	s_setprio 0
	s_barrier
	s_add_i32 s62, s54, s33
	v_lshl_add_u64 v[178:179], s[42:43], 0, v[164:165]
	s_mov_b32 m0, s62
	ds_read_b128 v[198:201], v194 offset:16384
	ds_read_b128 v[206:209], v194 offset:18432
	ds_read_b128 v[202:205], v195 offset:16384
	ds_read_b128 v[210:213], v195 offset:18432
	ds_read_b128 v[214:217], v194 offset:20480
	ds_read_b128 v[222:225], v194 offset:22528
	ds_read_b128 v[218:221], v195 offset:20480
	ds_read_b128 v[226:229], v195 offset:22528
	global_load_lds_dwordx4 v[178:179], off
	s_add_i32 m0, s62, 0x2000
	s_add_u32 s62, s42, 0x40000
	v_lshl_add_u64 v[180:181], s[42:43], 0, v[168:169]
	s_addc_u32 s63, s43, 0
	s_add_i32 s64, s55, s33
	global_load_lds_dwordx4 v[180:181], off
	s_mov_b32 m0, s64
	v_lshl_add_u64 v[184:185], s[44:45], 0, v[166:167]
	global_load_lds_dwordx4 v164, s[62:63]
	s_add_i32 m0, s64, 0x2000
	s_nop 0
	global_load_lds_dwordx4 v168, s[62:63]
	v_lshl_add_u64 v[182:183], s[44:45], 0, v[162:163]
	s_mov_b32 m0, s39
	s_nop 0
	global_load_lds_dwordx4 v[182:183], off
	s_mov_b32 m0, s47
	s_nop 0
	global_load_lds_dwordx4 v[184:185], off
	s_waitcnt vmcnt(8)
	s_waitcnt lgkmcnt(0)
	s_barrier
	s_setprio 1
	s_waitcnt lgkmcnt(0)
	v_mfma_scale_f32_16x16x128_f8f6f4 v[94:97], v[18:25], v[198:205], v[94:97], v1, v1 op_sel_hi:[0,0,0]
	v_mfma_scale_f32_16x16x128_f8f6f4 v[90:93], v[26:33], v[198:205], v[90:93], v1, v1 op_sel_hi:[0,0,0]
	v_mfma_scale_f32_16x16x128_f8f6f4 v[78:81], v[18:25], v[206:213], v[78:81], v1, v1 op_sel_hi:[0,0,0]
	v_mfma_scale_f32_16x16x128_f8f6f4 v[74:77], v[26:33], v[206:213], v[74:77], v1, v1 op_sel_hi:[0,0,0]
	v_mfma_scale_f32_16x16x128_f8f6f4 v[62:65], v[18:25], v[214:221], v[62:65], v1, v1 op_sel_hi:[0,0,0]
	v_mfma_scale_f32_16x16x128_f8f6f4 v[58:61], v[26:33], v[214:221], v[58:61], v1, v1 op_sel_hi:[0,0,0]
	v_mfma_scale_f32_16x16x128_f8f6f4 v[46:49], v[18:25], v[222:229], v[46:49], v1, v1 op_sel_hi:[0,0,0]
	v_mfma_scale_f32_16x16x128_f8f6f4 v[42:45], v[26:33], v[222:229], v[42:45], v1, v1 op_sel_hi:[0,0,0]
	s_setprio 0
	s_setprio 1
	v_mfma_scale_f32_16x16x128_f8f6f4 v[86:89], v[2:9], v[198:205], v[86:89], v1, v1 op_sel_hi:[0,0,0]
	v_mfma_scale_f32_16x16x128_f8f6f4 v[82:85], v[10:17], v[198:205], v[82:85], v1, v1 op_sel_hi:[0,0,0]
	v_mfma_scale_f32_16x16x128_f8f6f4 v[70:73], v[2:9], v[206:213], v[70:73], v1, v1 op_sel_hi:[0,0,0]
	v_mfma_scale_f32_16x16x128_f8f6f4 v[66:69], v[10:17], v[206:213], v[66:69], v1, v1 op_sel_hi:[0,0,0]
	v_mfma_scale_f32_16x16x128_f8f6f4 v[54:57], v[2:9], v[214:221], v[54:57], v1, v1 op_sel_hi:[0,0,0]
	v_mfma_scale_f32_16x16x128_f8f6f4 v[50:53], v[10:17], v[214:221], v[50:53], v1, v1 op_sel_hi:[0,0,0]
	v_mfma_scale_f32_16x16x128_f8f6f4 v[38:41], v[2:9], v[222:229], v[38:41], v1, v1 op_sel_hi:[0,0,0]
	v_mfma_scale_f32_16x16x128_f8f6f4 v[34:37], v[10:17], v[222:229], v[34:37], v1, v1 op_sel_hi:[0,0,0]
	s_setprio 0
	s_barrier
	s_add_i32 s62, 0, 0x18000
	s_add_i32 s63, 0, 0x1c000
	v_add_u32_e32 v6, s62, v186
	v_add_u32_e32 v14, s62, v187
	v_add_u32_e32 v22, s63, v186
	v_add_u32_e32 v30, s63, v187
	ds_read_b128 v[2:5], v6
	ds_read_b128 v[10:13], v6 offset:2048
	ds_read_b128 v[6:9], v14
	ds_read_b128 v[14:17], v14 offset:2048
	ds_read_b128 v[18:21], v22
	ds_read_b128 v[26:29], v22 offset:2048
	ds_read_b128 v[22:25], v30
	ds_read_b128 v[30:33], v30 offset:2048
	s_add_u32 s44, s44, 0x40000
	s_addc_u32 s45, s45, 0
	s_mov_b32 m0, s48
	ds_read_b128 v[198:201], v194 offset:32768
	ds_read_b128 v[206:209], v194 offset:34816
	ds_read_b128 v[202:205], v195 offset:32768
	ds_read_b128 v[210:213], v195 offset:34816
	ds_read_b128 v[214:217], v194 offset:36864
	ds_read_b128 v[222:225], v194 offset:38912
	ds_read_b128 v[218:221], v195 offset:36864
	ds_read_b128 v[226:229], v195 offset:38912
	global_load_lds_dwordx4 v162, s[44:45]
	s_mov_b32 m0, s49
	s_nop 0
	global_load_lds_dwordx4 v166, s[44:45]
	s_waitcnt vmcnt(8)
	s_waitcnt lgkmcnt(0)
	s_barrier
	s_setprio 1
	s_waitcnt lgkmcnt(0)
	v_mfma_scale_f32_16x16x128_f8f6f4 v[158:161], v[2:9], v[198:205], v[158:161], v1, v1 op_sel_hi:[0,0,0]
	v_mfma_scale_f32_16x16x128_f8f6f4 v[154:157], v[10:17], v[198:205], v[154:157], v1, v1 op_sel_hi:[0,0,0]
	v_mfma_scale_f32_16x16x128_f8f6f4 v[142:145], v[2:9], v[206:213], v[142:145], v1, v1 op_sel_hi:[0,0,0]
	v_mfma_scale_f32_16x16x128_f8f6f4 v[138:141], v[10:17], v[206:213], v[138:141], v1, v1 op_sel_hi:[0,0,0]
	v_mfma_scale_f32_16x16x128_f8f6f4 v[126:129], v[2:9], v[214:221], v[126:129], v1, v1 op_sel_hi:[0,0,0]
	v_mfma_scale_f32_16x16x128_f8f6f4 v[122:125], v[10:17], v[214:221], v[122:125], v1, v1 op_sel_hi:[0,0,0]
	v_mfma_scale_f32_16x16x128_f8f6f4 v[110:113], v[2:9], v[222:229], v[110:113], v1, v1 op_sel_hi:[0,0,0]
	v_mfma_scale_f32_16x16x128_f8f6f4 v[106:109], v[10:17], v[222:229], v[106:109], v1, v1 op_sel_hi:[0,0,0]
	s_setprio 0
	s_setprio 1
	v_mfma_scale_f32_16x16x128_f8f6f4 v[150:153], v[18:25], v[198:205], v[150:153], v1, v1 op_sel_hi:[0,0,0]
	v_mfma_scale_f32_16x16x128_f8f6f4 v[146:149], v[26:33], v[198:205], v[146:149], v1, v1 op_sel_hi:[0,0,0]
	v_mfma_scale_f32_16x16x128_f8f6f4 v[134:137], v[18:25], v[206:213], v[134:137], v1, v1 op_sel_hi:[0,0,0]
	v_mfma_scale_f32_16x16x128_f8f6f4 v[130:133], v[26:33], v[206:213], v[130:133], v1, v1 op_sel_hi:[0,0,0]
	v_mfma_scale_f32_16x16x128_f8f6f4 v[118:121], v[18:25], v[214:221], v[118:121], v1, v1 op_sel_hi:[0,0,0]
	v_mfma_scale_f32_16x16x128_f8f6f4 v[114:117], v[26:33], v[214:221], v[114:117], v1, v1 op_sel_hi:[0,0,0]
	v_mfma_scale_f32_16x16x128_f8f6f4 v[102:105], v[18:25], v[222:229], v[102:105], v1, v1 op_sel_hi:[0,0,0]
	v_mfma_scale_f32_16x16x128_f8f6f4 v[98:101], v[26:33], v[222:229], v[98:101], v1, v1 op_sel_hi:[0,0,0]
	s_setprio 0
	s_barrier
	s_add_i32 s44, s62, s33
	v_lshl_add_u64 v[178:179], v[178:179], 0, s[10:11]
	s_mov_b32 m0, s44
	ds_read_b128 v[198:201], v194 offset:49152
	ds_read_b128 v[206:209], v194 offset:51200
	ds_read_b128 v[202:205], v195 offset:49152
	ds_read_b128 v[210:213], v195 offset:51200
	ds_read_b128 v[214:217], v194 offset:53248
	ds_read_b128 v[222:225], v194 offset:55296
	ds_read_b128 v[218:221], v195 offset:53248
	ds_read_b128 v[226:229], v195 offset:55296
	global_load_lds_dwordx4 v[178:179], off
	s_add_i32 m0, s44, 0x2000
	s_add_u32 s42, s42, 0x40080
	v_lshl_add_u64 v[178:179], v[180:181], 0, s[10:11]
	s_addc_u32 s43, s43, 0
	s_add_i32 s44, s63, s33
	global_load_lds_dwordx4 v[178:179], off
	s_mov_b32 m0, s44
	s_nop 0
	global_load_lds_dwordx4 v164, s[42:43]
	s_add_i32 m0, s44, 0x2000
	s_nop 0
	global_load_lds_dwordx4 v168, s[42:43]
	v_lshl_add_u64 v[178:179], v[182:183], 0, s[10:11]
	s_mov_b32 m0, s52
	s_nop 0
	global_load_lds_dwordx4 v[178:179], off
	v_lshl_add_u64 v[178:179], v[184:185], 0, s[10:11]
	s_mov_b32 m0, s53
	s_nop 0
	global_load_lds_dwordx4 v[178:179], off
	s_waitcnt vmcnt(8)
	s_waitcnt lgkmcnt(0)
	s_barrier
	s_setprio 1
	s_waitcnt lgkmcnt(0)
	v_mfma_scale_f32_16x16x128_f8f6f4 v[94:97], v[2:9], v[198:205], v[94:97], v1, v1 op_sel_hi:[0,0,0]
	v_mfma_scale_f32_16x16x128_f8f6f4 v[90:93], v[10:17], v[198:205], v[90:93], v1, v1 op_sel_hi:[0,0,0]
	v_mfma_scale_f32_16x16x128_f8f6f4 v[78:81], v[2:9], v[206:213], v[78:81], v1, v1 op_sel_hi:[0,0,0]
	v_mfma_scale_f32_16x16x128_f8f6f4 v[74:77], v[10:17], v[206:213], v[74:77], v1, v1 op_sel_hi:[0,0,0]
	v_mfma_scale_f32_16x16x128_f8f6f4 v[62:65], v[2:9], v[214:221], v[62:65], v1, v1 op_sel_hi:[0,0,0]
	v_mfma_scale_f32_16x16x128_f8f6f4 v[58:61], v[10:17], v[214:221], v[58:61], v1, v1 op_sel_hi:[0,0,0]
	v_mfma_scale_f32_16x16x128_f8f6f4 v[46:49], v[2:9], v[222:229], v[46:49], v1, v1 op_sel_hi:[0,0,0]
	v_mfma_scale_f32_16x16x128_f8f6f4 v[42:45], v[10:17], v[222:229], v[42:45], v1, v1 op_sel_hi:[0,0,0]
	s_setprio 0
	s_setprio 1
	v_mfma_scale_f32_16x16x128_f8f6f4 v[86:89], v[18:25], v[198:205], v[86:89], v1, v1 op_sel_hi:[0,0,0]
	v_mfma_scale_f32_16x16x128_f8f6f4 v[82:85], v[26:33], v[198:205], v[82:85], v1, v1 op_sel_hi:[0,0,0]
	v_mfma_scale_f32_16x16x128_f8f6f4 v[70:73], v[18:25], v[206:213], v[70:73], v1, v1 op_sel_hi:[0,0,0]
	v_mfma_scale_f32_16x16x128_f8f6f4 v[66:69], v[26:33], v[206:213], v[66:69], v1, v1 op_sel_hi:[0,0,0]
	v_mfma_scale_f32_16x16x128_f8f6f4 v[54:57], v[18:25], v[214:221], v[54:57], v1, v1 op_sel_hi:[0,0,0]
	v_mfma_scale_f32_16x16x128_f8f6f4 v[50:53], v[26:33], v[214:221], v[50:53], v1, v1 op_sel_hi:[0,0,0]
	v_mfma_scale_f32_16x16x128_f8f6f4 v[38:41], v[18:25], v[222:229], v[38:41], v1, v1 op_sel_hi:[0,0,0]
	v_mfma_scale_f32_16x16x128_f8f6f4 v[34:37], v[26:33], v[222:229], v[34:37], v1, v1 op_sel_hi:[0,0,0]
	s_setprio 0
	s_barrier
	s_add_i32 s61, s61, 2
	s_add_u32 s40, s40, 0x100
	s_addc_u32 s41, s41, 0
	s_add_u32 s59, s59, 0x100
	s_addc_u32 s60, s60, 0
	s_cmp_gt_u32 s61, 13
	s_cbranch_scc0 .LBB0_532
	s_nop 15
	s_nop 15
	s_and_b64 vcc, exec, s[12:13]
	s_cbranch_vccz .LBB0_535
	s_barrier

.LBB0_619:
	ds_read_b128 v[152:155], v148
	ds_read_b128 v[156:159], v148 offset:1024
	ds_read_b128 v[160:163], v148 offset:2048
	ds_read_b128 v[164:167], v148 offset:3072
	ds_read_b128 v[168:171], v149
	ds_read_b128 v[172:175], v149 offset:1024
	ds_read_b128 v[176:179], v149 offset:2048
	ds_read_b128 v[180:183], v149 offset:3072
	s_add_i32 s63, s36, 2
	s_add_u32 s64, s34, 0x80
	s_addc_u32 s37, s35, 0
	s_cmp_eq_u32 s49, s36
	s_cselect_b32 s36, s4, s64
	s_cselect_b32 s37, s5, s37
	s_cselect_b32 s65, s31, s62
	s_cselect_b32 s64, s30, s61
	s_add_i32 m0, s41, 0xc000
	ds_read_b128 v[184:187], v150
	ds_read_b128 v[188:191], v150 offset:1024
	ds_read_b128 v[192:195], v150 offset:2048
	ds_read_b128 v[198:201], v150 offset:3072
	ds_read_b128 v[202:205], v150 offset:4096
	ds_read_b128 v[206:209], v150 offset:5120
	ds_read_b128 v[210:213], v150 offset:6144
	ds_read_b128 v[214:217], v150 offset:7168
	global_load_lds_dwordx4 v138, s[34:35]
	s_add_i32 m0, s41, 0xe000
	s_nop 0
	global_load_lds_dwordx4 v140, s[34:35]
	s_waitcnt vmcnt(8)
	s_waitcnt lgkmcnt(0)
	s_barrier
	s_setprio 1
	s_waitcnt lgkmcnt(0)
	v_mfma_f32_16x16x32_bf16 v[122:125], v[152:155], v[184:187], v[122:125]
	v_mfma_f32_16x16x32_bf16 v[126:129], v[160:163], v[184:187], v[126:129]
	v_mfma_f32_16x16x32_bf16 v[110:113], v[152:155], v[192:195], v[110:113]
	v_mfma_f32_16x16x32_bf16 v[106:109], v[160:163], v[192:195], v[106:109]
	v_mfma_f32_16x16x32_bf16 v[94:97], v[152:155], v[202:205], v[94:97]
	v_mfma_f32_16x16x32_bf16 v[90:93], v[160:163], v[202:205], v[90:93]
	v_mfma_f32_16x16x32_bf16 v[78:81], v[152:155], v[210:213], v[78:81]
	v_mfma_f32_16x16x32_bf16 v[74:77], v[160:163], v[210:213], v[74:77]
	v_mfma_f32_16x16x32_bf16 v[122:125], v[156:159], v[188:191], v[122:125]
	v_mfma_f32_16x16x32_bf16 v[126:129], v[164:167], v[188:191], v[126:129]
	v_mfma_f32_16x16x32_bf16 v[110:113], v[156:159], v[198:201], v[110:113]
	v_mfma_f32_16x16x32_bf16 v[106:109], v[164:167], v[198:201], v[106:109]
	v_mfma_f32_16x16x32_bf16 v[94:97], v[156:159], v[206:209], v[94:97]
	v_mfma_f32_16x16x32_bf16 v[90:93], v[164:167], v[206:209], v[90:93]
	v_mfma_f32_16x16x32_bf16 v[78:81], v[156:159], v[214:217], v[78:81]
	v_mfma_f32_16x16x32_bf16 v[74:77], v[164:167], v[214:217], v[74:77]
	s_setprio 0
	s_setprio 1
	v_mfma_f32_16x16x32_bf16 v[118:121], v[168:171], v[184:187], v[118:121]
	v_mfma_f32_16x16x32_bf16 v[114:117], v[176:179], v[184:187], v[114:117]
	v_mfma_f32_16x16x32_bf16 v[102:105], v[168:171], v[192:195], v[102:105]
	v_mfma_f32_16x16x32_bf16 v[98:101], v[176:179], v[192:195], v[98:101]
	v_mfma_f32_16x16x32_bf16 v[86:89], v[168:171], v[202:205], v[86:89]
	v_mfma_f32_16x16x32_bf16 v[82:85], v[176:179], v[202:205], v[82:85]
	v_mfma_f32_16x16x32_bf16 v[70:73], v[168:171], v[210:213], v[70:73]
	v_mfma_f32_16x16x32_bf16 v[66:69], v[176:179], v[210:213], v[66:69]
	v_mfma_f32_16x16x32_bf16 v[118:121], v[172:175], v[188:191], v[118:121]
	v_mfma_f32_16x16x32_bf16 v[114:117], v[180:183], v[188:191], v[114:117]
	v_mfma_f32_16x16x32_bf16 v[102:105], v[172:175], v[198:201], v[102:105]
	v_mfma_f32_16x16x32_bf16 v[98:101], v[180:183], v[198:201], v[98:101]
	v_mfma_f32_16x16x32_bf16 v[86:89], v[172:175], v[206:209], v[86:89]
	v_mfma_f32_16x16x32_bf16 v[82:85], v[180:183], v[206:209], v[82:85]
	v_mfma_f32_16x16x32_bf16 v[70:73], v[172:175], v[214:217], v[70:73]
	v_mfma_f32_16x16x32_bf16 v[66:69], v[180:183], v[214:217], v[66:69]
	s_setprio 0
	s_barrier
	s_add_i32 s66, s51, s40
	v_lshl_add_u64 v[218:219], s[64:65], 0, v[132:133]
	s_mov_b32 m0, s66
	ds_read_b128 v[184:187], v150 offset:16384
	ds_read_b128 v[188:191], v150 offset:17408
	ds_read_b128 v[192:195], v150 offset:18432
	ds_read_b128 v[198:201], v150 offset:19456
	ds_read_b128 v[202:205], v150 offset:20480
	ds_read_b128 v[206:209], v150 offset:21504
	ds_read_b128 v[210:213], v150 offset:22528
	ds_read_b128 v[214:217], v150 offset:23552
	global_load_lds_dwordx4 v[218:219], off
	s_add_i32 m0, s66, 0x2000
	v_lshl_add_u64 v[220:221], s[64:65], 0, v[136:137]
	s_add_u32 s64, s64, s6
	s_addc_u32 s65, s65, s7
	s_add_i32 s66, s52, s40
	global_load_lds_dwordx4 v[220:221], off
	v_lshl_add_u64 v[222:223], s[64:65], 0, v[132:133]
	s_mov_b32 m0, s66
	v_lshl_add_u64 v[224:225], s[64:65], 0, v[136:137]
	global_load_lds_dwordx4 v[222:223], off
	s_add_i32 m0, s66, 0x2000
	v_lshl_add_u64 v[226:227], s[36:37], 0, v[130:131]
	global_load_lds_dwordx4 v[224:225], off
	s_mov_b32 m0, s41
	v_lshl_add_u64 v[228:229], s[36:37], 0, v[134:135]
	global_load_lds_dwordx4 v[226:227], off
	s_mov_b32 m0, s42
	s_nop 0
	global_load_lds_dwordx4 v[228:229], off
	s_waitcnt vmcnt(8)
	s_waitcnt lgkmcnt(0)
	s_barrier
	s_setprio 1
	s_waitcnt lgkmcnt(0)
	v_mfma_f32_16x16x32_bf16 v[62:65], v[152:155], v[184:187], v[62:65]
	v_mfma_f32_16x16x32_bf16 v[58:61], v[160:163], v[184:187], v[58:61]
	v_mfma_f32_16x16x32_bf16 v[46:49], v[152:155], v[192:195], v[46:49]
	v_mfma_f32_16x16x32_bf16 v[42:45], v[160:163], v[192:195], v[42:45]
	v_mfma_f32_16x16x32_bf16 v[30:33], v[152:155], v[202:205], v[30:33]
	v_mfma_f32_16x16x32_bf16 v[26:29], v[160:163], v[202:205], v[26:29]
	v_mfma_f32_16x16x32_bf16 v[14:17], v[152:155], v[210:213], v[14:17]
	v_mfma_f32_16x16x32_bf16 v[10:13], v[160:163], v[210:213], v[10:13]
	v_mfma_f32_16x16x32_bf16 v[62:65], v[156:159], v[188:191], v[62:65]
	v_mfma_f32_16x16x32_bf16 v[58:61], v[164:167], v[188:191], v[58:61]
	v_mfma_f32_16x16x32_bf16 v[46:49], v[156:159], v[198:201], v[46:49]
	v_mfma_f32_16x16x32_bf16 v[42:45], v[164:167], v[198:201], v[42:45]
	v_mfma_f32_16x16x32_bf16 v[30:33], v[156:159], v[206:209], v[30:33]
	v_mfma_f32_16x16x32_bf16 v[26:29], v[164:167], v[206:209], v[26:29]
	v_mfma_f32_16x16x32_bf16 v[14:17], v[156:159], v[214:217], v[14:17]
	v_mfma_f32_16x16x32_bf16 v[10:13], v[164:167], v[214:217], v[10:13]
	s_setprio 0
	s_setprio 1
	v_mfma_f32_16x16x32_bf16 v[54:57], v[168:171], v[184:187], v[54:57]
	v_mfma_f32_16x16x32_bf16 v[50:53], v[176:179], v[184:187], v[50:53]
	v_mfma_f32_16x16x32_bf16 v[38:41], v[168:171], v[192:195], v[38:41]
	v_mfma_f32_16x16x32_bf16 v[34:37], v[176:179], v[192:195], v[34:37]
	v_mfma_f32_16x16x32_bf16 v[22:25], v[168:171], v[202:205], v[22:25]
	v_mfma_f32_16x16x32_bf16 v[18:21], v[176:179], v[202:205], v[18:21]
	v_mfma_f32_16x16x32_bf16 v[6:9], v[168:171], v[210:213], v[6:9]
	v_mfma_f32_16x16x32_bf16 v[2:5], v[176:179], v[210:213], v[2:5]
	v_mfma_f32_16x16x32_bf16 v[54:57], v[172:175], v[188:191], v[54:57]
	v_mfma_f32_16x16x32_bf16 v[50:53], v[180:183], v[188:191], v[50:53]
	v_mfma_f32_16x16x32_bf16 v[38:41], v[172:175], v[198:201], v[38:41]
	v_mfma_f32_16x16x32_bf16 v[34:37], v[180:183], v[198:201], v[34:37]
	v_mfma_f32_16x16x32_bf16 v[22:25], v[172:175], v[206:209], v[22:25]
	v_mfma_f32_16x16x32_bf16 v[18:21], v[180:183], v[206:209], v[18:21]
	v_mfma_f32_16x16x32_bf16 v[6:9], v[172:175], v[214:217], v[6:9]
	v_mfma_f32_16x16x32_bf16 v[2:5], v[180:183], v[214:217], v[2:5]
	s_setprio 0
	s_barrier
	s_add_i32 s64, 0, 0x18000
	v_add_u32_e32 v151, s64, v146
	s_add_i32 s65, 0, 0x1c000
	ds_read_b128 v[152:155], v151
	ds_read_b128 v[156:159], v151 offset:1024
	ds_read_b128 v[160:163], v151 offset:2048
	ds_read_b128 v[164:167], v151 offset:3072
	v_add_u32_e32 v151, s65, v146
	ds_read_b128 v[168:171], v151
	ds_read_b128 v[172:175], v151 offset:1024
	ds_read_b128 v[176:179], v151 offset:2048
	ds_read_b128 v[180:183], v151 offset:3072
	s_add_u32 s36, s36, s6
	s_addc_u32 s37, s37, s7
	s_mov_b32 m0, s43
	ds_read_b128 v[184:187], v150 offset:32768
	ds_read_b128 v[188:191], v150 offset:33792
	ds_read_b128 v[192:195], v150 offset:34816
	ds_read_b128 v[198:201], v150 offset:35840
	ds_read_b128 v[202:205], v150 offset:36864
	ds_read_b128 v[206:209], v150 offset:37888
	ds_read_b128 v[210:213], v150 offset:38912
	ds_read_b128 v[214:217], v150 offset:39936
	global_load_lds_dwordx4 v130, s[36:37]
	s_mov_b32 m0, s44
	s_nop 0
	global_load_lds_dwordx4 v134, s[36:37]
	s_waitcnt vmcnt(8)
	s_waitcnt lgkmcnt(0)
	s_barrier
	s_setprio 1
	s_waitcnt lgkmcnt(0)
	v_mfma_f32_16x16x32_bf16 v[122:125], v[152:155], v[184:187], v[122:125]
	v_mfma_f32_16x16x32_bf16 v[126:129], v[160:163], v[184:187], v[126:129]
	v_mfma_f32_16x16x32_bf16 v[110:113], v[152:155], v[192:195], v[110:113]
	v_mfma_f32_16x16x32_bf16 v[106:109], v[160:163], v[192:195], v[106:109]
	v_mfma_f32_16x16x32_bf16 v[94:97], v[152:155], v[202:205], v[94:97]
	v_mfma_f32_16x16x32_bf16 v[90:93], v[160:163], v[202:205], v[90:93]
	v_mfma_f32_16x16x32_bf16 v[78:81], v[152:155], v[210:213], v[78:81]
	v_mfma_f32_16x16x32_bf16 v[74:77], v[160:163], v[210:213], v[74:77]
	v_mfma_f32_16x16x32_bf16 v[122:125], v[156:159], v[188:191], v[122:125]
	v_mfma_f32_16x16x32_bf16 v[126:129], v[164:167], v[188:191], v[126:129]
	v_mfma_f32_16x16x32_bf16 v[110:113], v[156:159], v[198:201], v[110:113]
	v_mfma_f32_16x16x32_bf16 v[106:109], v[164:167], v[198:201], v[106:109]
	v_mfma_f32_16x16x32_bf16 v[94:97], v[156:159], v[206:209], v[94:97]
	v_mfma_f32_16x16x32_bf16 v[90:93], v[164:167], v[206:209], v[90:93]
	v_mfma_f32_16x16x32_bf16 v[78:81], v[156:159], v[214:217], v[78:81]
	v_mfma_f32_16x16x32_bf16 v[74:77], v[164:167], v[214:217], v[74:77]
	s_setprio 0
	s_setprio 1
	v_mfma_f32_16x16x32_bf16 v[118:121], v[168:171], v[184:187], v[118:121]
	v_mfma_f32_16x16x32_bf16 v[114:117], v[176:179], v[184:187], v[114:117]
	v_mfma_f32_16x16x32_bf16 v[102:105], v[168:171], v[192:195], v[102:105]
	v_mfma_f32_16x16x32_bf16 v[98:101], v[176:179], v[192:195], v[98:101]
	v_mfma_f32_16x16x32_bf16 v[86:89], v[168:171], v[202:205], v[86:89]
	v_mfma_f32_16x16x32_bf16 v[82:85], v[176:179], v[202:205], v[82:85]
	v_mfma_f32_16x16x32_bf16 v[70:73], v[168:171], v[210:213], v[70:73]
	v_mfma_f32_16x16x32_bf16 v[66:69], v[176:179], v[210:213], v[66:69]
	v_mfma_f32_16x16x32_bf16 v[118:121], v[172:175], v[188:191], v[118:121]
	v_mfma_f32_16x16x32_bf16 v[114:117], v[180:183], v[188:191], v[114:117]
	v_mfma_f32_16x16x32_bf16 v[102:105], v[172:175], v[198:201], v[102:105]
	v_mfma_f32_16x16x32_bf16 v[98:101], v[180:183], v[198:201], v[98:101]
	v_mfma_f32_16x16x32_bf16 v[86:89], v[172:175], v[206:209], v[86:89]
	v_mfma_f32_16x16x32_bf16 v[82:85], v[180:183], v[206:209], v[82:85]
	v_mfma_f32_16x16x32_bf16 v[70:73], v[172:175], v[214:217], v[70:73]
	v_mfma_f32_16x16x32_bf16 v[66:69], v[180:183], v[214:217], v[66:69]
	s_setprio 0
	s_barrier
	s_add_i32 s36, s64, s40
	v_lshl_add_u64 v[218:219], v[218:219], 0, s[14:15]
	s_mov_b32 m0, s36
	ds_read_b128 v[184:187], v150 offset:49152
	ds_read_b128 v[188:191], v150 offset:50176
	ds_read_b128 v[192:195], v150 offset:51200
	ds_read_b128 v[198:201], v150 offset:52224
	ds_read_b128 v[202:205], v150 offset:53248
	ds_read_b128 v[206:209], v150 offset:54272
	ds_read_b128 v[210:213], v150 offset:55296
	ds_read_b128 v[214:217], v150 offset:56320
	global_load_lds_dwordx4 v[218:219], off
	v_lshl_add_u64 v[218:219], v[220:221], 0, s[14:15]
	s_add_i32 m0, s36, 0x2000
	s_add_i32 s36, s65, s40
	global_load_lds_dwordx4 v[218:219], off
	v_lshl_add_u64 v[218:219], v[222:223], 0, s[14:15]
	s_mov_b32 m0, s36
	s_nop 0
	global_load_lds_dwordx4 v[218:219], off
	v_lshl_add_u64 v[218:219], v[224:225], 0, s[14:15]
	s_add_i32 m0, s36, 0x2000
	s_nop 0
	global_load_lds_dwordx4 v[218:219], off
	v_lshl_add_u64 v[218:219], v[226:227], 0, s[14:15]
	s_mov_b32 m0, s46
	s_nop 0
	global_load_lds_dwordx4 v[218:219], off
	v_lshl_add_u64 v[218:219], v[228:229], 0, s[14:15]
	s_mov_b32 m0, s47
	s_nop 0
	global_load_lds_dwordx4 v[218:219], off
	s_waitcnt vmcnt(8)
	s_waitcnt lgkmcnt(0)
	s_barrier
	s_setprio 1
	s_waitcnt lgkmcnt(0)
	v_mfma_f32_16x16x32_bf16 v[62:65], v[152:155], v[184:187], v[62:65]
	v_mfma_f32_16x16x32_bf16 v[58:61], v[160:163], v[184:187], v[58:61]
	v_mfma_f32_16x16x32_bf16 v[46:49], v[152:155], v[192:195], v[46:49]
	v_mfma_f32_16x16x32_bf16 v[42:45], v[160:163], v[192:195], v[42:45]
	v_mfma_f32_16x16x32_bf16 v[30:33], v[152:155], v[202:205], v[30:33]
	v_mfma_f32_16x16x32_bf16 v[26:29], v[160:163], v[202:205], v[26:29]
	v_mfma_f32_16x16x32_bf16 v[14:17], v[152:155], v[210:213], v[14:17]
	v_mfma_f32_16x16x32_bf16 v[10:13], v[160:163], v[210:213], v[10:13]
	v_mfma_f32_16x16x32_bf16 v[62:65], v[156:159], v[188:191], v[62:65]
	v_mfma_f32_16x16x32_bf16 v[58:61], v[164:167], v[188:191], v[58:61]
	v_mfma_f32_16x16x32_bf16 v[46:49], v[156:159], v[198:201], v[46:49]
	v_mfma_f32_16x16x32_bf16 v[42:45], v[164:167], v[198:201], v[42:45]
	v_mfma_f32_16x16x32_bf16 v[30:33], v[156:159], v[206:209], v[30:33]
	v_mfma_f32_16x16x32_bf16 v[26:29], v[164:167], v[206:209], v[26:29]
	v_mfma_f32_16x16x32_bf16 v[14:17], v[156:159], v[214:217], v[14:17]
	v_mfma_f32_16x16x32_bf16 v[10:13], v[164:167], v[214:217], v[10:13]
	s_setprio 0
	s_setprio 1
	v_mfma_f32_16x16x32_bf16 v[54:57], v[168:171], v[184:187], v[54:57]
	v_mfma_f32_16x16x32_bf16 v[50:53], v[176:179], v[184:187], v[50:53]
	v_mfma_f32_16x16x32_bf16 v[38:41], v[168:171], v[192:195], v[38:41]
	v_mfma_f32_16x16x32_bf16 v[34:37], v[176:179], v[192:195], v[34:37]
	v_mfma_f32_16x16x32_bf16 v[22:25], v[168:171], v[202:205], v[22:25]
	v_mfma_f32_16x16x32_bf16 v[18:21], v[176:179], v[202:205], v[18:21]
	v_mfma_f32_16x16x32_bf16 v[6:9], v[168:171], v[210:213], v[6:9]
	v_mfma_f32_16x16x32_bf16 v[2:5], v[176:179], v[210:213], v[2:5]
	v_mfma_f32_16x16x32_bf16 v[54:57], v[172:175], v[188:191], v[54:57]
	v_mfma_f32_16x16x32_bf16 v[50:53], v[180:183], v[188:191], v[50:53]
	v_mfma_f32_16x16x32_bf16 v[38:41], v[172:175], v[198:201], v[38:41]
	v_mfma_f32_16x16x32_bf16 v[34:37], v[180:183], v[198:201], v[34:37]
	v_mfma_f32_16x16x32_bf16 v[22:25], v[172:175], v[206:209], v[22:25]
	v_mfma_f32_16x16x32_bf16 v[18:21], v[180:183], v[206:209], v[18:21]
	v_mfma_f32_16x16x32_bf16 v[6:9], v[172:175], v[214:217], v[6:9]
	v_mfma_f32_16x16x32_bf16 v[2:5], v[180:183], v[214:217], v[2:5]
	s_setprio 0
	s_barrier
	s_add_u32 s34, s34, 0x100
	s_addc_u32 s35, s35, 0
	s_add_u32 s61, s61, 0x100
	s_addc_u32 s62, s62, 0
	s_cmp_ge_i32 s63, s48
	s_mov_b32 s36, s63
	s_cbranch_scc0 .LBB0_619

.LBB0_698:
	ds_read_b128 v[160:163], v157
	ds_read_b128 v[164:167], v157 offset:1024
	ds_read_b128 v[168:171], v157 offset:2048
	ds_read_b128 v[172:175], v157 offset:3072
	ds_read_b128 v[176:179], v158
	ds_read_b128 v[180:183], v158 offset:1024
	ds_read_b128 v[184:187], v158 offset:2048
	ds_read_b128 v[188:191], v158 offset:3072
	s_add_u32 s38, s36, 0xfff80080
	s_addc_u32 s39, s37, -1
	s_cmp_eq_u32 s61, 28
	s_cselect_b32 s41, s29, s39
	s_cselect_b32 s40, s57, s38
	s_cselect_b32 s39, s27, s60
	s_cselect_b32 s38, s58, s59
	s_add_i32 m0, s25, 0xc000
	ds_read_b128 v[192:195], v159
	ds_read_b128 v[196:199], v159 offset:1024
	ds_read_b128 v[200:203], v159 offset:2048
	ds_read_b128 v[204:207], v159 offset:3072
	ds_read_b128 v[208:211], v159 offset:4096
	ds_read_b128 v[212:215], v159 offset:5120
	ds_read_b128 v[216:219], v159 offset:6144
	ds_read_b128 v[220:223], v159 offset:7168
	global_load_lds_dwordx4 v138, s[36:37]
	s_add_i32 m0, s25, 0xe000
	s_nop 0
	global_load_lds_dwordx4 v140, s[36:37]
	s_waitcnt vmcnt(8)
	s_waitcnt lgkmcnt(0)
	s_barrier
	s_setprio 1
	s_waitcnt lgkmcnt(0)
	v_mfma_f32_16x16x32_bf16 v[126:129], v[160:163], v[192:195], v[126:129]
	v_mfma_f32_16x16x32_bf16 v[122:125], v[168:171], v[192:195], v[122:125]
	v_mfma_f32_16x16x32_bf16 v[118:121], v[160:163], v[200:203], v[118:121]
	v_mfma_f32_16x16x32_bf16 v[114:117], v[168:171], v[200:203], v[114:117]
	v_mfma_f32_16x16x32_bf16 v[102:105], v[160:163], v[208:211], v[102:105]
	v_mfma_f32_16x16x32_bf16 v[98:101], v[168:171], v[208:211], v[98:101]
	v_mfma_f32_16x16x32_bf16 v[86:89], v[160:163], v[216:219], v[86:89]
	v_mfma_f32_16x16x32_bf16 v[82:85], v[168:171], v[216:219], v[82:85]
	v_mfma_f32_16x16x32_bf16 v[126:129], v[164:167], v[196:199], v[126:129]
	v_mfma_f32_16x16x32_bf16 v[122:125], v[172:175], v[196:199], v[122:125]
	v_mfma_f32_16x16x32_bf16 v[118:121], v[164:167], v[204:207], v[118:121]
	v_mfma_f32_16x16x32_bf16 v[114:117], v[172:175], v[204:207], v[114:117]
	v_mfma_f32_16x16x32_bf16 v[102:105], v[164:167], v[212:215], v[102:105]
	v_mfma_f32_16x16x32_bf16 v[98:101], v[172:175], v[212:215], v[98:101]
	v_mfma_f32_16x16x32_bf16 v[86:89], v[164:167], v[220:223], v[86:89]
	v_mfma_f32_16x16x32_bf16 v[82:85], v[172:175], v[220:223], v[82:85]
	s_setprio 0
	s_setprio 1
	v_mfma_f32_16x16x32_bf16 v[110:113], v[176:179], v[192:195], v[110:113]
	v_mfma_f32_16x16x32_bf16 v[106:109], v[184:187], v[192:195], v[106:109]
	v_mfma_f32_16x16x32_bf16 v[94:97], v[176:179], v[200:203], v[94:97]
	v_mfma_f32_16x16x32_bf16 v[90:93], v[184:187], v[200:203], v[90:93]
	v_mfma_f32_16x16x32_bf16 v[78:81], v[176:179], v[208:211], v[78:81]
	v_mfma_f32_16x16x32_bf16 v[74:77], v[184:187], v[208:211], v[74:77]
	v_mfma_f32_16x16x32_bf16 v[70:73], v[176:179], v[216:219], v[70:73]
	v_mfma_f32_16x16x32_bf16 v[66:69], v[184:187], v[216:219], v[66:69]
	v_mfma_f32_16x16x32_bf16 v[110:113], v[180:183], v[196:199], v[110:113]
	v_mfma_f32_16x16x32_bf16 v[106:109], v[188:191], v[196:199], v[106:109]
	v_mfma_f32_16x16x32_bf16 v[94:97], v[180:183], v[204:207], v[94:97]
	v_mfma_f32_16x16x32_bf16 v[90:93], v[188:191], v[204:207], v[90:93]
	v_mfma_f32_16x16x32_bf16 v[78:81], v[180:183], v[212:215], v[78:81]
	v_mfma_f32_16x16x32_bf16 v[74:77], v[188:191], v[212:215], v[74:77]
	v_mfma_f32_16x16x32_bf16 v[70:73], v[180:183], v[220:223], v[70:73]
	v_mfma_f32_16x16x32_bf16 v[66:69], v[188:191], v[220:223], v[66:69]
	s_setprio 0
	s_barrier
	s_add_i32 s62, s50, s42
	v_lshl_add_u64 v[224:225], s[38:39], 0, v[132:133]
	s_mov_b32 m0, s62
	ds_read_b128 v[192:195], v159 offset:16384
	ds_read_b128 v[196:199], v159 offset:17408
	ds_read_b128 v[200:203], v159 offset:18432
	ds_read_b128 v[204:207], v159 offset:19456
	ds_read_b128 v[208:211], v159 offset:20480
	ds_read_b128 v[212:215], v159 offset:21504
	ds_read_b128 v[216:219], v159 offset:22528
	ds_read_b128 v[220:223], v159 offset:23552
	global_load_lds_dwordx4 v[224:225], off
	s_add_i32 m0, s62, 0x2000
	s_add_u32 s62, s38, 0x80000
	v_lshl_add_u64 v[226:227], s[38:39], 0, v[136:137]
	s_addc_u32 s63, s39, 0
	s_add_i32 s64, s51, s42
	global_load_lds_dwordx4 v[226:227], off
	s_mov_b32 m0, s64
	v_lshl_add_u64 v[230:231], s[40:41], 0, v[134:135]
	global_load_lds_dwordx4 v132, s[62:63]
	s_add_i32 m0, s64, 0x2000
	s_nop 0
	global_load_lds_dwordx4 v136, s[62:63]
	v_lshl_add_u64 v[228:229], s[40:41], 0, v[130:131]
	s_mov_b32 m0, s25
	s_nop 0
	global_load_lds_dwordx4 v[228:229], off
	s_mov_b32 m0, s43
	s_nop 0
	global_load_lds_dwordx4 v[230:231], off
	s_waitcnt vmcnt(8)
	s_waitcnt lgkmcnt(0)
	s_barrier
	s_setprio 1
	s_waitcnt lgkmcnt(0)
	v_mfma_f32_16x16x32_bf16 v[62:65], v[160:163], v[192:195], v[62:65]
	v_mfma_f32_16x16x32_bf16 v[58:61], v[168:171], v[192:195], v[58:61]
	v_mfma_f32_16x16x32_bf16 v[54:57], v[160:163], v[200:203], v[54:57]
	v_mfma_f32_16x16x32_bf16 v[50:53], v[168:171], v[200:203], v[50:53]
	v_mfma_f32_16x16x32_bf16 v[38:41], v[160:163], v[208:211], v[38:41]
	v_mfma_f32_16x16x32_bf16 v[34:37], v[168:171], v[208:211], v[34:37]
	v_mfma_f32_16x16x32_bf16 v[22:25], v[160:163], v[216:219], v[22:25]
	v_mfma_f32_16x16x32_bf16 v[18:21], v[168:171], v[216:219], v[18:21]
	v_mfma_f32_16x16x32_bf16 v[62:65], v[164:167], v[196:199], v[62:65]
	v_mfma_f32_16x16x32_bf16 v[58:61], v[172:175], v[196:199], v[58:61]
	v_mfma_f32_16x16x32_bf16 v[54:57], v[164:167], v[204:207], v[54:57]
	v_mfma_f32_16x16x32_bf16 v[50:53], v[172:175], v[204:207], v[50:53]
	v_mfma_f32_16x16x32_bf16 v[38:41], v[164:167], v[212:215], v[38:41]
	v_mfma_f32_16x16x32_bf16 v[34:37], v[172:175], v[212:215], v[34:37]
	v_mfma_f32_16x16x32_bf16 v[22:25], v[164:167], v[220:223], v[22:25]
	v_mfma_f32_16x16x32_bf16 v[18:21], v[172:175], v[220:223], v[18:21]
	s_setprio 0
	s_setprio 1
	v_mfma_f32_16x16x32_bf16 v[46:49], v[176:179], v[192:195], v[46:49]
	v_mfma_f32_16x16x32_bf16 v[42:45], v[184:187], v[192:195], v[42:45]
	v_mfma_f32_16x16x32_bf16 v[30:33], v[176:179], v[200:203], v[30:33]
	v_mfma_f32_16x16x32_bf16 v[26:29], v[184:187], v[200:203], v[26:29]
	v_mfma_f32_16x16x32_bf16 v[14:17], v[176:179], v[208:211], v[14:17]
	v_mfma_f32_16x16x32_bf16 v[10:13], v[184:187], v[208:211], v[10:13]
	v_mfma_f32_16x16x32_bf16 v[6:9], v[176:179], v[216:219], v[6:9]
	v_mfma_f32_16x16x32_bf16 v[2:5], v[184:187], v[216:219], v[2:5]
	v_mfma_f32_16x16x32_bf16 v[46:49], v[180:183], v[196:199], v[46:49]
	v_mfma_f32_16x16x32_bf16 v[42:45], v[188:191], v[196:199], v[42:45]
	v_mfma_f32_16x16x32_bf16 v[30:33], v[180:183], v[204:207], v[30:33]
	v_mfma_f32_16x16x32_bf16 v[26:29], v[188:191], v[204:207], v[26:29]
	v_mfma_f32_16x16x32_bf16 v[14:17], v[180:183], v[212:215], v[14:17]
	v_mfma_f32_16x16x32_bf16 v[10:13], v[188:191], v[212:215], v[10:13]
	v_mfma_f32_16x16x32_bf16 v[6:9], v[180:183], v[220:223], v[6:9]
	v_mfma_f32_16x16x32_bf16 v[2:5], v[188:191], v[220:223], v[2:5]
	s_setprio 0
	s_barrier
	s_add_i32 s62, 0, 0x18000
	s_add_i32 s63, 0, 0x1c000
	v_add_u32_e32 v172, s62, v155
	v_add_u32_e32 v188, s63, v155
	ds_read_b128 v[160:163], v172
	ds_read_b128 v[164:167], v172 offset:1024
	ds_read_b128 v[168:171], v172 offset:2048
	ds_read_b128 v[172:175], v172 offset:3072
	ds_read_b128 v[176:179], v188
	ds_read_b128 v[180:183], v188 offset:1024
	ds_read_b128 v[184:187], v188 offset:2048
	ds_read_b128 v[188:191], v188 offset:3072
	s_add_u32 s40, s40, 0x80000
	s_addc_u32 s41, s41, 0
	s_mov_b32 m0, s44
	ds_read_b128 v[192:195], v159 offset:32768
	ds_read_b128 v[196:199], v159 offset:33792
	ds_read_b128 v[200:203], v159 offset:34816
	ds_read_b128 v[204:207], v159 offset:35840
	ds_read_b128 v[208:211], v159 offset:36864
	ds_read_b128 v[212:215], v159 offset:37888
	ds_read_b128 v[216:219], v159 offset:38912
	ds_read_b128 v[220:223], v159 offset:39936
	global_load_lds_dwordx4 v130, s[40:41]
	s_mov_b32 m0, s45
	s_nop 0
	global_load_lds_dwordx4 v134, s[40:41]
	s_waitcnt vmcnt(8)
	s_waitcnt lgkmcnt(0)
	s_barrier
	s_setprio 1
	s_waitcnt lgkmcnt(0)
	v_mfma_f32_16x16x32_bf16 v[126:129], v[160:163], v[192:195], v[126:129]
	v_mfma_f32_16x16x32_bf16 v[122:125], v[168:171], v[192:195], v[122:125]
	v_mfma_f32_16x16x32_bf16 v[118:121], v[160:163], v[200:203], v[118:121]
	v_mfma_f32_16x16x32_bf16 v[114:117], v[168:171], v[200:203], v[114:117]
	v_mfma_f32_16x16x32_bf16 v[102:105], v[160:163], v[208:211], v[102:105]
	v_mfma_f32_16x16x32_bf16 v[98:101], v[168:171], v[208:211], v[98:101]
	v_mfma_f32_16x16x32_bf16 v[86:89], v[160:163], v[216:219], v[86:89]
	v_mfma_f32_16x16x32_bf16 v[82:85], v[168:171], v[216:219], v[82:85]
	v_mfma_f32_16x16x32_bf16 v[126:129], v[164:167], v[196:199], v[126:129]
	v_mfma_f32_16x16x32_bf16 v[122:125], v[172:175], v[196:199], v[122:125]
	v_mfma_f32_16x16x32_bf16 v[118:121], v[164:167], v[204:207], v[118:121]
	v_mfma_f32_16x16x32_bf16 v[114:117], v[172:175], v[204:207], v[114:117]
	v_mfma_f32_16x16x32_bf16 v[102:105], v[164:167], v[212:215], v[102:105]
	v_mfma_f32_16x16x32_bf16 v[98:101], v[172:175], v[212:215], v[98:101]
	v_mfma_f32_16x16x32_bf16 v[86:89], v[164:167], v[220:223], v[86:89]
	v_mfma_f32_16x16x32_bf16 v[82:85], v[172:175], v[220:223], v[82:85]
	s_setprio 0
	s_setprio 1
	v_mfma_f32_16x16x32_bf16 v[110:113], v[176:179], v[192:195], v[110:113]
	v_mfma_f32_16x16x32_bf16 v[106:109], v[184:187], v[192:195], v[106:109]
	v_mfma_f32_16x16x32_bf16 v[94:97], v[176:179], v[200:203], v[94:97]
	v_mfma_f32_16x16x32_bf16 v[90:93], v[184:187], v[200:203], v[90:93]
	v_mfma_f32_16x16x32_bf16 v[78:81], v[176:179], v[208:211], v[78:81]
	v_mfma_f32_16x16x32_bf16 v[74:77], v[184:187], v[208:211], v[74:77]
	v_mfma_f32_16x16x32_bf16 v[70:73], v[176:179], v[216:219], v[70:73]
	v_mfma_f32_16x16x32_bf16 v[66:69], v[184:187], v[216:219], v[66:69]
	v_mfma_f32_16x16x32_bf16 v[110:113], v[180:183], v[196:199], v[110:113]
	v_mfma_f32_16x16x32_bf16 v[106:109], v[188:191], v[196:199], v[106:109]
	v_mfma_f32_16x16x32_bf16 v[94:97], v[180:183], v[204:207], v[94:97]
	v_mfma_f32_16x16x32_bf16 v[90:93], v[188:191], v[204:207], v[90:93]
	v_mfma_f32_16x16x32_bf16 v[78:81], v[180:183], v[212:215], v[78:81]
	v_mfma_f32_16x16x32_bf16 v[74:77], v[188:191], v[212:215], v[74:77]
	v_mfma_f32_16x16x32_bf16 v[70:73], v[180:183], v[220:223], v[70:73]
	v_mfma_f32_16x16x32_bf16 v[66:69], v[188:191], v[220:223], v[66:69]
	s_setprio 0
	s_barrier
	s_add_i32 s40, s62, s42
	v_lshl_add_u64 v[224:225], v[224:225], 0, s[12:13]
	s_mov_b32 m0, s40
	ds_read_b128 v[192:195], v159 offset:49152
	ds_read_b128 v[196:199], v159 offset:50176
	ds_read_b128 v[200:203], v159 offset:51200
	ds_read_b128 v[204:207], v159 offset:52224
	ds_read_b128 v[208:211], v159 offset:53248
	ds_read_b128 v[212:215], v159 offset:54272
	ds_read_b128 v[216:219], v159 offset:55296
	ds_read_b128 v[220:223], v159 offset:56320
	global_load_lds_dwordx4 v[224:225], off
	s_add_i32 m0, s40, 0x2000
	s_add_u32 s38, s38, 0x80080
	v_lshl_add_u64 v[224:225], v[226:227], 0, s[12:13]
	s_addc_u32 s39, s39, 0
	s_add_i32 s40, s63, s42
	global_load_lds_dwordx4 v[224:225], off
	s_mov_b32 m0, s40
	s_nop 0
	global_load_lds_dwordx4 v132, s[38:39]
	s_add_i32 m0, s40, 0x2000
	s_nop 0
	global_load_lds_dwordx4 v136, s[38:39]
	v_lshl_add_u64 v[224:225], v[228:229], 0, s[12:13]
	s_mov_b32 m0, s47
	s_nop 0
	global_load_lds_dwordx4 v[224:225], off
	v_lshl_add_u64 v[224:225], v[230:231], 0, s[12:13]
	s_mov_b32 m0, s48
	s_nop 0
	global_load_lds_dwordx4 v[224:225], off
	s_waitcnt vmcnt(8)
	s_waitcnt lgkmcnt(0)
	s_barrier
	s_setprio 1
	s_waitcnt lgkmcnt(0)
	v_mfma_f32_16x16x32_bf16 v[62:65], v[160:163], v[192:195], v[62:65]
	v_mfma_f32_16x16x32_bf16 v[58:61], v[168:171], v[192:195], v[58:61]
	v_mfma_f32_16x16x32_bf16 v[54:57], v[160:163], v[200:203], v[54:57]
	v_mfma_f32_16x16x32_bf16 v[50:53], v[168:171], v[200:203], v[50:53]
	v_mfma_f32_16x16x32_bf16 v[38:41], v[160:163], v[208:211], v[38:41]
	v_mfma_f32_16x16x32_bf16 v[34:37], v[168:171], v[208:211], v[34:37]
	v_mfma_f32_16x16x32_bf16 v[22:25], v[160:163], v[216:219], v[22:25]
	v_mfma_f32_16x16x32_bf16 v[18:21], v[168:171], v[216:219], v[18:21]
	v_mfma_f32_16x16x32_bf16 v[62:65], v[164:167], v[196:199], v[62:65]
	v_mfma_f32_16x16x32_bf16 v[58:61], v[172:175], v[196:199], v[58:61]
	v_mfma_f32_16x16x32_bf16 v[54:57], v[164:167], v[204:207], v[54:57]
	v_mfma_f32_16x16x32_bf16 v[50:53], v[172:175], v[204:207], v[50:53]
	v_mfma_f32_16x16x32_bf16 v[38:41], v[164:167], v[212:215], v[38:41]
	v_mfma_f32_16x16x32_bf16 v[34:37], v[172:175], v[212:215], v[34:37]
	v_mfma_f32_16x16x32_bf16 v[22:25], v[164:167], v[220:223], v[22:25]
	v_mfma_f32_16x16x32_bf16 v[18:21], v[172:175], v[220:223], v[18:21]
	s_setprio 0
	s_setprio 1
	v_mfma_f32_16x16x32_bf16 v[46:49], v[176:179], v[192:195], v[46:49]
	v_mfma_f32_16x16x32_bf16 v[42:45], v[184:187], v[192:195], v[42:45]
	v_mfma_f32_16x16x32_bf16 v[30:33], v[176:179], v[200:203], v[30:33]
	v_mfma_f32_16x16x32_bf16 v[26:29], v[184:187], v[200:203], v[26:29]
	v_mfma_f32_16x16x32_bf16 v[14:17], v[176:179], v[208:211], v[14:17]
	v_mfma_f32_16x16x32_bf16 v[10:13], v[184:187], v[208:211], v[10:13]
	v_mfma_f32_16x16x32_bf16 v[6:9], v[176:179], v[216:219], v[6:9]
	v_mfma_f32_16x16x32_bf16 v[2:5], v[184:187], v[216:219], v[2:5]
	v_mfma_f32_16x16x32_bf16 v[46:49], v[180:183], v[196:199], v[46:49]
	v_mfma_f32_16x16x32_bf16 v[42:45], v[188:191], v[196:199], v[42:45]
	v_mfma_f32_16x16x32_bf16 v[30:33], v[180:183], v[204:207], v[30:33]
	v_mfma_f32_16x16x32_bf16 v[26:29], v[188:191], v[204:207], v[26:29]
	v_mfma_f32_16x16x32_bf16 v[14:17], v[180:183], v[212:215], v[14:17]
	v_mfma_f32_16x16x32_bf16 v[10:13], v[188:191], v[212:215], v[10:13]
	v_mfma_f32_16x16x32_bf16 v[6:9], v[180:183], v[220:223], v[6:9]
	v_mfma_f32_16x16x32_bf16 v[2:5], v[188:191], v[220:223], v[2:5]
	s_setprio 0
	s_barrier
	s_add_i32 s61, s61, 2
	s_add_u32 s36, s36, 0x100
	s_addc_u32 s37, s37, 0
	s_add_u32 s59, s59, 0x100
	s_addc_u32 s60, s60, 0
	s_cmp_gt_u32 s61, 29
	s_cbranch_scc0 .LBB0_698
	s_and_b64 vcc, exec, s[14:15]
	s_cbranch_vccz .LBB0_701
	s_barrier

.LBB0_722:
	ds_read_b128 v[18:21], v191
	ds_read_b128 v[26:29], v191 offset:2048
	ds_read_b128 v[22:25], v192
	ds_read_b128 v[30:33], v192 offset:2048
	ds_read_b128 v[2:5], v193
	ds_read_b128 v[10:13], v193 offset:2048
	ds_read_b128 v[6:9], v194
	ds_read_b128 v[14:17], v194 offset:2048
	s_add_u32 s38, s36, 0xfffc0080
	s_addc_u32 s39, s37, -1
	s_cmp_eq_u32 s62, 12
	s_cselect_b32 s41, s27, s39
	s_cselect_b32 s40, s58, s38
	s_cselect_b32 s39, s25, s61
	s_cselect_b32 s38, s59, s60
	s_add_i32 m0, s35, 0xc000
	ds_read_b128 v[178:181], v195
	ds_read_b128 v[198:201], v195 offset:2048
	ds_read_b128 v[182:185], v196
	ds_read_b128 v[202:205], v196 offset:2048
	ds_read_b128 v[206:209], v195 offset:4096
	ds_read_b128 v[214:217], v195 offset:6144
	ds_read_b128 v[210:213], v196 offset:4096
	ds_read_b128 v[218:221], v196 offset:6144
	global_load_lds_dwordx4 v170, s[36:37]
	s_add_i32 m0, s35, 0xe000
	s_nop 0
	global_load_lds_dwordx4 v172, s[36:37]
	s_waitcnt vmcnt(8)
	s_waitcnt lgkmcnt(0)
	s_barrier
	s_setprio 1
	s_waitcnt lgkmcnt(0)
	v_mfma_scale_f32_16x16x128_f8f6f4 v[158:161], v[18:25], v[178:185], v[158:161], v186, v186 op_sel_hi:[0,0,0]
	v_mfma_scale_f32_16x16x128_f8f6f4 v[154:157], v[26:33], v[178:185], v[154:157], v186, v186 op_sel_hi:[0,0,0]
	v_mfma_scale_f32_16x16x128_f8f6f4 v[142:145], v[18:25], v[198:205], v[142:145], v186, v186 op_sel_hi:[0,0,0]
	v_mfma_scale_f32_16x16x128_f8f6f4 v[138:141], v[26:33], v[198:205], v[138:141], v186, v186 op_sel_hi:[0,0,0]
	v_mfma_scale_f32_16x16x128_f8f6f4 v[126:129], v[18:25], v[206:213], v[126:129], v186, v186 op_sel_hi:[0,0,0]
	v_mfma_scale_f32_16x16x128_f8f6f4 v[122:125], v[26:33], v[206:213], v[122:125], v186, v186 op_sel_hi:[0,0,0]
	v_mfma_scale_f32_16x16x128_f8f6f4 v[110:113], v[18:25], v[214:221], v[110:113], v186, v186 op_sel_hi:[0,0,0]
	v_mfma_scale_f32_16x16x128_f8f6f4 v[106:109], v[26:33], v[214:221], v[106:109], v186, v186 op_sel_hi:[0,0,0]
	s_setprio 0
	s_setprio 1
	v_mfma_scale_f32_16x16x128_f8f6f4 v[150:153], v[2:9], v[178:185], v[150:153], v186, v186 op_sel_hi:[0,0,0]
	v_mfma_scale_f32_16x16x128_f8f6f4 v[146:149], v[10:17], v[178:185], v[146:149], v186, v186 op_sel_hi:[0,0,0]
	v_mfma_scale_f32_16x16x128_f8f6f4 v[134:137], v[2:9], v[198:205], v[134:137], v186, v186 op_sel_hi:[0,0,0]
	v_mfma_scale_f32_16x16x128_f8f6f4 v[130:133], v[10:17], v[198:205], v[130:133], v186, v186 op_sel_hi:[0,0,0]
	v_mfma_scale_f32_16x16x128_f8f6f4 v[118:121], v[2:9], v[206:213], v[118:121], v186, v186 op_sel_hi:[0,0,0]
	v_mfma_scale_f32_16x16x128_f8f6f4 v[114:117], v[10:17], v[206:213], v[114:117], v186, v186 op_sel_hi:[0,0,0]
	v_mfma_scale_f32_16x16x128_f8f6f4 v[102:105], v[2:9], v[214:221], v[102:105], v186, v186 op_sel_hi:[0,0,0]
	v_mfma_scale_f32_16x16x128_f8f6f4 v[98:101], v[10:17], v[214:221], v[98:101], v186, v186 op_sel_hi:[0,0,0]
	s_setprio 0
	s_barrier
	s_add_i32 s63, s51, s43
	v_lshl_add_u64 v[178:179], s[38:39], 0, v[164:165]
	s_mov_b32 m0, s63
	ds_read_b128 v[198:201], v195 offset:16384
	ds_read_b128 v[206:209], v195 offset:18432
	ds_read_b128 v[202:205], v196 offset:16384
	ds_read_b128 v[210:213], v196 offset:18432
	ds_read_b128 v[214:217], v195 offset:20480
	ds_read_b128 v[222:225], v195 offset:22528
	ds_read_b128 v[218:221], v196 offset:20480
	ds_read_b128 v[226:229], v196 offset:22528
	global_load_lds_dwordx4 v[178:179], off
	s_add_i32 m0, s63, 0x2000
	s_add_u32 s64, s38, 0x40000
	v_lshl_add_u64 v[180:181], s[38:39], 0, v[168:169]
	s_addc_u32 s65, s39, 0
	s_add_i32 s63, s52, s43
	global_load_lds_dwordx4 v[180:181], off
	s_mov_b32 m0, s63
	v_lshl_add_u64 v[184:185], s[40:41], 0, v[166:167]
	global_load_lds_dwordx4 v164, s[64:65]
	s_add_i32 m0, s63, 0x2000
	s_nop 0
	global_load_lds_dwordx4 v168, s[64:65]
	v_lshl_add_u64 v[182:183], s[40:41], 0, v[162:163]
	s_mov_b32 m0, s35
	s_nop 0
	global_load_lds_dwordx4 v[182:183], off
	s_mov_b32 m0, s44
	s_nop 0
	global_load_lds_dwordx4 v[184:185], off
	s_waitcnt vmcnt(8)
	s_waitcnt lgkmcnt(0)
	s_barrier
	s_setprio 1
	s_waitcnt lgkmcnt(0)
	v_mfma_scale_f32_16x16x128_f8f6f4 v[94:97], v[18:25], v[198:205], v[94:97], v186, v186 op_sel_hi:[0,0,0]
	v_mfma_scale_f32_16x16x128_f8f6f4 v[90:93], v[26:33], v[198:205], v[90:93], v186, v186 op_sel_hi:[0,0,0]
	v_mfma_scale_f32_16x16x128_f8f6f4 v[78:81], v[18:25], v[206:213], v[78:81], v186, v186 op_sel_hi:[0,0,0]
	v_mfma_scale_f32_16x16x128_f8f6f4 v[74:77], v[26:33], v[206:213], v[74:77], v186, v186 op_sel_hi:[0,0,0]
	v_mfma_scale_f32_16x16x128_f8f6f4 v[62:65], v[18:25], v[214:221], v[62:65], v186, v186 op_sel_hi:[0,0,0]
	v_mfma_scale_f32_16x16x128_f8f6f4 v[58:61], v[26:33], v[214:221], v[58:61], v186, v186 op_sel_hi:[0,0,0]
	v_mfma_scale_f32_16x16x128_f8f6f4 v[46:49], v[18:25], v[222:229], v[46:49], v186, v186 op_sel_hi:[0,0,0]
	v_mfma_scale_f32_16x16x128_f8f6f4 v[42:45], v[26:33], v[222:229], v[42:45], v186, v186 op_sel_hi:[0,0,0]
	s_setprio 0
	s_setprio 1
	v_mfma_scale_f32_16x16x128_f8f6f4 v[86:89], v[2:9], v[198:205], v[86:89], v186, v186 op_sel_hi:[0,0,0]
	v_mfma_scale_f32_16x16x128_f8f6f4 v[82:85], v[10:17], v[198:205], v[82:85], v186, v186 op_sel_hi:[0,0,0]
	v_mfma_scale_f32_16x16x128_f8f6f4 v[70:73], v[2:9], v[206:213], v[70:73], v186, v186 op_sel_hi:[0,0,0]
	v_mfma_scale_f32_16x16x128_f8f6f4 v[66:69], v[10:17], v[206:213], v[66:69], v186, v186 op_sel_hi:[0,0,0]
	v_mfma_scale_f32_16x16x128_f8f6f4 v[54:57], v[2:9], v[214:221], v[54:57], v186, v186 op_sel_hi:[0,0,0]
	v_mfma_scale_f32_16x16x128_f8f6f4 v[50:53], v[10:17], v[214:221], v[50:53], v186, v186 op_sel_hi:[0,0,0]
	v_mfma_scale_f32_16x16x128_f8f6f4 v[38:41], v[2:9], v[222:229], v[38:41], v186, v186 op_sel_hi:[0,0,0]
	v_mfma_scale_f32_16x16x128_f8f6f4 v[34:37], v[10:17], v[222:229], v[34:37], v186, v186 op_sel_hi:[0,0,0]
	s_setprio 0
	s_barrier
	s_add_i32 s63, 0, 0x18000
	s_add_i32 s64, 0, 0x1c000
	v_add_u32_e32 v6, s63, v187
	v_add_u32_e32 v14, s63, v188
	v_add_u32_e32 v22, s64, v187
	v_add_u32_e32 v30, s64, v188
	ds_read_b128 v[2:5], v6
	ds_read_b128 v[10:13], v6 offset:2048
	ds_read_b128 v[6:9], v14
	ds_read_b128 v[14:17], v14 offset:2048
	ds_read_b128 v[18:21], v22
	ds_read_b128 v[26:29], v22 offset:2048
	ds_read_b128 v[22:25], v30
	ds_read_b128 v[30:33], v30 offset:2048
	s_add_u32 s40, s40, 0x40000
	s_addc_u32 s41, s41, 0
	s_mov_b32 m0, s45
	ds_read_b128 v[198:201], v195 offset:32768
	ds_read_b128 v[206:209], v195 offset:34816
	ds_read_b128 v[202:205], v196 offset:32768
	ds_read_b128 v[210:213], v196 offset:34816
	ds_read_b128 v[214:217], v195 offset:36864
	ds_read_b128 v[222:225], v195 offset:38912
	ds_read_b128 v[218:221], v196 offset:36864
	ds_read_b128 v[226:229], v196 offset:38912
	global_load_lds_dwordx4 v162, s[40:41]
	s_mov_b32 m0, s46
	s_nop 0
	global_load_lds_dwordx4 v166, s[40:41]
	s_waitcnt vmcnt(8)
	s_waitcnt lgkmcnt(0)
	s_barrier
	s_setprio 1
	s_waitcnt lgkmcnt(0)
	v_mfma_scale_f32_16x16x128_f8f6f4 v[158:161], v[2:9], v[198:205], v[158:161], v186, v186 op_sel_hi:[0,0,0]
	v_mfma_scale_f32_16x16x128_f8f6f4 v[154:157], v[10:17], v[198:205], v[154:157], v186, v186 op_sel_hi:[0,0,0]
	v_mfma_scale_f32_16x16x128_f8f6f4 v[142:145], v[2:9], v[206:213], v[142:145], v186, v186 op_sel_hi:[0,0,0]
	v_mfma_scale_f32_16x16x128_f8f6f4 v[138:141], v[10:17], v[206:213], v[138:141], v186, v186 op_sel_hi:[0,0,0]
	v_mfma_scale_f32_16x16x128_f8f6f4 v[126:129], v[2:9], v[214:221], v[126:129], v186, v186 op_sel_hi:[0,0,0]
	v_mfma_scale_f32_16x16x128_f8f6f4 v[122:125], v[10:17], v[214:221], v[122:125], v186, v186 op_sel_hi:[0,0,0]
	v_mfma_scale_f32_16x16x128_f8f6f4 v[110:113], v[2:9], v[222:229], v[110:113], v186, v186 op_sel_hi:[0,0,0]
	v_mfma_scale_f32_16x16x128_f8f6f4 v[106:109], v[10:17], v[222:229], v[106:109], v186, v186 op_sel_hi:[0,0,0]
	s_setprio 0
	s_setprio 1
	v_mfma_scale_f32_16x16x128_f8f6f4 v[150:153], v[18:25], v[198:205], v[150:153], v186, v186 op_sel_hi:[0,0,0]
	v_mfma_scale_f32_16x16x128_f8f6f4 v[146:149], v[26:33], v[198:205], v[146:149], v186, v186 op_sel_hi:[0,0,0]
	v_mfma_scale_f32_16x16x128_f8f6f4 v[134:137], v[18:25], v[206:213], v[134:137], v186, v186 op_sel_hi:[0,0,0]
	v_mfma_scale_f32_16x16x128_f8f6f4 v[130:133], v[26:33], v[206:213], v[130:133], v186, v186 op_sel_hi:[0,0,0]
	v_mfma_scale_f32_16x16x128_f8f6f4 v[118:121], v[18:25], v[214:221], v[118:121], v186, v186 op_sel_hi:[0,0,0]
	v_mfma_scale_f32_16x16x128_f8f6f4 v[114:117], v[26:33], v[214:221], v[114:117], v186, v186 op_sel_hi:[0,0,0]
	v_mfma_scale_f32_16x16x128_f8f6f4 v[102:105], v[18:25], v[222:229], v[102:105], v186, v186 op_sel_hi:[0,0,0]
	v_mfma_scale_f32_16x16x128_f8f6f4 v[98:101], v[26:33], v[222:229], v[98:101], v186, v186 op_sel_hi:[0,0,0]
	s_setprio 0
	s_barrier
	s_add_i32 s40, s63, s43
	v_lshl_add_u64 v[178:179], v[178:179], 0, s[8:9]
	s_mov_b32 m0, s40
	ds_read_b128 v[198:201], v195 offset:49152
	ds_read_b128 v[206:209], v195 offset:51200
	ds_read_b128 v[202:205], v196 offset:49152
	ds_read_b128 v[210:213], v196 offset:51200
	ds_read_b128 v[214:217], v195 offset:53248
	ds_read_b128 v[222:225], v195 offset:55296
	ds_read_b128 v[218:221], v196 offset:53248
	ds_read_b128 v[226:229], v196 offset:55296
	global_load_lds_dwordx4 v[178:179], off
	s_add_i32 m0, s40, 0x2000
	s_add_u32 s38, s38, 0x40080
	v_lshl_add_u64 v[178:179], v[180:181], 0, s[8:9]
	s_addc_u32 s39, s39, 0
	s_add_i32 s40, s64, s43
	global_load_lds_dwordx4 v[178:179], off
	s_mov_b32 m0, s40
	s_nop 0
	global_load_lds_dwordx4 v164, s[38:39]
	s_add_i32 m0, s40, 0x2000
	s_nop 0
	global_load_lds_dwordx4 v168, s[38:39]
	v_lshl_add_u64 v[178:179], v[182:183], 0, s[8:9]
	s_mov_b32 m0, s48
	s_nop 0
	global_load_lds_dwordx4 v[178:179], off
	v_lshl_add_u64 v[178:179], v[184:185], 0, s[8:9]
	s_mov_b32 m0, s49
	s_nop 0
	global_load_lds_dwordx4 v[178:179], off
	s_waitcnt vmcnt(8)
	s_waitcnt lgkmcnt(0)
	s_barrier
	s_setprio 1
	s_waitcnt lgkmcnt(0)
	v_mfma_scale_f32_16x16x128_f8f6f4 v[94:97], v[2:9], v[198:205], v[94:97], v186, v186 op_sel_hi:[0,0,0]
	v_mfma_scale_f32_16x16x128_f8f6f4 v[90:93], v[10:17], v[198:205], v[90:93], v186, v186 op_sel_hi:[0,0,0]
	v_mfma_scale_f32_16x16x128_f8f6f4 v[78:81], v[2:9], v[206:213], v[78:81], v186, v186 op_sel_hi:[0,0,0]
	v_mfma_scale_f32_16x16x128_f8f6f4 v[74:77], v[10:17], v[206:213], v[74:77], v186, v186 op_sel_hi:[0,0,0]
	v_mfma_scale_f32_16x16x128_f8f6f4 v[62:65], v[2:9], v[214:221], v[62:65], v186, v186 op_sel_hi:[0,0,0]
	v_mfma_scale_f32_16x16x128_f8f6f4 v[58:61], v[10:17], v[214:221], v[58:61], v186, v186 op_sel_hi:[0,0,0]
	v_mfma_scale_f32_16x16x128_f8f6f4 v[46:49], v[2:9], v[222:229], v[46:49], v186, v186 op_sel_hi:[0,0,0]
	v_mfma_scale_f32_16x16x128_f8f6f4 v[42:45], v[10:17], v[222:229], v[42:45], v186, v186 op_sel_hi:[0,0,0]
	s_setprio 0
	s_setprio 1
	v_mfma_scale_f32_16x16x128_f8f6f4 v[86:89], v[18:25], v[198:205], v[86:89], v186, v186 op_sel_hi:[0,0,0]
	v_mfma_scale_f32_16x16x128_f8f6f4 v[82:85], v[26:33], v[198:205], v[82:85], v186, v186 op_sel_hi:[0,0,0]
	v_mfma_scale_f32_16x16x128_f8f6f4 v[70:73], v[18:25], v[206:213], v[70:73], v186, v186 op_sel_hi:[0,0,0]
	v_mfma_scale_f32_16x16x128_f8f6f4 v[66:69], v[26:33], v[206:213], v[66:69], v186, v186 op_sel_hi:[0,0,0]
	v_mfma_scale_f32_16x16x128_f8f6f4 v[54:57], v[18:25], v[214:221], v[54:57], v186, v186 op_sel_hi:[0,0,0]
	v_mfma_scale_f32_16x16x128_f8f6f4 v[50:53], v[26:33], v[214:221], v[50:53], v186, v186 op_sel_hi:[0,0,0]
	v_mfma_scale_f32_16x16x128_f8f6f4 v[38:41], v[18:25], v[222:229], v[38:41], v186, v186 op_sel_hi:[0,0,0]
	v_mfma_scale_f32_16x16x128_f8f6f4 v[34:37], v[26:33], v[222:229], v[34:37], v186, v186 op_sel_hi:[0,0,0]
	s_setprio 0
	s_barrier
	s_add_i32 s62, s62, 2
	s_add_u32 s36, s36, 0x100
	s_addc_u32 s37, s37, 0
	s_add_u32 s60, s60, 0x100
	s_addc_u32 s61, s61, 0
	s_cmp_gt_u32 s62, 13
	s_cbranch_scc0 .LBB0_722
	s_nop 15
	s_nop 15
	s_and_b64 vcc, exec, s[10:11]
	s_cbranch_vccz .LBB0_725
	s_barrier
